# grid-barrier census words now saved once per phase into SGPRs (removes a latent LDS race of the per-tile save), otherwise same 64-deep K-loops
# baseline (speedup 1.0000x reference)
.LBB0_597:
	v_readlane_b32 s0, v255, 4
	s_cmp_lt_i32 s0, 6
	s_cselect_b64 s[0:1], -1, 0
	s_cmp_gt_i32 s46, 5
	s_cselect_b64 s[2:3], -1, 0
	s_and_b64 s[0:1], s[0:1], s[2:3]
	s_andn2_b64 vcc, exec, s[0:1]
	s_cbranch_vccnz .LBB0_662
	v_mov_b32_e32 v254, 0x12000
	ds_read_b64 v[252:253], v254
	s_waitcnt lgkmcnt(0)
	v_readfirstlane_b32 s97, v252
	v_readfirstlane_b32 s96, v253
	v_readlane_b32 s0, v255, 0
	s_cmpk_gt_u32 s0, 0x1ff
	v_readlane_b32 s1, v255, 1
	s_cbranch_scc1 .LBB0_608
	v_lshrrev_b32_e32 v3, 4, v180
	v_xor_b32_e32 v3, v3, v180
	v_lshlrev_b32_e32 v3, 3, v3
	v_and_b32_e32 v128, 24, v3
	v_lshlrev_b32_e32 v3, 4, v180
	s_add_u32 s0, s94, 0x108de000
	v_lshrrev_b32_e32 v1, 5, v180
	v_and_b32_e32 v3, 0x3c00, v3
	v_bfe_u32 v4, v180, 2, 2
	s_addc_u32 s1, s95, 0
	v_add_u32_e32 v148, 0, v3
	v_bfe_u32 v3, v180, 5, 1
	v_bitop3_b32 v1, v1, v4, 1 bitop3:0x6c
	s_add_u32 s16, s94, 0x280000
	v_lshlrev_b32_e32 v149, 4, v1
	v_bitop3_b32 v1, v3, v4, 2 bitop3:0x36
	s_addc_u32 s17, s95, 0
	v_and_b32_e32 v2, 31, v180
	v_lshlrev_b32_e32 v150, 4, v1
	v_lshlrev_b32_e32 v1, 6, v180
	v_and_b32_e32 v4, 64, v180
	s_add_u32 s18, s94, 0x14ede000
	v_readlane_b32 s2, v255, 0
	v_lshlrev_b32_e32 v0, 8, v180
	v_and_b32_e32 v151, 0xe7c0, v1
	v_and_b32_e32 v152, 0x17c0, v1
	v_lshrrev_b32_e32 v1, 3, v180
	v_lshlrev_b32_e32 v4, 2, v4
	v_lshlrev_b32_e32 v2, 2, v2
	s_addc_u32 s19, s95, 0
	s_lshr_b32 s21, s2, 3
	s_lshl_b32 s2, s2, 3
	v_and_b32_e32 v129, 0x3fc00, v0
	v_lshrrev_b32_e32 v0, 2, v180
	v_add3_u32 v2, 0, v4, v2
	s_movk_i32 s4, 0x840
	v_or_b32_e32 v1, 0x7b, v1
	v_readlane_b32 s3, v255, 1
	s_and_b32 s22, s2, 56
	v_lshlrev_b32_e32 v0, 10, v0
	v_mov_b32_e32 v131, 0
	s_movk_i32 s2, 0x80
	v_mad_u32_u24 v153, v3, s4, v2
	v_and_b32_e32 v3, 0x380, v180
	v_mul_u32_u24_e32 v1, 0x210, v1
	s_lshr_b32 s20, s33, 3
	s_mov_b32 s3, 0
	v_cmp_gt_u32_e64 s[6:7], s2, v180
	v_cmp_eq_u32_e64 s[8:9], s2, v3
	s_movk_i32 s23, 0x210
	v_or_b32_e32 v154, 0x10000, v128
	s_mov_b32 s24, 0x20000
	v_or_b32_e32 v155, 0x20000, v128
	v_or_b32_e32 v156, 0x30000, v128
	v_lshlrev_b32_e32 v132, 1, v0
	v_mov_b32_e32 v133, v131
	v_lshlrev_b32_e32 v134, 1, v128
	v_mov_b32_e32 v135, v131
	v_add_u32_e32 v157, 0x1000, v148
	v_add_u32_e32 v158, 0x2000, v148
	v_add_u32_e32 v159, 0x3000, v148
	s_mov_b64 s[4:5], 0x20000
	v_add_u32_e32 v160, 0x4000, v148
	v_add_u32_e32 v161, 0x5000, v148
	v_add_u32_e32 v162, 0x6000, v148
	v_add_u32_e32 v163, 0x7000, v148
	v_add_u32_e32 v164, 0x8000, v148
	v_add_u32_e32 v165, 0x9000, v148
	v_add_u32_e32 v166, 0xa000, v148
	s_waitcnt lgkmcnt(0)
	s_mov_b64 s[10:11], 0x20040
	v_add_u32_e32 v167, 0xb000, v148
	s_mov_b64 s[12:13], 0x80
	v_add_u32_e32 v168, v2, v1
	s_mov_b32 s25, 0x40000
	s_mov_b32 s26, 0x60000
	s_branch .LBB0_601

.LBB0_601:
	s_lshr_b32 s2, s21, 3
	s_or_b32 s2, s2, s22
	s_lshl_b32 s28, s2, 18
	s_and_b32 s27, s21, 7
	v_or_b32_e32 v1, s28, v129
	s_lshl_b32 s2, s27, 18
	s_add_u32 s14, s16, s2
	v_or_b32_e32 v0, v1, v128
	v_readfirstlane_b32 s2, v148
	v_lshlrev_b32_e32 v130, 1, v0
	s_mov_b32 m0, s2
	v_readfirstlane_b32 s2, v157
	v_add_lshl_u32 v0, v1, v154, 1
	s_waitcnt vmcnt(0)
	s_barrier
	s_nop 0
	s_mov_b32 m0, s2
	v_readfirstlane_b32 s2, v158
	s_addc_u32 s15, s17, 0
	v_add_lshl_u32 v2, v1, v155, 1
	s_nop 0
	s_mov_b32 m0, s2
	v_readfirstlane_b32 s2, v159
	v_add_lshl_u32 v4, v1, v156, 1
	v_lshl_add_u64 v[6:7], s[14:15], 0, v[132:133]
	s_nop 0
	s_mov_b32 m0, s2
	v_readfirstlane_b32 s2, v160
	v_lshl_add_u64 v[136:137], v[6:7], 0, v[134:135]
	s_nop 0
	s_mov_b32 m0, s2
	v_readfirstlane_b32 s2, v161
	v_lshl_add_u64 v[138:139], s[0:1], 0, v[130:131]
	v_mov_b32_e32 v1, v131
	v_lshl_add_u64 v[146:147], v[136:137], 0, s[4:5]
	s_nop 0
	s_mov_b32 m0, s2
	v_readfirstlane_b32 s2, v162
	v_lshl_add_u64 v[140:141], s[0:1], 0, v[0:1]
	v_mov_b32_e32 v3, v131
	s_nop 0
	v_lshl_add_u64 v[0:1], v[138:139], 0, 64
	s_mov_b32 m0, s2
	v_readfirstlane_b32 s2, v163
	v_lshl_add_u64 v[142:143], s[0:1], 0, v[2:3]
	v_mov_b32_e32 v5, v131
	s_nop 0
	v_lshl_add_u64 v[0:1], v[140:141], 0, 64
	s_mov_b32 m0, s2
	v_readfirstlane_b32 s2, v164
	v_lshl_add_u64 v[144:145], s[0:1], 0, v[4:5]
	s_nop 0
	v_lshl_add_u64 v[0:1], v[142:143], 0, 64
	s_mov_b32 m0, s2
	v_readfirstlane_b32 s2, v165
	s_nop 0
	v_lshl_add_u64 v[0:1], v[144:145], 0, 64
	s_mov_b32 m0, s2
	v_readfirstlane_b32 s2, v166
	s_nop 0
	v_lshl_add_u64 v[0:1], v[136:137], 0, 64
	s_mov_b32 m0, s2
	v_readfirstlane_b32 s2, v167
	s_nop 0
	v_lshl_add_u64 v[0:1], v[136:137], 0, s[10:11]
	s_mov_b32 m0, s2
	s_mov_b32 s14, s3
	s_nop 0
	s_mov_b32 s15, 2
	s_mov_b32 s29, s3
	v_mov_b32_e32 v0, 0
	v_mov_b32_e32 v1, v131
	v_mov_b32_e32 v2, v131
	v_mov_b32_e32 v4, v131
	v_mov_b32_e32 v6, v131
	v_mov_b32_e32 v7, v131
	v_mov_b32_e32 v8, v131
	v_mov_b32_e32 v9, v131
	v_mov_b32_e32 v10, v131
	v_mov_b32_e32 v11, v131
	v_mov_b32_e32 v12, v131
	v_mov_b32_e32 v13, v131
	v_mov_b32_e32 v14, v131
	v_mov_b32_e32 v15, v131
	v_mov_b32_e32 v16, 0
	v_mov_b32_e32 v17, v131
	v_mov_b32_e32 v18, v131
	v_mov_b32_e32 v19, v131
	v_mov_b32_e32 v20, v131
	v_mov_b32_e32 v21, v131
	v_mov_b32_e32 v22, v131
	v_mov_b32_e32 v23, v131
	v_mov_b32_e32 v24, v131
	v_mov_b32_e32 v25, v131
	v_mov_b32_e32 v26, v131
	v_mov_b32_e32 v27, v131
	v_mov_b32_e32 v28, v131
	v_mov_b32_e32 v29, v131
	v_mov_b32_e32 v30, v131
	v_mov_b32_e32 v31, v131
	v_mov_b32_e32 v32, 0
	v_mov_b32_e32 v33, v131
	v_mov_b32_e32 v34, v131
	v_mov_b32_e32 v35, v131
	v_mov_b32_e32 v36, v131
	v_mov_b32_e32 v37, v131
	v_mov_b32_e32 v38, v131
	v_mov_b32_e32 v39, v131
	v_mov_b32_e32 v40, v131
	v_mov_b32_e32 v41, v131
	v_mov_b32_e32 v42, v131
	v_mov_b32_e32 v43, v131
	v_mov_b32_e32 v44, v131
	v_mov_b32_e32 v45, v131
	v_mov_b32_e32 v46, v131
	v_mov_b32_e32 v47, v131
	v_mov_b32_e32 v48, 0
	v_mov_b32_e32 v49, v131
	v_mov_b32_e32 v50, v131
	v_mov_b32_e32 v51, v131
	v_mov_b32_e32 v52, v131
	v_mov_b32_e32 v53, v131
	v_mov_b32_e32 v54, v131
	v_mov_b32_e32 v55, v131
	v_mov_b32_e32 v56, v131
	v_mov_b32_e32 v57, v131
	v_mov_b32_e32 v58, v131
	v_mov_b32_e32 v59, v131
	v_mov_b32_e32 v60, v131
	v_mov_b32_e32 v61, v131
	v_mov_b32_e32 v62, v131
	v_mov_b32_e32 v63, v131
	v_mov_b32_e32 v64, 0
	v_mov_b32_e32 v65, v131
	v_mov_b32_e32 v66, v131
	v_mov_b32_e32 v67, v131
	v_mov_b32_e32 v68, v131
	v_mov_b32_e32 v69, v131
	v_mov_b32_e32 v70, v131
	v_mov_b32_e32 v71, v131
	v_mov_b32_e32 v72, v131
	v_mov_b32_e32 v73, v131
	v_mov_b32_e32 v74, v131
	v_mov_b32_e32 v75, v131
	v_mov_b32_e32 v76, v131
	v_mov_b32_e32 v77, v131
	v_mov_b32_e32 v78, v131
	v_mov_b32_e32 v79, v131
	v_mov_b32_e32 v80, 0
	v_mov_b32_e32 v81, v131
	v_mov_b32_e32 v82, v131
	v_mov_b32_e32 v83, v131
	v_mov_b32_e32 v84, v131
	v_mov_b32_e32 v85, v131
	v_mov_b32_e32 v86, v131
	v_mov_b32_e32 v87, v131
	v_mov_b32_e32 v88, v131
	v_mov_b32_e32 v89, v131
	v_mov_b32_e32 v90, v131
	v_mov_b32_e32 v91, v131
	v_mov_b32_e32 v92, v131
	v_mov_b32_e32 v93, v131
	v_mov_b32_e32 v94, v131
	v_mov_b32_e32 v95, v131
	v_mov_b32_e32 v96, 0
	v_mov_b32_e32 v97, v131
	v_mov_b32_e32 v98, v131
	v_mov_b32_e32 v99, v131
	v_mov_b32_e32 v100, v131
	v_mov_b32_e32 v101, v131
	v_mov_b32_e32 v102, v131
	v_mov_b32_e32 v103, v131
	v_mov_b32_e32 v104, v131
	v_mov_b32_e32 v105, v131
	v_mov_b32_e32 v106, v131
	v_mov_b32_e32 v107, v131
	v_mov_b32_e32 v108, v131
	v_mov_b32_e32 v109, v131
	v_mov_b32_e32 v110, v131
	v_mov_b32_e32 v111, v131
	v_mov_b32_e32 v112, 0
	v_mov_b32_e32 v113, v131
	v_mov_b32_e32 v114, v131
	v_mov_b32_e32 v115, v131
	v_mov_b32_e32 v116, v131
	v_mov_b32_e32 v117, v131
	v_mov_b32_e32 v118, v131
	v_mov_b32_e32 v119, v131
	v_mov_b32_e32 v120, v131
	v_mov_b32_e32 v121, v131
	v_mov_b32_e32 v122, v131
	v_mov_b32_e32 v123, v131
	v_mov_b32_e32 v124, v131
	v_mov_b32_e32 v125, v131
	v_mov_b32_e32 v126, v131
	v_mov_b32_e32 v127, v131
	s_mov_b64 s[50:51], 0x80
	v_lshrrev_b32_e32 v174, 6, v180
	v_lshlrev_b32_e32 v184, 11, v174
	v_and_b32_e32 v170, 63, v180
	v_readfirstlane_b32 s49, v184
	v_lshrrev_b32_e32 v171, 5, v170
	v_bfe_u32 v172, v170, 1, 3
	v_xor_b32_e32 v172, v171, v172
	v_and_b32_e32 v173, 31, v170
	v_lshlrev_b32_e32 v173, 7, v173
	v_lshrrev_b32_e32 v173, 3, v170
	v_lshlrev_b32_e32 v184, 4, v173
	v_add_u32_e32 v185, 0x80, v184
	v_and_b32_e32 v173, 7, v170
	v_lshrrev_b32_e32 v171, 4, v170
	v_xor_b32_e32 v171, v173, v171
	v_lshrrev_b32_e32 v173, 5, v170
	v_sub_u32_e32 v186, v171, v173
	v_xor_b32_e32 v171, 4, v171
	v_add_u32_e32 v173, 2, v173
	v_sub_u32_e32 v188, v171, v173
	v_lshlrev_b32_e32 v186, 4, v186
	v_ashrrev_i32_e32 v187, 31, v186
	v_lshlrev_b32_e32 v188, 4, v188
	v_ashrrev_i32_e32 v189, 31, v188
	ds_bpermute_b32 v244, v184, v136
	ds_bpermute_b32 v245, v184, v137
	ds_bpermute_b32 v246, v185, v136
	ds_bpermute_b32 v247, v185, v137
	ds_bpermute_b32 v248, v184, v146
	ds_bpermute_b32 v249, v184, v147
	ds_bpermute_b32 v250, v185, v146
	ds_bpermute_b32 v251, v185, v147
	s_waitcnt lgkmcnt(0)
	ds_bpermute_b32 v178, v184, v138
	ds_bpermute_b32 v179, v184, v139
	ds_bpermute_b32 v234, v185, v138
	ds_bpermute_b32 v235, v185, v139
	ds_bpermute_b32 v236, v184, v140
	ds_bpermute_b32 v237, v184, v141
	ds_bpermute_b32 v238, v185, v140
	ds_bpermute_b32 v239, v185, v141
	ds_bpermute_b32 v240, v184, v142
	ds_bpermute_b32 v241, v184, v143
	ds_bpermute_b32 v242, v185, v142
	ds_bpermute_b32 v243, v185, v143
	ds_bpermute_b32 v136, v184, v144
	ds_bpermute_b32 v137, v184, v145
	ds_bpermute_b32 v146, v185, v144
	ds_bpermute_b32 v147, v185, v145
	s_waitcnt lgkmcnt(0)
	v_and_b32_e32 v173, 31, v170
	v_lshlrev_b32_e32 v173, 7, v173
	v_lshrrev_b32_e32 v171, 1, v174
	v_lshl_add_u32 v138, v171, 14, v173
	v_and_b32_e32 v171, 1, v174
	v_lshl_add_u32 v142, v171, 13, v173
	v_add_u32_e32 v142, 0x10000, v142
	v_xor_b32_e32 v173, 6, v172
	v_lshl_add_u32 v141, v173, 4, v138
	v_lshl_add_u32 v145, v173, 4, v142
	v_xor_b32_e32 v173, 4, v172
	v_lshl_add_u32 v140, v173, 4, v138
	v_lshl_add_u32 v144, v173, 4, v142
	v_xor_b32_e32 v173, 2, v172
	v_lshl_add_u32 v139, v173, 4, v138
	v_lshl_add_u32 v143, v173, 4, v142
	v_xor_b32_e32 v173, 0, v172
	v_lshl_add_u32 v138, v173, 4, v138
	v_lshl_add_u32 v142, v173, 4, v142
	v_lshl_add_u64 v[178:179], v[178:179], 0, v[186:187]
	v_lshl_add_u64 v[234:235], v[234:235], 0, v[188:189]
	v_lshl_add_u64 v[236:237], v[236:237], 0, v[186:187]
	v_lshl_add_u64 v[238:239], v[238:239], 0, v[188:189]
	v_lshl_add_u64 v[240:241], v[240:241], 0, v[186:187]
	v_lshl_add_u64 v[242:243], v[242:243], 0, v[188:189]
	v_lshl_add_u64 v[136:137], v[136:137], 0, v[186:187]
	v_lshl_add_u64 v[146:147], v[146:147], 0, v[188:189]
	v_lshl_add_u64 v[244:245], v[244:245], 0, v[186:187]
	v_lshl_add_u64 v[246:247], v[246:247], 0, v[188:189]
	v_lshl_add_u64 v[248:249], v[248:249], 0, v[186:187]
	v_lshl_add_u64 v[250:251], v[250:251], 0, v[188:189]
	s_mov_b32 s54, s49
	s_add_i32 m0, s54, 0x0
	s_nop 0
	global_load_lds_dwordx4 v[178:179], off
	s_add_i32 m0, s54, 0x400
	v_lshl_add_u64 v[178:179], v[178:179], 0, s[50:51]
	global_load_lds_dwordx4 v[234:235], off
	s_add_i32 m0, s54, 0x2000
	v_lshl_add_u64 v[234:235], v[234:235], 0, s[50:51]
	global_load_lds_dwordx4 v[236:237], off
	s_add_i32 m0, s54, 0x2400
	v_lshl_add_u64 v[236:237], v[236:237], 0, s[50:51]
	global_load_lds_dwordx4 v[238:239], off
	s_add_i32 m0, s54, 0x4000
	v_lshl_add_u64 v[238:239], v[238:239], 0, s[50:51]
	global_load_lds_dwordx4 v[240:241], off
	s_add_i32 m0, s54, 0x4400
	v_lshl_add_u64 v[240:241], v[240:241], 0, s[50:51]
	global_load_lds_dwordx4 v[242:243], off
	s_add_i32 m0, s54, 0x6000
	v_lshl_add_u64 v[242:243], v[242:243], 0, s[50:51]
	global_load_lds_dwordx4 v[136:137], off
	s_add_i32 m0, s54, 0x6400
	v_lshl_add_u64 v[136:137], v[136:137], 0, s[50:51]
	global_load_lds_dwordx4 v[146:147], off
	v_lshl_add_u64 v[146:147], v[146:147], 0, s[50:51]
	s_add_i32 s54, s49, 0x10000
	s_add_i32 m0, s54, 0x0
	s_nop 0
	global_load_lds_dwordx4 v[244:245], off
	s_add_i32 m0, s54, 0x400
	v_lshl_add_u64 v[244:245], v[244:245], 0, s[50:51]
	global_load_lds_dwordx4 v[246:247], off
	s_add_i32 m0, s54, 0x2000
	v_lshl_add_u64 v[246:247], v[246:247], 0, s[50:51]
	global_load_lds_dwordx4 v[248:249], off
	s_add_i32 m0, s54, 0x2400
	v_lshl_add_u64 v[248:249], v[248:249], 0, s[50:51]
	global_load_lds_dwordx4 v[250:251], off
	v_lshl_add_u64 v[250:251], v[250:251], 0, s[50:51]
	s_mov_b32 s14, 0
	s_mov_b32 s15, 0

.Lg_ph5_noB:
	s_waitcnt lgkmcnt(3)
	v_mfma_f32_32x32x16_bf16 v[0:15], v[170:173], v[190:193], v[0:15]
	v_mfma_f32_32x32x16_bf16 v[16:31], v[170:173], v[194:197], v[16:31]
	ds_read_b128 v[170:173], v139
	s_waitcnt lgkmcnt(3)
	v_mfma_f32_32x32x16_bf16 v[32:47], v[174:177], v[190:193], v[32:47]
	v_mfma_f32_32x32x16_bf16 v[48:63], v[174:177], v[194:197], v[48:63]
	ds_read_b128 v[174:177], v139 offset:4096
	s_waitcnt lgkmcnt(3)
	v_mfma_f32_32x32x16_bf16 v[64:79], v[182:185], v[190:193], v[64:79]
	v_mfma_f32_32x32x16_bf16 v[80:95], v[182:185], v[194:197], v[80:95]
	ds_read_b128 v[182:185], v139 offset:8192
	s_waitcnt lgkmcnt(3)
	v_mfma_f32_32x32x16_bf16 v[96:111], v[186:189], v[190:193], v[96:111]
	v_mfma_f32_32x32x16_bf16 v[112:127], v[186:189], v[194:197], v[112:127]
	ds_read_b128 v[186:189], v139 offset:12288
	s_waitcnt lgkmcnt(3)
	v_mfma_f32_32x32x16_bf16 v[0:15], v[170:173], v[198:201], v[0:15]
	v_mfma_f32_32x32x16_bf16 v[16:31], v[170:173], v[202:205], v[16:31]
	ds_read_b128 v[170:173], v140
	s_waitcnt lgkmcnt(3)
	v_mfma_f32_32x32x16_bf16 v[32:47], v[174:177], v[198:201], v[32:47]
	v_mfma_f32_32x32x16_bf16 v[48:63], v[174:177], v[202:205], v[48:63]
	ds_read_b128 v[174:177], v140 offset:4096
	s_waitcnt lgkmcnt(3)
	v_mfma_f32_32x32x16_bf16 v[64:79], v[182:185], v[198:201], v[64:79]
	v_mfma_f32_32x32x16_bf16 v[80:95], v[182:185], v[202:205], v[80:95]
	ds_read_b128 v[182:185], v140 offset:8192
	s_waitcnt lgkmcnt(3)
	v_mfma_f32_32x32x16_bf16 v[96:111], v[186:189], v[198:201], v[96:111]
	v_mfma_f32_32x32x16_bf16 v[112:127], v[186:189], v[202:205], v[112:127]
	ds_read_b128 v[186:189], v140 offset:12288
	s_waitcnt lgkmcnt(3)
	v_mfma_f32_32x32x16_bf16 v[0:15], v[170:173], v[206:209], v[0:15]
	v_mfma_f32_32x32x16_bf16 v[16:31], v[170:173], v[222:225], v[16:31]
	ds_read_b128 v[170:173], v141
	s_waitcnt lgkmcnt(3)
	v_mfma_f32_32x32x16_bf16 v[32:47], v[174:177], v[206:209], v[32:47]
	v_mfma_f32_32x32x16_bf16 v[48:63], v[174:177], v[222:225], v[48:63]
	ds_read_b128 v[174:177], v141 offset:4096
	s_waitcnt lgkmcnt(3)
	v_mfma_f32_32x32x16_bf16 v[64:79], v[182:185], v[206:209], v[64:79]
	v_mfma_f32_32x32x16_bf16 v[80:95], v[182:185], v[222:225], v[80:95]
	ds_read_b128 v[182:185], v141 offset:8192
	s_waitcnt lgkmcnt(3)
	v_mfma_f32_32x32x16_bf16 v[96:111], v[186:189], v[206:209], v[96:111]
	v_mfma_f32_32x32x16_bf16 v[112:127], v[186:189], v[222:225], v[112:127]
	ds_read_b128 v[186:189], v141 offset:12288
	s_waitcnt lgkmcnt(3)
	v_mfma_f32_32x32x16_bf16 v[0:15], v[170:173], v[226:229], v[0:15]
	v_mfma_f32_32x32x16_bf16 v[16:31], v[170:173], v[230:233], v[16:31]
	s_waitcnt lgkmcnt(2)
	v_mfma_f32_32x32x16_bf16 v[32:47], v[174:177], v[226:229], v[32:47]
	v_mfma_f32_32x32x16_bf16 v[48:63], v[174:177], v[230:233], v[48:63]
	s_waitcnt lgkmcnt(1)
	v_mfma_f32_32x32x16_bf16 v[64:79], v[182:185], v[226:229], v[64:79]
	v_mfma_f32_32x32x16_bf16 v[80:95], v[182:185], v[230:233], v[80:95]
	s_waitcnt lgkmcnt(0)
	v_mfma_f32_32x32x16_bf16 v[96:111], v[186:189], v[226:229], v[96:111]
	v_mfma_f32_32x32x16_bf16 v[112:127], v[186:189], v[230:233], v[112:127]
	v_xor_b32_e32 v138, 0x8000, v138
	v_xor_b32_e32 v139, 0x8000, v139
	v_xor_b32_e32 v140, 0x8000, v140
	v_xor_b32_e32 v141, 0x8000, v141
	s_xor_b32 s15, s15, 0x8000
	s_add_i32 s14, s14, 1
	s_cmp_eq_u32 s14, 16
	s_cbranch_scc0 .Lg_ph5_top
	s_waitcnt vmcnt(0)
	v_mov_b32_e32 v130, v180
	v_add_u32_e32 v201, 0x400, v153
	v_add_u32_e32 v200, 0x1000, v153
	v_add_u32_e32 v199, 0x1400, v153
	v_add_u32_e32 v198, 0x2000, v153
	v_add_u32_e32 v192, 0x2400, v153
	v_add_u32_e32 v193, 0x3000, v153
	v_add_u32_e32 v194, 0x3200, v153
	v_add_u32_e32 v195, 0x3400, v153
	v_add_u32_e32 v196, 0x3600, v153
	v_add_u32_e32 v197, 0x4000, v153
	v_add_u32_e32 v189, 0x4400, v153
	v_add_u32_e32 v190, 0x4800, v153
	v_add_u32_e32 v191, 0x5000, v153
	v_add_u32_e32 v186, 0x5400, v153
	v_add_u32_e32 v187, 0x5800, v153
	v_add_u32_e32 v188, 0x6000, v153
	v_add_u32_e32 v179, 0x6400, v153
	v_add_u32_e32 v181, 0x6800, v153
	v_add_u32_e32 v182, 0x7200, v153
	v_add_u32_e32 v183, 0x7400, v153
	v_add_u32_e32 v184, 0x7600, v153
	v_add_u32_e32 v185, 0x7800, v153
	v_add_u32_e32 v178, 0x8400, v153
	v_add_u32_e32 v177, 0x8800, v153
	v_add_u32_e32 v176, 0x9400, v153
	v_add_u32_e32 v175, 0x9800, v153
	v_add_u32_e32 v174, 0xa400, v153
	v_add_u32_e32 v147, 0xa800, v153
	v_add_u32_e32 v169, 0xb400, v153
	v_add_u32_e32 v170, 0xb600, v153
	v_add_u32_e32 v171, 0xb800, v153
	v_add_u32_e32 v172, 0xba00, v153
	s_waitcnt vmcnt(0)
	s_barrier
	s_and_saveexec_b64 s[14:15], s[6:7]
	s_cbranch_execz .LBB0_605
	v_add_u32_e32 v136, 0xc400, v153
	ds_write2_b32 v153, v0, v16 offset1:32
	ds_write2_b32 v153, v1, v17 offset0:132 offset1:164
	ds_write2_b32 v201, v2, v18 offset0:8 offset1:40
	ds_write2_b32 v201, v3, v19 offset0:140 offset1:172
	ds_write2_b32 v200, v4, v20 offset0:32 offset1:64
	ds_write2_b32 v200, v5, v21 offset0:164 offset1:196
	ds_write2_b32 v199, v6, v22 offset0:40 offset1:72
	ds_write2_b32 v199, v7, v23 offset0:172 offset1:204
	ds_write2_b32 v198, v8, v24 offset0:64 offset1:96
	ds_write2_b32 v198, v9, v25 offset0:196 offset1:228
	ds_write2_b32 v192, v10, v26 offset0:72 offset1:104
	ds_write2_b32 v192, v11, v27 offset0:204 offset1:236
	ds_write2_b32 v193, v12, v28 offset0:96 offset1:128
	ds_write2_b32 v194, v13, v29 offset0:100 offset1:132
	ds_write2_b32 v195, v14, v30 offset0:104 offset1:136
	ds_write2_b32 v196, v15, v31 offset0:108 offset1:140
	ds_write2_b32 v197, v32, v48 offset0:128 offset1:160
	ds_write2_b32 v189, v33, v49 offset0:4 offset1:36
	ds_write2_b32 v189, v34, v50 offset0:136 offset1:168
	ds_write2_b32 v190, v35, v51 offset0:12 offset1:44
	ds_write2_b32 v191, v36, v52 offset0:160 offset1:192
	ds_write2_b32 v186, v37, v53 offset0:36 offset1:68
	ds_write2_b32 v186, v38, v54 offset0:168 offset1:200
	ds_write2_b32 v187, v39, v55 offset0:44 offset1:76
	ds_write2_b32 v188, v40, v56 offset0:192 offset1:224
	ds_write2_b32 v179, v41, v57 offset0:68 offset1:100
	ds_write2_b32 v179, v42, v58 offset0:200 offset1:232
	ds_write2_b32 v181, v43, v59 offset0:76 offset1:108
	ds_write2_b32 v182, v44, v60 offset0:96 offset1:128
	ds_write2_b32 v183, v45, v61 offset0:100 offset1:132
	ds_write2_b32 v184, v46, v62 offset0:104 offset1:136
	ds_write2_b32 v185, v47, v63 offset0:108 offset1:140
	ds_write2_b32 v178, v64, v80 offset1:32
	ds_write2_b32 v178, v65, v81 offset0:132 offset1:164
	ds_write2_b32 v177, v66, v82 offset0:8 offset1:40
	ds_write2_b32 v177, v67, v83 offset0:140 offset1:172
	ds_write2_b32 v176, v68, v84 offset0:32 offset1:64
	ds_write2_b32 v176, v69, v85 offset0:164 offset1:196
	ds_write2_b32 v175, v70, v86 offset0:40 offset1:72
	ds_write2_b32 v175, v71, v87 offset0:172 offset1:204
	ds_write2_b32 v174, v72, v88 offset0:64 offset1:96
	ds_write2_b32 v174, v73, v89 offset0:196 offset1:228
	ds_write2_b32 v147, v74, v90 offset0:72 offset1:104
	ds_write2_b32 v147, v75, v91 offset0:204 offset1:236
	ds_write2_b32 v169, v76, v92 offset0:96 offset1:128
	ds_write2_b32 v170, v77, v93 offset0:100 offset1:132
	ds_write2_b32 v171, v78, v94 offset0:104 offset1:136
	ds_write2_b32 v172, v79, v95 offset0:108 offset1:140
	ds_write2_b32 v136, v96, v112 offset0:128 offset1:160
	v_add_u32_e32 v136, 0xc800, v153
	ds_write2_b32 v136, v97, v113 offset0:4 offset1:36
	ds_write2_b32 v136, v98, v114 offset0:136 offset1:168
	v_add_u32_e32 v136, 0xcc00, v153
	ds_write2_b32 v136, v99, v115 offset0:12 offset1:44
	v_add_u32_e32 v136, 0xd400, v153
	ds_write2_b32 v136, v100, v116 offset0:160 offset1:192
	v_add_u32_e32 v136, 0xd800, v153
	ds_write2_b32 v136, v101, v117 offset0:36 offset1:68
	ds_write2_b32 v136, v102, v118 offset0:168 offset1:200
	v_add_u32_e32 v136, 0xdc00, v153
	ds_write2_b32 v136, v103, v119 offset0:44 offset1:76
	v_add_u32_e32 v136, 0xe400, v153
	ds_write2_b32 v136, v104, v120 offset0:192 offset1:224
	v_add_u32_e32 v136, 0xe800, v153
	ds_write2_b32 v136, v105, v121 offset0:68 offset1:100
	ds_write2_b32 v136, v106, v122 offset0:200 offset1:232
	v_add_u32_e32 v136, 0xec00, v153
	ds_write2_b32 v136, v107, v123 offset0:76 offset1:108
	v_add_u32_e32 v136, 0xf600, v153
	ds_write2_b32 v136, v108, v124 offset0:96 offset1:128
	v_add_u32_e32 v136, 0xf800, v153
	ds_write2_b32 v136, v109, v125 offset0:100 offset1:132
	v_add_u32_e32 v136, 0xfa00, v153
	ds_write2_b32 v136, v110, v126 offset0:104 offset1:136
	v_add_u32_e32 v136, 0xfc00, v153
	ds_write2_b32 v136, v111, v127 offset0:108 offset1:140

.LBB0_608:
	s_waitcnt lgkmcnt(0)
	s_cmp_lt_i32 s46, 7
	s_cbranch_scc1 .LBB0_662
	s_waitcnt vmcnt(0)
	v_mov_b32_e32 v254, 0x12000
	v_mov_b32_e32 v252, s97
	v_mov_b32_e32 v253, s96
	ds_write_b64 v254, v[252:253]
	s_waitcnt lgkmcnt(0)
	s_barrier
	s_mov_b64 s[0:1], exec
	v_readlane_b32 s2, v255, 5
	v_readlane_b32 s3, v255, 6
	s_and_b64 s[2:3], s[0:1], s[2:3]
	s_mov_b64 exec, s[2:3]
	s_cbranch_execz .LBB0_661
	s_add_i32 s46, 0, 0x12000
	s_mov_b64 s[2:3], src_shared_base
	s_cmp_lg_u32 s46, -1
	s_cselect_b32 s2, s46, 0
	s_cselect_b32 s4, s3, 0
	s_add_i32 s47, 0, 0x12004
	s_cmp_lg_u32 s47, -1
	v_mov_b32_e32 v0, s2
	v_mov_b32_e32 v1, s4
	s_cselect_b32 s2, s47, 0
	s_cselect_b32 s3, s3, 0
	s_waitcnt vmcnt(0) expcnt(0) lgkmcnt(0)
	flat_load_dword v2, v[0:1] sc0 sc1
	s_waitcnt vmcnt(0)
	v_mov_b32_e32 v0, s2
	v_mov_b32_e32 v1, s3
	flat_load_dword v0, v[0:1] sc0 sc1
	s_waitcnt vmcnt(0) lgkmcnt(0)
	v_cmp_eq_u32_e32 vcc, 0, v2
	s_and_saveexec_b64 s[2:3], vcc
	s_cbranch_execz .LBB0_625
	s_add_u32 s4, s94, 0x1d11e200
	s_addc_u32 s5, s95, 0
	s_add_u32 s6, s94, 0x1d11e400
	s_addc_u32 s7, s95, 0
	s_add_u32 s8, s94, 0x1d11e500
	s_addc_u32 s9, s95, 0
	s_add_u32 s10, s94, 0x1d11e600
	s_addc_u32 s11, s95, 0
	s_add_u32 s12, s94, 0x1d11e700
	s_addc_u32 s13, s95, 0
	s_add_u32 s14, s94, 0x1d11e800
	s_addc_u32 s15, s95, 0
	s_add_u32 s16, s94, 0x1d11e900
	s_addc_u32 s17, s95, 0
	s_add_u32 s18, s94, 0x1d11ea00
	s_addc_u32 s19, s95, 0
	s_add_u32 s20, s94, 0x1d11eb00
	s_addc_u32 s21, s95, 0
	s_add_u32 s22, s94, 0x1d11ec00
	s_addc_u32 s23, s95, 0
	s_add_u32 s24, s94, 0x1d11ed00
	s_addc_u32 s25, s95, 0
	s_add_u32 s26, s94, 0x1d11ee00
	s_addc_u32 s27, s95, 0
	s_add_u32 s28, s94, 0x1d11ef00
	s_addc_u32 s29, s95, 0
	s_add_u32 s30, s94, 0x1d11f000
	s_addc_u32 s31, s95, 0
	s_add_u32 s34, s94, 0x1d11f100
	s_addc_u32 s35, s95, 0
	s_add_u32 s36, s94, 0x1d11f200
	s_addc_u32 s37, s95, 0
	s_add_u32 s38, s94, 0x1d11f300
	s_addc_u32 s39, s95, 0
	s_mov_b32 s48, 1
	v_mov_b32_e32 v16, 0
	s_branch .LBB0_613

.LBB0_951:
	s_or_b64 exec, exec, s[26:27]
	v_readlane_b32 s0, v255, 4
	s_cmp_lt_i32 s0, 9
	s_cselect_b64 s[0:1], -1, 0
	v_cmp_lt_i32_e32 vcc, 8, v4
	s_and_b64 s[2:3], s[0:1], vcc
	s_and_saveexec_b64 s[0:1], s[2:3]
	s_cbranch_execz .LBB0_1017
	v_mov_b32_e32 v254, 0x12000
	ds_read_b64 v[252:253], v254
	s_waitcnt lgkmcnt(0)
	v_readfirstlane_b32 s97, v252
	v_readfirstlane_b32 s96, v253
	v_readlane_b32 s2, v255, 0
	s_cmpk_gt_u32 s2, 0x7ff
	v_readlane_b32 s3, v255, 1
	s_cbranch_scc1 .LBB0_962
	v_lshrrev_b32_e32 v2, 4, v180
	v_xor_b32_e32 v2, v2, v180
	v_lshlrev_b32_e32 v2, 3, v2
	v_and_b32_e32 v147, 24, v2
	v_lshlrev_b32_e32 v2, 4, v180
	s_add_u32 s2, s94, 0x1cfde000
	v_lshrrev_b32_e32 v0, 5, v180
	v_and_b32_e32 v2, 0x3c00, v2
	v_bfe_u32 v3, v180, 2, 2
	s_addc_u32 s3, s95, 0
	v_add_u32_e32 v148, 0, v2
	v_bfe_u32 v2, v180, 5, 1
	v_bitop3_b32 v0, v0, v3, 1 bitop3:0x6c
	s_add_u32 s4, s94, 0x16ede000
	v_lshlrev_b32_e32 v149, 4, v0
	v_bitop3_b32 v0, v2, v3, 2 bitop3:0x36
	s_addc_u32 s5, s95, 0
	v_and_b32_e32 v1, 31, v180
	v_lshlrev_b32_e32 v150, 4, v0
	v_lshlrev_b32_e32 v0, 6, v180
	v_and_b32_e32 v3, 64, v180
	v_lshrrev_b32_e32 v146, 2, v180
	s_add_u32 s16, s94, 0xcede000
	v_readlane_b32 s6, v255, 0
	v_and_b32_e32 v151, 0xe7c0, v0
	v_and_b32_e32 v152, 0x17c0, v0
	v_lshrrev_b32_e32 v0, 3, v180
	v_lshlrev_b32_e32 v3, 2, v3
	v_lshlrev_b32_e32 v1, 2, v1
	s_addc_u32 s17, s95, 0
	v_readlane_b32 s7, v255, 1
	s_lshr_b32 s19, s6, 3
	s_bfe_u32 s20, s6, 0x20001
	s_lshl_b32 s6, s6, 3
	v_add3_u32 v3, 0, v3, v1
	s_movk_i32 s8, 0x80
	s_movk_i32 s9, 0x840
	v_and_b32_e32 v1, 0x380, v180
	v_or_b32_e32 v0, 0x7b, v0
	v_lshlrev_b32_e32 v128, 11, v146
	v_mov_b32_e32 v129, 0
	s_and_b32 s21, s6, 8
	v_cmp_gt_u32_e64 s[6:7], s8, v180
	v_mad_u32_u24 v153, v2, s9, v3
	v_cmp_eq_u32_e64 s[8:9], s8, v1
	v_mul_u32_u24_e32 v2, 0x210, v0
	v_lshl_add_u64 v[0:1], s[94:95], 0, v[128:129]
	v_lshlrev_b32_e32 v128, 1, v147
	v_lshl_add_u64 v[0:1], v[0:1], 0, v[128:129]
	s_waitcnt lgkmcnt(0)
	s_mov_b64 s[12:13], 0xca0000
	v_lshl_add_u64 v[130:131], v[0:1], 0, s[12:13]
	s_mov_b64 s[12:13], 0x4ca0000
	s_lshr_b32 s18, s33, 3
	s_mov_b32 s11, 0
	s_movk_i32 s22, 0x210
	v_lshl_add_u64 v[132:133], v[0:1], 0, s[12:13]
	v_add_u32_e32 v154, 0x1000, v148
	v_add_u32_e32 v155, 0x2000, v148
	v_add_u32_e32 v156, 0x3000, v148
	v_add_u32_e32 v157, 0x4000, v148
	v_add_u32_e32 v158, 0x5000, v148
	v_add_u32_e32 v159, 0x6000, v148
	v_add_u32_e32 v160, 0x7000, v148
	v_add_u32_e32 v161, 0x8000, v148
	v_add_u32_e32 v162, 0x9000, v148
	v_add_u32_e32 v163, 0xa000, v148
	v_add_u32_e32 v164, 0xb000, v148
	s_mov_b64 s[12:13], 0x80
	s_mov_b32 s23, 0x20000
	v_add_u32_e32 v165, v3, v2
	s_mov_b32 s24, 0x40000
	s_mov_b32 s25, 0x60000
	s_branch .LBB0_955

.LBB0_955:
	s_lshr_b32 s10, s19, 4
	s_and_b32 s10, s10, 12
	s_bfe_u32 s28, s19, 0x20001
	s_or_b32 s10, s10, s20
	s_lshl_b32 s14, s28, 4
	s_and_b32 s26, s19, 1
	s_or_b32 s27, s14, s10
	s_lshl_b32 s14, s27, 9
	s_lshl_b32 s15, s26, 8
	s_or_b32 s14, s14, s15
	v_or_b32_e32 v0, s14, v146
	v_lshlrev_b32_e32 v0, 2, v0
	global_load_dword v2, v0, s[2:3]
	global_load_dword v4, v0, s[2:3] offset:256
	global_load_dword v10, v0, s[2:3] offset:512
	global_load_dword v11, v0, s[2:3] offset:768
	s_lshl_b32 s44, s28, 22
	v_readfirstlane_b32 s30, v148
	s_bfe_u32 s29, s19, 0x30003
	v_readfirstlane_b32 s31, v154
	s_mov_b32 m0, s30
	v_readfirstlane_b32 s34, v155
	s_or_b32 s28, s29, s21
	s_waitcnt vmcnt(0)
	s_barrier
	v_readfirstlane_b32 s35, v156
	s_lshl_b32 s29, s28, 17
	s_lshl_b32 s10, s10, 21
	v_readfirstlane_b32 s36, v157
	s_or_b32 s10, s10, s29
	v_readfirstlane_b32 s37, v158
	v_lshl_add_u64 v[134:135], v[130:131], 0, s[10:11]
	v_mov_b32_e32 v1, v129
	v_readfirstlane_b32 s38, v159
	v_lshl_add_u64 v[136:137], v[132:133], 0, s[10:11]
	v_mov_b32_e32 v3, v129
	v_readfirstlane_b32 s39, v160
	v_mov_b32_e32 v5, v129
	v_readfirstlane_b32 s40, v161
	v_readfirstlane_b32 s41, v162
	v_readfirstlane_b32 s42, v163
	v_readfirstlane_b32 s43, v164
	v_lshl_add_u64 v[6:7], v[134:135], 0, 64
	v_lshl_add_u64 v[8:9], v[136:137], 0, 64
	s_mov_b32 s14, s11
	s_mov_b32 s15, 2
	s_mov_b32 s29, s11
	v_mov_b32_e32 v16, 0
	v_mov_b32_e32 v17, v129
	v_mov_b32_e32 v18, v129
	v_mov_b32_e32 v19, v129
	v_mov_b32_e32 v20, v129
	v_mov_b32_e32 v21, v129
	v_mov_b32_e32 v22, v129
	v_mov_b32_e32 v23, v129
	v_mov_b32_e32 v24, v129
	v_mov_b32_e32 v25, v129
	v_mov_b32_e32 v26, v129
	v_mov_b32_e32 v27, v129
	v_mov_b32_e32 v28, v129
	v_mov_b32_e32 v29, v129
	v_mov_b32_e32 v30, v129
	v_mov_b32_e32 v31, v129
	v_mov_b32_e32 v32, 0
	v_mov_b32_e32 v33, v129
	v_mov_b32_e32 v34, v129
	v_mov_b32_e32 v35, v129
	v_mov_b32_e32 v36, v129
	v_mov_b32_e32 v37, v129
	v_mov_b32_e32 v38, v129
	v_mov_b32_e32 v39, v129
	v_mov_b32_e32 v40, v129
	v_mov_b32_e32 v41, v129
	v_mov_b32_e32 v42, v129
	v_mov_b32_e32 v43, v129
	v_mov_b32_e32 v44, v129
	v_mov_b32_e32 v45, v129
	v_mov_b32_e32 v46, v129
	v_mov_b32_e32 v47, v129
	v_mov_b32_e32 v48, 0
	v_mov_b32_e32 v49, v129
	v_mov_b32_e32 v50, v129
	v_mov_b32_e32 v51, v129
	v_mov_b32_e32 v52, v129
	v_mov_b32_e32 v53, v129
	v_mov_b32_e32 v54, v129
	v_mov_b32_e32 v55, v129
	v_mov_b32_e32 v56, v129
	v_mov_b32_e32 v57, v129
	v_mov_b32_e32 v58, v129
	s_waitcnt vmcnt(3)
	v_lshl_add_u32 v0, v2, 10, s44
	s_waitcnt vmcnt(2)
	v_lshl_add_u32 v2, v4, 10, s44
	v_or_b32_e32 v0, v0, v147
	s_waitcnt vmcnt(1)
	v_lshl_add_u32 v4, v10, 10, s44
	v_or_b32_e32 v2, v2, v147
	v_lshlrev_b32_e32 v128, 1, v0
	s_waitcnt vmcnt(0)
	v_lshl_add_u32 v10, v11, 10, s44
	v_or_b32_e32 v4, v4, v147
	v_lshlrev_b32_e32 v0, 1, v2
	s_nop 0
	s_mov_b32 m0, s31
	v_or_b32_e32 v10, v10, v147
	v_lshlrev_b32_e32 v2, 1, v4
	s_nop 0
	s_mov_b32 m0, s34
	v_lshlrev_b32_e32 v4, 1, v10
	s_nop 0
	s_mov_b32 m0, s35
	v_lshl_add_u64 v[138:139], s[4:5], 0, v[128:129]
	s_nop 0
	s_mov_b32 m0, s36
	v_lshl_add_u64 v[140:141], s[4:5], 0, v[0:1]
	s_nop 0
	s_mov_b32 m0, s37
	v_lshl_add_u64 v[0:1], v[138:139], 0, 64
	s_nop 0
	s_mov_b32 m0, s38
	v_lshl_add_u64 v[142:143], s[4:5], 0, v[2:3]
	v_lshl_add_u64 v[10:11], v[140:141], 0, 64
	s_nop 0
	s_mov_b32 m0, s39
	v_lshl_add_u64 v[144:145], s[4:5], 0, v[4:5]
	v_lshl_add_u64 v[12:13], v[142:143], 0, 64
	s_nop 0
	s_mov_b32 m0, s40
	v_lshl_add_u64 v[14:15], v[144:145], 0, 64
	s_nop 0
	s_mov_b32 m0, s41
	v_mov_b32_e32 v0, 0
	s_nop 0
	s_mov_b32 m0, s42
	v_mov_b32_e32 v1, v129
	s_nop 0
	s_mov_b32 m0, s43
	v_mov_b32_e32 v2, v129
	s_nop 0
	v_mov_b32_e32 v4, v129
	v_mov_b32_e32 v6, v129
	v_mov_b32_e32 v7, v129
	v_mov_b32_e32 v8, v129
	v_mov_b32_e32 v9, v129
	v_mov_b32_e32 v10, v129
	v_mov_b32_e32 v11, v129
	v_mov_b32_e32 v12, v129
	v_mov_b32_e32 v13, v129
	v_mov_b32_e32 v14, v129
	v_mov_b32_e32 v15, v129
	v_mov_b32_e32 v59, v129
	v_mov_b32_e32 v60, v129
	v_mov_b32_e32 v61, v129
	v_mov_b32_e32 v62, v129
	v_mov_b32_e32 v63, v129
	v_mov_b32_e32 v64, 0
	v_mov_b32_e32 v65, v129
	v_mov_b32_e32 v66, v129
	v_mov_b32_e32 v67, v129
	v_mov_b32_e32 v68, v129
	v_mov_b32_e32 v69, v129
	v_mov_b32_e32 v70, v129
	v_mov_b32_e32 v71, v129
	v_mov_b32_e32 v72, v129
	v_mov_b32_e32 v73, v129
	v_mov_b32_e32 v74, v129
	v_mov_b32_e32 v75, v129
	v_mov_b32_e32 v76, v129
	v_mov_b32_e32 v77, v129
	v_mov_b32_e32 v78, v129
	v_mov_b32_e32 v79, v129
	v_mov_b32_e32 v80, 0
	v_mov_b32_e32 v81, v129
	v_mov_b32_e32 v82, v129
	v_mov_b32_e32 v83, v129
	v_mov_b32_e32 v84, v129
	v_mov_b32_e32 v85, v129
	v_mov_b32_e32 v86, v129
	v_mov_b32_e32 v87, v129
	v_mov_b32_e32 v88, v129
	v_mov_b32_e32 v89, v129
	v_mov_b32_e32 v90, v129
	v_mov_b32_e32 v91, v129
	v_mov_b32_e32 v92, v129
	v_mov_b32_e32 v93, v129
	v_mov_b32_e32 v94, v129
	v_mov_b32_e32 v95, v129
	v_mov_b32_e32 v96, 0
	v_mov_b32_e32 v97, v129
	v_mov_b32_e32 v98, v129
	v_mov_b32_e32 v99, v129
	v_mov_b32_e32 v100, v129
	v_mov_b32_e32 v101, v129
	v_mov_b32_e32 v102, v129
	v_mov_b32_e32 v103, v129
	v_mov_b32_e32 v104, v129
	v_mov_b32_e32 v105, v129
	v_mov_b32_e32 v106, v129
	v_mov_b32_e32 v107, v129
	v_mov_b32_e32 v108, v129
	v_mov_b32_e32 v109, v129
	v_mov_b32_e32 v110, v129
	v_mov_b32_e32 v111, v129
	v_mov_b32_e32 v112, 0
	v_mov_b32_e32 v113, v129
	v_mov_b32_e32 v114, v129
	v_mov_b32_e32 v115, v129
	v_mov_b32_e32 v116, v129
	v_mov_b32_e32 v117, v129
	v_mov_b32_e32 v118, v129
	v_mov_b32_e32 v119, v129
	v_mov_b32_e32 v120, v129
	v_mov_b32_e32 v121, v129
	v_mov_b32_e32 v122, v129
	v_mov_b32_e32 v123, v129
	v_mov_b32_e32 v124, v129
	v_mov_b32_e32 v125, v129
	v_mov_b32_e32 v126, v129
	v_mov_b32_e32 v127, v129
	s_mov_b64 s[54:55], 0x80
	v_lshrrev_b32_e32 v170, 6, v180
	v_lshlrev_b32_e32 v176, 11, v170
	v_and_b32_e32 v166, 63, v180
	v_readfirstlane_b32 s53, v176
	v_lshrrev_b32_e32 v167, 5, v166
	v_bfe_u32 v168, v166, 1, 3
	v_xor_b32_e32 v168, v167, v168
	v_and_b32_e32 v169, 31, v166
	v_lshlrev_b32_e32 v169, 7, v169
	v_lshrrev_b32_e32 v169, 3, v166
	v_lshlrev_b32_e32 v176, 4, v169
	v_add_u32_e32 v177, 0x80, v176
	v_and_b32_e32 v169, 7, v166
	v_lshrrev_b32_e32 v167, 4, v166
	v_xor_b32_e32 v167, v169, v167
	v_lshrrev_b32_e32 v169, 5, v166
	v_sub_u32_e32 v182, v167, v169
	v_xor_b32_e32 v167, 4, v167
	v_add_u32_e32 v169, 2, v169
	v_sub_u32_e32 v184, v167, v169
	v_lshlrev_b32_e32 v182, 4, v182
	v_ashrrev_i32_e32 v183, 31, v182
	v_lshlrev_b32_e32 v184, 4, v184
	v_ashrrev_i32_e32 v185, 31, v184
	ds_bpermute_b32 v242, v176, v134
	ds_bpermute_b32 v243, v176, v135
	ds_bpermute_b32 v244, v177, v134
	ds_bpermute_b32 v245, v177, v135
	ds_bpermute_b32 v246, v176, v136
	ds_bpermute_b32 v247, v176, v137
	ds_bpermute_b32 v248, v177, v136
	ds_bpermute_b32 v249, v177, v137
	s_waitcnt lgkmcnt(0)
	ds_bpermute_b32 v178, v176, v138
	ds_bpermute_b32 v179, v176, v139
	ds_bpermute_b32 v232, v177, v138
	ds_bpermute_b32 v233, v177, v139
	ds_bpermute_b32 v234, v176, v140
	ds_bpermute_b32 v235, v176, v141
	ds_bpermute_b32 v236, v177, v140
	ds_bpermute_b32 v237, v177, v141
	ds_bpermute_b32 v238, v176, v142
	ds_bpermute_b32 v239, v176, v143
	ds_bpermute_b32 v240, v177, v142
	ds_bpermute_b32 v241, v177, v143
	ds_bpermute_b32 v134, v176, v144
	ds_bpermute_b32 v135, v176, v145
	ds_bpermute_b32 v136, v177, v144
	ds_bpermute_b32 v137, v177, v145
	s_waitcnt lgkmcnt(0)
	v_and_b32_e32 v169, 31, v166
	v_lshlrev_b32_e32 v169, 7, v169
	v_lshrrev_b32_e32 v167, 1, v170
	v_lshl_add_u32 v138, v167, 14, v169
	v_and_b32_e32 v167, 1, v170
	v_lshl_add_u32 v142, v167, 13, v169
	v_add_u32_e32 v142, 0x10000, v142
	v_xor_b32_e32 v169, 6, v168
	v_lshl_add_u32 v141, v169, 4, v138
	v_lshl_add_u32 v145, v169, 4, v142
	v_xor_b32_e32 v169, 4, v168
	v_lshl_add_u32 v140, v169, 4, v138
	v_lshl_add_u32 v144, v169, 4, v142
	v_xor_b32_e32 v169, 2, v168
	v_lshl_add_u32 v139, v169, 4, v138
	v_lshl_add_u32 v143, v169, 4, v142
	v_xor_b32_e32 v169, 0, v168
	v_lshl_add_u32 v138, v169, 4, v138
	v_lshl_add_u32 v142, v169, 4, v142
	v_lshl_add_u64 v[178:179], v[178:179], 0, v[182:183]
	v_lshl_add_u64 v[232:233], v[232:233], 0, v[184:185]
	v_lshl_add_u64 v[234:235], v[234:235], 0, v[182:183]
	v_lshl_add_u64 v[236:237], v[236:237], 0, v[184:185]
	v_lshl_add_u64 v[238:239], v[238:239], 0, v[182:183]
	v_lshl_add_u64 v[240:241], v[240:241], 0, v[184:185]
	v_lshl_add_u64 v[134:135], v[134:135], 0, v[182:183]
	v_lshl_add_u64 v[136:137], v[136:137], 0, v[184:185]
	v_lshl_add_u64 v[242:243], v[242:243], 0, v[182:183]
	v_lshl_add_u64 v[244:245], v[244:245], 0, v[184:185]
	v_lshl_add_u64 v[246:247], v[246:247], 0, v[182:183]
	v_lshl_add_u64 v[248:249], v[248:249], 0, v[184:185]
	s_mov_b32 s58, s53
	s_add_i32 m0, s58, 0x0
	s_nop 0
	global_load_lds_dwordx4 v[178:179], off
	s_add_i32 m0, s58, 0x400
	v_lshl_add_u64 v[178:179], v[178:179], 0, s[54:55]
	global_load_lds_dwordx4 v[232:233], off
	s_add_i32 m0, s58, 0x2000
	v_lshl_add_u64 v[232:233], v[232:233], 0, s[54:55]
	global_load_lds_dwordx4 v[234:235], off
	s_add_i32 m0, s58, 0x2400
	v_lshl_add_u64 v[234:235], v[234:235], 0, s[54:55]
	global_load_lds_dwordx4 v[236:237], off
	s_add_i32 m0, s58, 0x4000
	v_lshl_add_u64 v[236:237], v[236:237], 0, s[54:55]
	global_load_lds_dwordx4 v[238:239], off
	s_add_i32 m0, s58, 0x4400
	v_lshl_add_u64 v[238:239], v[238:239], 0, s[54:55]
	global_load_lds_dwordx4 v[240:241], off
	s_add_i32 m0, s58, 0x6000
	v_lshl_add_u64 v[240:241], v[240:241], 0, s[54:55]
	global_load_lds_dwordx4 v[134:135], off
	s_add_i32 m0, s58, 0x6400
	v_lshl_add_u64 v[134:135], v[134:135], 0, s[54:55]
	global_load_lds_dwordx4 v[136:137], off
	v_lshl_add_u64 v[136:137], v[136:137], 0, s[54:55]
	s_add_i32 s58, s53, 0x10000
	s_add_i32 m0, s58, 0x0
	s_nop 0
	global_load_lds_dwordx4 v[242:243], off
	s_add_i32 m0, s58, 0x400
	v_lshl_add_u64 v[242:243], v[242:243], 0, s[54:55]
	global_load_lds_dwordx4 v[244:245], off
	s_add_i32 m0, s58, 0x2000
	v_lshl_add_u64 v[244:245], v[244:245], 0, s[54:55]
	global_load_lds_dwordx4 v[246:247], off
	s_add_i32 m0, s58, 0x2400
	v_lshl_add_u64 v[246:247], v[246:247], 0, s[54:55]
	global_load_lds_dwordx4 v[248:249], off
	v_lshl_add_u64 v[248:249], v[248:249], 0, s[54:55]
	s_mov_b32 s14, 0
	s_mov_b32 s15, 0

.Lg_ph8_noB:
	s_waitcnt lgkmcnt(3)
	v_mfma_f32_32x32x16_bf16 v[0:15], v[166:169], v[190:193], v[0:15]
	v_mfma_f32_32x32x16_bf16 v[16:31], v[166:169], v[194:197], v[16:31]
	ds_read_b128 v[166:169], v139
	s_waitcnt lgkmcnt(3)
	v_mfma_f32_32x32x16_bf16 v[32:47], v[170:173], v[190:193], v[32:47]
	v_mfma_f32_32x32x16_bf16 v[48:63], v[170:173], v[194:197], v[48:63]
	ds_read_b128 v[170:173], v139 offset:4096
	s_waitcnt lgkmcnt(3)
	v_mfma_f32_32x32x16_bf16 v[64:79], v[174:177], v[190:193], v[64:79]
	v_mfma_f32_32x32x16_bf16 v[80:95], v[174:177], v[194:197], v[80:95]
	ds_read_b128 v[174:177], v139 offset:8192
	s_waitcnt lgkmcnt(3)
	v_mfma_f32_32x32x16_bf16 v[96:111], v[182:185], v[190:193], v[96:111]
	v_mfma_f32_32x32x16_bf16 v[112:127], v[182:185], v[194:197], v[112:127]
	ds_read_b128 v[182:185], v139 offset:12288
	s_waitcnt lgkmcnt(3)
	v_mfma_f32_32x32x16_bf16 v[0:15], v[166:169], v[198:201], v[0:15]
	v_mfma_f32_32x32x16_bf16 v[16:31], v[166:169], v[202:205], v[16:31]
	ds_read_b128 v[166:169], v140
	s_waitcnt lgkmcnt(3)
	v_mfma_f32_32x32x16_bf16 v[32:47], v[170:173], v[198:201], v[32:47]
	v_mfma_f32_32x32x16_bf16 v[48:63], v[170:173], v[202:205], v[48:63]
	ds_read_b128 v[170:173], v140 offset:4096
	s_waitcnt lgkmcnt(3)
	v_mfma_f32_32x32x16_bf16 v[64:79], v[174:177], v[198:201], v[64:79]
	v_mfma_f32_32x32x16_bf16 v[80:95], v[174:177], v[202:205], v[80:95]
	ds_read_b128 v[174:177], v140 offset:8192
	s_waitcnt lgkmcnt(3)
	v_mfma_f32_32x32x16_bf16 v[96:111], v[182:185], v[198:201], v[96:111]
	v_mfma_f32_32x32x16_bf16 v[112:127], v[182:185], v[202:205], v[112:127]
	ds_read_b128 v[182:185], v140 offset:12288
	s_waitcnt lgkmcnt(3)
	v_mfma_f32_32x32x16_bf16 v[0:15], v[166:169], v[206:209], v[0:15]
	v_mfma_f32_32x32x16_bf16 v[16:31], v[166:169], v[220:223], v[16:31]
	ds_read_b128 v[166:169], v141
	s_waitcnt lgkmcnt(3)
	v_mfma_f32_32x32x16_bf16 v[32:47], v[170:173], v[206:209], v[32:47]
	v_mfma_f32_32x32x16_bf16 v[48:63], v[170:173], v[220:223], v[48:63]
	ds_read_b128 v[170:173], v141 offset:4096
	s_waitcnt lgkmcnt(3)
	v_mfma_f32_32x32x16_bf16 v[64:79], v[174:177], v[206:209], v[64:79]
	v_mfma_f32_32x32x16_bf16 v[80:95], v[174:177], v[220:223], v[80:95]
	ds_read_b128 v[174:177], v141 offset:8192
	s_waitcnt lgkmcnt(3)
	v_mfma_f32_32x32x16_bf16 v[96:111], v[182:185], v[206:209], v[96:111]
	v_mfma_f32_32x32x16_bf16 v[112:127], v[182:185], v[220:223], v[112:127]
	ds_read_b128 v[182:185], v141 offset:12288
	s_waitcnt lgkmcnt(3)
	v_mfma_f32_32x32x16_bf16 v[0:15], v[166:169], v[224:227], v[0:15]
	v_mfma_f32_32x32x16_bf16 v[16:31], v[166:169], v[228:231], v[16:31]
	s_waitcnt lgkmcnt(2)
	v_mfma_f32_32x32x16_bf16 v[32:47], v[170:173], v[224:227], v[32:47]
	v_mfma_f32_32x32x16_bf16 v[48:63], v[170:173], v[228:231], v[48:63]
	s_waitcnt lgkmcnt(1)
	v_mfma_f32_32x32x16_bf16 v[64:79], v[174:177], v[224:227], v[64:79]
	v_mfma_f32_32x32x16_bf16 v[80:95], v[174:177], v[228:231], v[80:95]
	s_waitcnt lgkmcnt(0)
	v_mfma_f32_32x32x16_bf16 v[96:111], v[182:185], v[224:227], v[96:111]
	v_mfma_f32_32x32x16_bf16 v[112:127], v[182:185], v[228:231], v[112:127]
	v_xor_b32_e32 v138, 0x8000, v138
	v_xor_b32_e32 v139, 0x8000, v139
	v_xor_b32_e32 v140, 0x8000, v140
	v_xor_b32_e32 v141, 0x8000, v141
	s_xor_b32 s15, s15, 0x8000
	s_add_i32 s14, s14, 1
	s_cmp_eq_u32 s14, 16
	s_cbranch_scc0 .Lg_ph8_top
	s_waitcnt vmcnt(0)
	v_mov_b32_e32 v128, v180
	v_add_u32_e32 v193, 0x400, v153
	v_add_u32_e32 v192, 0x1000, v153
	v_add_u32_e32 v191, 0x1400, v153
	v_add_u32_e32 v190, 0x2000, v153
	v_add_u32_e32 v183, 0x2400, v153
	v_add_u32_e32 v184, 0x3000, v153
	v_add_u32_e32 v185, 0x3200, v153
	v_add_u32_e32 v186, 0x3400, v153
	v_add_u32_e32 v187, 0x3600, v153
	v_add_u32_e32 v189, 0x4000, v153
	v_add_u32_e32 v179, 0x4400, v153
	v_add_u32_e32 v181, 0x4800, v153
	v_add_u32_e32 v182, 0x5000, v153
	v_add_u32_e32 v176, 0x5400, v153
	v_add_u32_e32 v177, 0x5800, v153
	v_add_u32_e32 v178, 0x6000, v153
	v_add_u32_e32 v170, 0x6400, v153
	v_add_u32_e32 v171, 0x6800, v153
	v_add_u32_e32 v172, 0x7200, v153
	v_add_u32_e32 v173, 0x7400, v153
	v_add_u32_e32 v174, 0x7600, v153
	v_add_u32_e32 v175, 0x7800, v153
	v_add_u32_e32 v169, 0x8400, v153
	v_add_u32_e32 v168, 0x8800, v153
	v_add_u32_e32 v167, 0x9400, v153
	v_add_u32_e32 v166, 0x9800, v153
	v_add_u32_e32 v145, 0xa400, v153
	v_add_u32_e32 v140, 0xa800, v153
	v_add_u32_e32 v141, 0xb400, v153
	v_add_u32_e32 v142, 0xb600, v153
	v_add_u32_e32 v143, 0xb800, v153
	v_add_u32_e32 v144, 0xba00, v153
	s_waitcnt vmcnt(0)
	s_barrier
	s_and_saveexec_b64 s[14:15], s[6:7]
	s_cbranch_execz .LBB0_959
	v_add_u32_e32 v134, 0xc400, v153
	ds_write2_b32 v153, v0, v16 offset1:32
	ds_write2_b32 v153, v1, v17 offset0:132 offset1:164
	ds_write2_b32 v193, v2, v18 offset0:8 offset1:40
	ds_write2_b32 v193, v3, v19 offset0:140 offset1:172
	ds_write2_b32 v192, v4, v20 offset0:32 offset1:64
	ds_write2_b32 v192, v5, v21 offset0:164 offset1:196
	ds_write2_b32 v191, v6, v22 offset0:40 offset1:72
	ds_write2_b32 v191, v7, v23 offset0:172 offset1:204
	ds_write2_b32 v190, v8, v24 offset0:64 offset1:96
	ds_write2_b32 v190, v9, v25 offset0:196 offset1:228
	ds_write2_b32 v183, v10, v26 offset0:72 offset1:104
	ds_write2_b32 v183, v11, v27 offset0:204 offset1:236
	ds_write2_b32 v184, v12, v28 offset0:96 offset1:128
	ds_write2_b32 v185, v13, v29 offset0:100 offset1:132
	ds_write2_b32 v186, v14, v30 offset0:104 offset1:136
	ds_write2_b32 v187, v15, v31 offset0:108 offset1:140
	ds_write2_b32 v189, v32, v48 offset0:128 offset1:160
	ds_write2_b32 v179, v33, v49 offset0:4 offset1:36
	ds_write2_b32 v179, v34, v50 offset0:136 offset1:168
	ds_write2_b32 v181, v35, v51 offset0:12 offset1:44
	ds_write2_b32 v182, v36, v52 offset0:160 offset1:192
	ds_write2_b32 v176, v37, v53 offset0:36 offset1:68
	ds_write2_b32 v176, v38, v54 offset0:168 offset1:200
	ds_write2_b32 v177, v39, v55 offset0:44 offset1:76
	ds_write2_b32 v178, v40, v56 offset0:192 offset1:224
	ds_write2_b32 v170, v41, v57 offset0:68 offset1:100
	ds_write2_b32 v170, v42, v58 offset0:200 offset1:232
	ds_write2_b32 v171, v43, v59 offset0:76 offset1:108
	ds_write2_b32 v172, v44, v60 offset0:96 offset1:128
	ds_write2_b32 v173, v45, v61 offset0:100 offset1:132
	ds_write2_b32 v174, v46, v62 offset0:104 offset1:136
	ds_write2_b32 v175, v47, v63 offset0:108 offset1:140
	ds_write2_b32 v169, v64, v80 offset1:32
	ds_write2_b32 v169, v65, v81 offset0:132 offset1:164
	ds_write2_b32 v168, v66, v82 offset0:8 offset1:40
	ds_write2_b32 v168, v67, v83 offset0:140 offset1:172
	ds_write2_b32 v167, v68, v84 offset0:32 offset1:64
	ds_write2_b32 v167, v69, v85 offset0:164 offset1:196
	ds_write2_b32 v166, v70, v86 offset0:40 offset1:72
	ds_write2_b32 v166, v71, v87 offset0:172 offset1:204
	ds_write2_b32 v145, v72, v88 offset0:64 offset1:96
	ds_write2_b32 v145, v73, v89 offset0:196 offset1:228
	ds_write2_b32 v140, v74, v90 offset0:72 offset1:104
	ds_write2_b32 v140, v75, v91 offset0:204 offset1:236
	ds_write2_b32 v141, v76, v92 offset0:96 offset1:128
	ds_write2_b32 v142, v77, v93 offset0:100 offset1:132
	ds_write2_b32 v143, v78, v94 offset0:104 offset1:136
	ds_write2_b32 v144, v79, v95 offset0:108 offset1:140
	ds_write2_b32 v134, v96, v112 offset0:128 offset1:160
	v_add_u32_e32 v134, 0xc800, v153
	ds_write2_b32 v134, v97, v113 offset0:4 offset1:36
	ds_write2_b32 v134, v98, v114 offset0:136 offset1:168
	v_add_u32_e32 v134, 0xcc00, v153
	ds_write2_b32 v134, v99, v115 offset0:12 offset1:44
	v_add_u32_e32 v134, 0xd400, v153
	ds_write2_b32 v134, v100, v116 offset0:160 offset1:192
	v_add_u32_e32 v134, 0xd800, v153
	ds_write2_b32 v134, v101, v117 offset0:36 offset1:68
	ds_write2_b32 v134, v102, v118 offset0:168 offset1:200
	v_add_u32_e32 v134, 0xdc00, v153
	ds_write2_b32 v134, v103, v119 offset0:44 offset1:76
	v_add_u32_e32 v134, 0xe400, v153
	ds_write2_b32 v134, v104, v120 offset0:192 offset1:224
	v_add_u32_e32 v134, 0xe800, v153
	ds_write2_b32 v134, v105, v121 offset0:68 offset1:100
	ds_write2_b32 v134, v106, v122 offset0:200 offset1:232
	v_add_u32_e32 v134, 0xec00, v153
	ds_write2_b32 v134, v107, v123 offset0:76 offset1:108
	v_add_u32_e32 v134, 0xf600, v153
	ds_write2_b32 v134, v108, v124 offset0:96 offset1:128
	v_add_u32_e32 v134, 0xf800, v153
	ds_write2_b32 v134, v109, v125 offset0:100 offset1:132
	v_add_u32_e32 v134, 0xfa00, v153
	ds_write2_b32 v134, v110, v126 offset0:104 offset1:136
	v_add_u32_e32 v134, 0xfc00, v153
	ds_write2_b32 v134, v111, v127 offset0:108 offset1:140

.LBB0_962:
	v_cmp_lt_i32_e32 vcc, 9, v4
	s_and_saveexec_b64 s[2:3], vcc
	s_cbranch_execz .LBB0_1016
	s_waitcnt vmcnt(0)
	s_waitcnt lgkmcnt(0)
	v_mov_b32_e32 v254, 0x12000
	v_mov_b32_e32 v252, s97
	v_mov_b32_e32 v253, s96
	ds_write_b64 v254, v[252:253]
	s_waitcnt lgkmcnt(0)
	s_barrier
	s_mov_b64 s[4:5], exec
	v_readlane_b32 s6, v255, 5
	v_readlane_b32 s7, v255, 6
	s_and_b64 s[6:7], s[4:5], s[6:7]
	s_mov_b64 exec, s[6:7]
	s_cbranch_execz .LBB0_1015
	s_add_i32 s50, 0, 0x12000
	s_mov_b64 s[6:7], src_shared_base
	s_cmp_lg_u32 s50, -1
	s_cselect_b32 s6, s50, 0
	s_cselect_b32 s8, s7, 0
	s_add_i32 s51, 0, 0x12004
	s_cmp_lg_u32 s51, -1
	v_mov_b32_e32 v0, s6
	v_mov_b32_e32 v1, s8
	s_cselect_b32 s6, s51, 0
	s_cselect_b32 s7, s7, 0
	s_waitcnt vmcnt(0) expcnt(0) lgkmcnt(0)
	flat_load_dword v2, v[0:1] sc0 sc1
	s_waitcnt vmcnt(0)
	v_mov_b32_e32 v0, s6
	v_mov_b32_e32 v1, s7
	flat_load_dword v0, v[0:1] sc0 sc1
	s_waitcnt vmcnt(0) lgkmcnt(0)
	v_cmp_eq_u32_e32 vcc, 0, v2
	s_and_saveexec_b64 s[6:7], vcc
	s_cbranch_execz .LBB0_979
	s_add_u32 s8, s94, 0x1d11e200
	s_addc_u32 s9, s95, 0
	s_add_u32 s10, s94, 0x1d11e400
	s_addc_u32 s11, s95, 0
	s_add_u32 s12, s94, 0x1d11e500
	s_addc_u32 s13, s95, 0
	s_add_u32 s14, s94, 0x1d11e600
	s_addc_u32 s15, s95, 0
	s_add_u32 s16, s94, 0x1d11e700
	s_addc_u32 s17, s95, 0
	s_add_u32 s18, s94, 0x1d11e800
	s_addc_u32 s19, s95, 0
	s_add_u32 s20, s94, 0x1d11e900
	s_addc_u32 s21, s95, 0
	s_add_u32 s22, s94, 0x1d11ea00
	s_addc_u32 s23, s95, 0
	s_add_u32 s24, s94, 0x1d11eb00
	s_addc_u32 s25, s95, 0
	s_add_u32 s26, s94, 0x1d11ec00
	s_addc_u32 s27, s95, 0
	s_add_u32 s28, s94, 0x1d11ed00
	s_addc_u32 s29, s95, 0
	s_add_u32 s30, s94, 0x1d11ee00
	s_addc_u32 s31, s95, 0
	s_add_u32 s34, s94, 0x1d11ef00
	s_addc_u32 s35, s95, 0
	s_add_u32 s36, s94, 0x1d11f000
	s_addc_u32 s37, s95, 0
	s_add_u32 s38, s94, 0x1d11f100
	s_addc_u32 s39, s95, 0
	s_add_u32 s40, s94, 0x1d11f200
	s_addc_u32 s41, s95, 0
	s_add_u32 s42, s94, 0x1d11f300
	s_addc_u32 s43, s95, 0
	s_mov_b32 s52, 1
	v_mov_b32_e32 v16, 0
	s_branch .LBB0_967

.LBB0_1017:
	s_or_b64 exec, exec, s[0:1]
	v_readlane_b32 s0, v255, 4
	s_cmp_lt_i32 s0, 10
	s_cselect_b64 s[0:1], -1, 0
	v_cmp_lt_i32_e32 vcc, 9, v4
	s_and_b64 s[2:3], s[0:1], vcc
	s_and_saveexec_b64 s[0:1], s[2:3]
	s_cbranch_execz .LBB0_1083
	v_mov_b32_e32 v254, 0x12000
	ds_read_b64 v[252:253], v254
	s_waitcnt lgkmcnt(0)
	v_readfirstlane_b32 s97, v252
	v_readfirstlane_b32 s96, v253
	v_readlane_b32 s2, v255, 0
	s_cmpk_gt_u32 s2, 0x3ff
	v_readlane_b32 s3, v255, 1
	s_cbranch_scc1 .LBB0_1028
	v_lshlrev_b32_e32 v3, 4, v180
	s_add_u32 s2, s94, 0xcede000
	v_lshrrev_b32_e32 v1, 5, v180
	v_and_b32_e32 v3, 0x3c00, v3
	v_bfe_u32 v4, v180, 2, 2
	s_addc_u32 s3, s95, 0
	v_add_u32_e32 v152, 0, v3
	v_bfe_u32 v3, v180, 5, 1
	v_bitop3_b32 v1, v1, v4, 1 bitop3:0x6c
	s_add_u32 s20, s94, 0x14ede000
	v_lshlrev_b32_e32 v153, 4, v1
	v_bitop3_b32 v1, v3, v4, 2 bitop3:0x36
	s_addc_u32 s21, s95, 0
	v_and_b32_e32 v2, 31, v180
	v_lshrrev_b32_e32 v0, 4, v180
	v_lshlrev_b32_e32 v154, 4, v1
	v_lshlrev_b32_e32 v1, 6, v180
	v_and_b32_e32 v4, 64, v180
	s_add_u32 s22, s94, 0x1cffe000
	v_readlane_b32 s4, v255, 0
	v_xor_b32_e32 v0, v0, v180
	v_and_b32_e32 v155, 0xe7c0, v1
	v_and_b32_e32 v156, 0x17c0, v1
	v_lshrrev_b32_e32 v1, 3, v180
	v_lshlrev_b32_e32 v4, 2, v4
	v_lshlrev_b32_e32 v2, 2, v2
	v_lshrrev_b32_e32 v129, 2, v180
	s_addc_u32 s23, s95, 0
	s_and_b32 s24, s4, 7
	s_lshr_b32 s25, s33, 3
	s_lshr_b32 s26, s4, 3
	v_lshlrev_b32_e32 v0, 3, v0
	v_add3_u32 v2, 0, v4, v2
	s_movk_i32 s8, 0x840
	v_or_b32_e32 v1, 0x7b, v1
	v_readlane_b32 s5, v255, 1
	v_and_b32_e32 v128, 24, v0
	v_lshlrev_b32_e32 v0, 10, v129
	v_mov_b32_e32 v131, 0
	s_movk_i32 s4, 0x80
	v_mad_u32_u24 v157, v3, s8, v2
	v_and_b32_e32 v3, 0x380, v180
	v_mul_u32_u24_e32 v1, 0x210, v1
	s_add_u32 s28, s94, 0x8ca0000
	s_mov_b32 s5, 0
	v_cmp_gt_u32_e64 s[6:7], s4, v180
	v_cmp_eq_u32_e64 s[8:9], s4, v3
	s_movk_i32 s27, 0x210
	s_addc_u32 s29, s95, 0
	v_or_b32_e32 v158, 0x10000, v128
	s_mov_b32 s30, 0x20000
	v_or_b32_e32 v159, 0x20000, v128
	v_or_b32_e32 v160, 0x30000, v128
	v_lshlrev_b32_e32 v132, 1, v0
	v_mov_b32_e32 v133, v131
	v_lshlrev_b32_e32 v134, 1, v128
	v_mov_b32_e32 v135, v131
	v_add_u32_e32 v161, 0x1000, v152
	v_add_u32_e32 v162, 0x2000, v152
	v_add_u32_e32 v163, 0x3000, v152
	s_waitcnt lgkmcnt(0)
	s_mov_b64 s[10:11], 0x20000
	v_add_u32_e32 v164, 0x4000, v152
	v_add_u32_e32 v165, 0x5000, v152
	v_add_u32_e32 v166, 0x6000, v152
	v_add_u32_e32 v167, 0x7000, v152
	v_add_u32_e32 v168, 0x8000, v152
	v_add_u32_e32 v169, 0x9000, v152
	v_add_u32_e32 v170, 0xa000, v152
	s_mov_b64 s[12:13], 0x20040
	v_add_u32_e32 v171, 0xb000, v152
	s_mov_b64 s[14:15], 0x80
	v_add_u32_e32 v172, v2, v1
	s_mov_b32 s31, 0x40000
	s_mov_b32 s34, 0x60000
	s_branch .LBB0_1021

.LBB0_1021:
	s_lshr_b32 s4, s26, 3
	s_and_b32 s4, s4, 8
	s_lshl_b32 s16, s26, 3
	s_or_b32 s4, s4, s24
	s_and_b32 s35, s26, 1
	s_and_b32 s16, s16, 48
	s_or_b32 s36, s4, s16
	s_lshl_b32 s18, s35, 8
	s_lshl_b32 s16, s26, 4
	s_lshl_b32 s19, s36, 9
	v_or_b32_e32 v0, s18, v129
	s_and_b32 s37, s16, 0x380
	v_or_b32_e32 v0, s19, v0
	s_lshl_b32 s16, s37, 11
	s_lshl_b32 s4, s4, 21
	v_lshlrev_b32_e32 v1, 10, v0
	s_or_b32 s4, s4, s16
	s_add_u32 s16, s28, s4
	v_or_b32_e32 v0, v1, v128
	v_readfirstlane_b32 s4, v152
	v_lshlrev_b32_e32 v130, 1, v0
	s_mov_b32 m0, s4
	v_readfirstlane_b32 s4, v161
	v_add_lshl_u32 v0, v1, v158, 1
	s_waitcnt vmcnt(0)
	s_barrier
	s_nop 0
	s_mov_b32 m0, s4
	v_readfirstlane_b32 s4, v162
	s_addc_u32 s17, s29, 0
	v_add_lshl_u32 v2, v1, v159, 1
	s_nop 0
	s_mov_b32 m0, s4
	v_readfirstlane_b32 s4, v163
	v_add_lshl_u32 v4, v1, v160, 1
	v_lshl_add_u64 v[6:7], s[16:17], 0, v[132:133]
	s_nop 0
	s_mov_b32 m0, s4
	v_readfirstlane_b32 s4, v164
	v_lshl_add_u64 v[136:137], v[6:7], 0, v[134:135]
	s_nop 0
	s_mov_b32 m0, s4
	v_readfirstlane_b32 s4, v165
	v_lshl_add_u64 v[138:139], s[2:3], 0, v[130:131]
	v_mov_b32_e32 v1, v131
	v_lshl_add_u64 v[146:147], v[136:137], 0, s[10:11]
	s_nop 0
	s_mov_b32 m0, s4
	v_readfirstlane_b32 s4, v166
	v_lshl_add_u64 v[140:141], s[2:3], 0, v[0:1]
	v_mov_b32_e32 v3, v131
	s_nop 0
	v_lshl_add_u64 v[0:1], v[138:139], 0, 64
	s_mov_b32 m0, s4
	v_readfirstlane_b32 s4, v167
	v_lshl_add_u64 v[142:143], s[2:3], 0, v[2:3]
	v_mov_b32_e32 v5, v131
	s_nop 0
	v_lshl_add_u64 v[0:1], v[140:141], 0, 64
	s_mov_b32 m0, s4
	v_readfirstlane_b32 s4, v168
	v_lshl_add_u64 v[144:145], s[2:3], 0, v[4:5]
	s_nop 0
	v_lshl_add_u64 v[0:1], v[142:143], 0, 64
	s_mov_b32 m0, s4
	v_readfirstlane_b32 s4, v169
	s_nop 0
	v_lshl_add_u64 v[0:1], v[144:145], 0, 64
	s_mov_b32 m0, s4
	v_readfirstlane_b32 s4, v170
	s_nop 0
	v_lshl_add_u64 v[0:1], v[136:137], 0, 64
	s_mov_b32 m0, s4
	v_readfirstlane_b32 s4, v171
	s_nop 0
	v_lshl_add_u64 v[0:1], v[136:137], 0, s[12:13]
	s_mov_b32 m0, s4
	s_mov_b32 s16, s5
	s_nop 0
	s_mov_b32 s17, 2
	s_mov_b32 s38, s5
	v_mov_b32_e32 v0, 0
	v_mov_b32_e32 v1, v131
	v_mov_b32_e32 v2, v131
	v_mov_b32_e32 v4, v131
	v_mov_b32_e32 v6, v131
	v_mov_b32_e32 v7, v131
	v_mov_b32_e32 v8, v131
	v_mov_b32_e32 v9, v131
	v_mov_b32_e32 v10, v131
	v_mov_b32_e32 v11, v131
	v_mov_b32_e32 v12, v131
	v_mov_b32_e32 v13, v131
	v_mov_b32_e32 v14, v131
	v_mov_b32_e32 v15, v131
	v_mov_b32_e32 v16, 0
	v_mov_b32_e32 v17, v131
	v_mov_b32_e32 v18, v131
	v_mov_b32_e32 v19, v131
	v_mov_b32_e32 v20, v131
	v_mov_b32_e32 v21, v131
	v_mov_b32_e32 v22, v131
	v_mov_b32_e32 v23, v131
	v_mov_b32_e32 v24, v131
	v_mov_b32_e32 v25, v131
	v_mov_b32_e32 v26, v131
	v_mov_b32_e32 v27, v131
	v_mov_b32_e32 v28, v131
	v_mov_b32_e32 v29, v131
	v_mov_b32_e32 v30, v131
	v_mov_b32_e32 v31, v131
	v_mov_b32_e32 v32, 0
	v_mov_b32_e32 v33, v131
	v_mov_b32_e32 v34, v131
	v_mov_b32_e32 v35, v131
	v_mov_b32_e32 v36, v131
	v_mov_b32_e32 v37, v131
	v_mov_b32_e32 v38, v131
	v_mov_b32_e32 v39, v131
	v_mov_b32_e32 v40, v131
	v_mov_b32_e32 v41, v131
	v_mov_b32_e32 v42, v131
	v_mov_b32_e32 v43, v131
	v_mov_b32_e32 v44, v131
	v_mov_b32_e32 v45, v131
	v_mov_b32_e32 v46, v131
	v_mov_b32_e32 v47, v131
	v_mov_b32_e32 v48, 0
	v_mov_b32_e32 v49, v131
	v_mov_b32_e32 v50, v131
	v_mov_b32_e32 v51, v131
	v_mov_b32_e32 v52, v131
	v_mov_b32_e32 v53, v131
	v_mov_b32_e32 v54, v131
	v_mov_b32_e32 v55, v131
	v_mov_b32_e32 v56, v131
	v_mov_b32_e32 v57, v131
	v_mov_b32_e32 v58, v131
	v_mov_b32_e32 v59, v131
	v_mov_b32_e32 v60, v131
	v_mov_b32_e32 v61, v131
	v_mov_b32_e32 v62, v131
	v_mov_b32_e32 v63, v131
	v_mov_b32_e32 v64, 0
	v_mov_b32_e32 v65, v131
	v_mov_b32_e32 v66, v131
	v_mov_b32_e32 v67, v131
	v_mov_b32_e32 v68, v131
	v_mov_b32_e32 v69, v131
	v_mov_b32_e32 v70, v131
	v_mov_b32_e32 v71, v131
	v_mov_b32_e32 v72, v131
	v_mov_b32_e32 v73, v131
	v_mov_b32_e32 v74, v131
	v_mov_b32_e32 v75, v131
	v_mov_b32_e32 v76, v131
	v_mov_b32_e32 v77, v131
	v_mov_b32_e32 v78, v131
	v_mov_b32_e32 v79, v131
	v_mov_b32_e32 v80, 0
	v_mov_b32_e32 v81, v131
	v_mov_b32_e32 v82, v131
	v_mov_b32_e32 v83, v131
	v_mov_b32_e32 v84, v131
	v_mov_b32_e32 v85, v131
	v_mov_b32_e32 v86, v131
	v_mov_b32_e32 v87, v131
	v_mov_b32_e32 v88, v131
	v_mov_b32_e32 v89, v131
	v_mov_b32_e32 v90, v131
	v_mov_b32_e32 v91, v131
	v_mov_b32_e32 v92, v131
	v_mov_b32_e32 v93, v131
	v_mov_b32_e32 v94, v131
	v_mov_b32_e32 v95, v131
	v_mov_b32_e32 v96, 0
	v_mov_b32_e32 v97, v131
	v_mov_b32_e32 v98, v131
	v_mov_b32_e32 v99, v131
	v_mov_b32_e32 v100, v131
	v_mov_b32_e32 v101, v131
	v_mov_b32_e32 v102, v131
	v_mov_b32_e32 v103, v131
	v_mov_b32_e32 v104, v131
	v_mov_b32_e32 v105, v131
	v_mov_b32_e32 v106, v131
	v_mov_b32_e32 v107, v131
	v_mov_b32_e32 v108, v131
	v_mov_b32_e32 v109, v131
	v_mov_b32_e32 v110, v131
	v_mov_b32_e32 v111, v131
	v_mov_b32_e32 v112, 0
	v_mov_b32_e32 v113, v131
	v_mov_b32_e32 v114, v131
	v_mov_b32_e32 v115, v131
	v_mov_b32_e32 v116, v131
	v_mov_b32_e32 v117, v131
	v_mov_b32_e32 v118, v131
	v_mov_b32_e32 v119, v131
	v_mov_b32_e32 v120, v131
	v_mov_b32_e32 v121, v131
	v_mov_b32_e32 v122, v131
	v_mov_b32_e32 v123, v131
	v_mov_b32_e32 v124, v131
	v_mov_b32_e32 v125, v131
	v_mov_b32_e32 v126, v131
	v_mov_b32_e32 v127, v131
	s_mov_b64 s[54:55], 0x80
	v_lshrrev_b32_e32 v174, 6, v180
	v_lshlrev_b32_e32 v184, 11, v174
	v_and_b32_e32 v148, 63, v180
	v_readfirstlane_b32 s53, v184
	v_lshrrev_b32_e32 v149, 5, v148
	v_bfe_u32 v150, v148, 1, 3
	v_xor_b32_e32 v150, v149, v150
	v_and_b32_e32 v151, 31, v148
	v_lshlrev_b32_e32 v151, 7, v151
	v_lshrrev_b32_e32 v151, 3, v148
	v_lshlrev_b32_e32 v184, 4, v151
	v_add_u32_e32 v185, 0x80, v184
	v_and_b32_e32 v151, 7, v148
	v_lshrrev_b32_e32 v149, 4, v148
	v_xor_b32_e32 v149, v151, v149
	v_lshrrev_b32_e32 v151, 5, v148
	v_sub_u32_e32 v190, v149, v151
	v_xor_b32_e32 v149, 4, v149
	v_add_u32_e32 v151, 2, v151
	v_sub_u32_e32 v192, v149, v151
	v_lshlrev_b32_e32 v190, 4, v190
	v_ashrrev_i32_e32 v191, 31, v190
	v_lshlrev_b32_e32 v192, 4, v192
	v_ashrrev_i32_e32 v193, 31, v192
	ds_bpermute_b32 v246, v184, v136
	ds_bpermute_b32 v247, v184, v137
	ds_bpermute_b32 v248, v185, v136
	ds_bpermute_b32 v249, v185, v137
	ds_bpermute_b32 v250, v184, v146
	ds_bpermute_b32 v251, v184, v147
	ds_bpermute_b32 v252, v185, v146
	ds_bpermute_b32 v253, v185, v147
	s_waitcnt lgkmcnt(0)
	ds_bpermute_b32 v178, v184, v138
	ds_bpermute_b32 v179, v184, v139
	ds_bpermute_b32 v186, v185, v138
	ds_bpermute_b32 v187, v185, v139
	ds_bpermute_b32 v238, v184, v140
	ds_bpermute_b32 v239, v184, v141
	ds_bpermute_b32 v240, v185, v140
	ds_bpermute_b32 v241, v185, v141
	ds_bpermute_b32 v242, v184, v142
	ds_bpermute_b32 v243, v184, v143
	ds_bpermute_b32 v244, v185, v142
	ds_bpermute_b32 v245, v185, v143
	ds_bpermute_b32 v136, v184, v144
	ds_bpermute_b32 v137, v184, v145
	ds_bpermute_b32 v146, v185, v144
	ds_bpermute_b32 v147, v185, v145
	s_waitcnt lgkmcnt(0)
	v_and_b32_e32 v151, 31, v148
	v_lshlrev_b32_e32 v151, 7, v151
	v_lshrrev_b32_e32 v149, 1, v174
	v_lshl_add_u32 v138, v149, 14, v151
	v_and_b32_e32 v149, 1, v174
	v_lshl_add_u32 v142, v149, 13, v151
	v_add_u32_e32 v142, 0x10000, v142
	v_xor_b32_e32 v151, 6, v150
	v_lshl_add_u32 v141, v151, 4, v138
	v_lshl_add_u32 v145, v151, 4, v142
	v_xor_b32_e32 v151, 4, v150
	v_lshl_add_u32 v140, v151, 4, v138
	v_lshl_add_u32 v144, v151, 4, v142
	v_xor_b32_e32 v151, 2, v150
	v_lshl_add_u32 v139, v151, 4, v138
	v_lshl_add_u32 v143, v151, 4, v142
	v_xor_b32_e32 v151, 0, v150
	v_lshl_add_u32 v138, v151, 4, v138
	v_lshl_add_u32 v142, v151, 4, v142
	v_lshl_add_u64 v[178:179], v[178:179], 0, v[190:191]
	v_lshl_add_u64 v[186:187], v[186:187], 0, v[192:193]
	v_lshl_add_u64 v[238:239], v[238:239], 0, v[190:191]
	v_lshl_add_u64 v[240:241], v[240:241], 0, v[192:193]
	v_lshl_add_u64 v[242:243], v[242:243], 0, v[190:191]
	v_lshl_add_u64 v[244:245], v[244:245], 0, v[192:193]
	v_lshl_add_u64 v[136:137], v[136:137], 0, v[190:191]
	v_lshl_add_u64 v[146:147], v[146:147], 0, v[192:193]
	v_lshl_add_u64 v[246:247], v[246:247], 0, v[190:191]
	v_lshl_add_u64 v[248:249], v[248:249], 0, v[192:193]
	v_lshl_add_u64 v[250:251], v[250:251], 0, v[190:191]
	v_lshl_add_u64 v[252:253], v[252:253], 0, v[192:193]
	s_mov_b32 s58, s53
	s_add_i32 m0, s58, 0x0
	s_nop 0
	global_load_lds_dwordx4 v[178:179], off
	s_add_i32 m0, s58, 0x400
	v_lshl_add_u64 v[178:179], v[178:179], 0, s[54:55]
	global_load_lds_dwordx4 v[186:187], off
	s_add_i32 m0, s58, 0x2000
	v_lshl_add_u64 v[186:187], v[186:187], 0, s[54:55]
	global_load_lds_dwordx4 v[238:239], off
	s_add_i32 m0, s58, 0x2400
	v_lshl_add_u64 v[238:239], v[238:239], 0, s[54:55]
	global_load_lds_dwordx4 v[240:241], off
	s_add_i32 m0, s58, 0x4000
	v_lshl_add_u64 v[240:241], v[240:241], 0, s[54:55]
	global_load_lds_dwordx4 v[242:243], off
	s_add_i32 m0, s58, 0x4400
	v_lshl_add_u64 v[242:243], v[242:243], 0, s[54:55]
	global_load_lds_dwordx4 v[244:245], off
	s_add_i32 m0, s58, 0x6000
	v_lshl_add_u64 v[244:245], v[244:245], 0, s[54:55]
	global_load_lds_dwordx4 v[136:137], off
	s_add_i32 m0, s58, 0x6400
	v_lshl_add_u64 v[136:137], v[136:137], 0, s[54:55]
	global_load_lds_dwordx4 v[146:147], off
	v_lshl_add_u64 v[146:147], v[146:147], 0, s[54:55]
	s_add_i32 s58, s53, 0x10000
	s_add_i32 m0, s58, 0x0
	s_nop 0
	global_load_lds_dwordx4 v[246:247], off
	s_add_i32 m0, s58, 0x400
	v_lshl_add_u64 v[246:247], v[246:247], 0, s[54:55]
	global_load_lds_dwordx4 v[248:249], off
	s_add_i32 m0, s58, 0x2000
	v_lshl_add_u64 v[248:249], v[248:249], 0, s[54:55]
	global_load_lds_dwordx4 v[250:251], off
	s_add_i32 m0, s58, 0x2400
	v_lshl_add_u64 v[250:251], v[250:251], 0, s[54:55]
	global_load_lds_dwordx4 v[252:253], off
	v_lshl_add_u64 v[252:253], v[252:253], 0, s[54:55]
	s_mov_b32 s16, 0
	s_mov_b32 s17, 0

.Lg_ph9_noB:
	s_waitcnt lgkmcnt(3)
	v_mfma_f32_32x32x16_bf16 v[0:15], v[148:151], v[194:197], v[0:15]
	v_mfma_f32_32x32x16_bf16 v[16:31], v[148:151], v[198:201], v[16:31]
	ds_read_b128 v[148:151], v139
	s_waitcnt lgkmcnt(3)
	v_mfma_f32_32x32x16_bf16 v[32:47], v[174:177], v[194:197], v[32:47]
	v_mfma_f32_32x32x16_bf16 v[48:63], v[174:177], v[198:201], v[48:63]
	ds_read_b128 v[174:177], v139 offset:4096
	s_waitcnt lgkmcnt(3)
	v_mfma_f32_32x32x16_bf16 v[64:79], v[182:185], v[194:197], v[64:79]
	v_mfma_f32_32x32x16_bf16 v[80:95], v[182:185], v[198:201], v[80:95]
	ds_read_b128 v[182:185], v139 offset:8192
	s_waitcnt lgkmcnt(3)
	v_mfma_f32_32x32x16_bf16 v[96:111], v[190:193], v[194:197], v[96:111]
	v_mfma_f32_32x32x16_bf16 v[112:127], v[190:193], v[198:201], v[112:127]
	ds_read_b128 v[190:193], v139 offset:12288
	s_waitcnt lgkmcnt(3)
	v_mfma_f32_32x32x16_bf16 v[0:15], v[148:151], v[202:205], v[0:15]
	v_mfma_f32_32x32x16_bf16 v[16:31], v[148:151], v[206:209], v[16:31]
	ds_read_b128 v[148:151], v140
	s_waitcnt lgkmcnt(3)
	v_mfma_f32_32x32x16_bf16 v[32:47], v[174:177], v[202:205], v[32:47]
	v_mfma_f32_32x32x16_bf16 v[48:63], v[174:177], v[206:209], v[48:63]
	ds_read_b128 v[174:177], v140 offset:4096
	s_waitcnt lgkmcnt(3)
	v_mfma_f32_32x32x16_bf16 v[64:79], v[182:185], v[202:205], v[64:79]
	v_mfma_f32_32x32x16_bf16 v[80:95], v[182:185], v[206:209], v[80:95]
	ds_read_b128 v[182:185], v140 offset:8192
	s_waitcnt lgkmcnt(3)
	v_mfma_f32_32x32x16_bf16 v[96:111], v[190:193], v[202:205], v[96:111]
	v_mfma_f32_32x32x16_bf16 v[112:127], v[190:193], v[206:209], v[112:127]
	ds_read_b128 v[190:193], v140 offset:12288
	s_waitcnt lgkmcnt(3)
	v_mfma_f32_32x32x16_bf16 v[0:15], v[148:151], v[214:217], v[0:15]
	v_mfma_f32_32x32x16_bf16 v[16:31], v[148:151], v[226:229], v[16:31]
	ds_read_b128 v[148:151], v141
	s_waitcnt lgkmcnt(3)
	v_mfma_f32_32x32x16_bf16 v[32:47], v[174:177], v[214:217], v[32:47]
	v_mfma_f32_32x32x16_bf16 v[48:63], v[174:177], v[226:229], v[48:63]
	ds_read_b128 v[174:177], v141 offset:4096
	s_waitcnt lgkmcnt(3)
	v_mfma_f32_32x32x16_bf16 v[64:79], v[182:185], v[214:217], v[64:79]
	v_mfma_f32_32x32x16_bf16 v[80:95], v[182:185], v[226:229], v[80:95]
	ds_read_b128 v[182:185], v141 offset:8192
	s_waitcnt lgkmcnt(3)
	v_mfma_f32_32x32x16_bf16 v[96:111], v[190:193], v[214:217], v[96:111]
	v_mfma_f32_32x32x16_bf16 v[112:127], v[190:193], v[226:229], v[112:127]
	ds_read_b128 v[190:193], v141 offset:12288
	s_waitcnt lgkmcnt(3)
	v_mfma_f32_32x32x16_bf16 v[0:15], v[148:151], v[230:233], v[0:15]
	v_mfma_f32_32x32x16_bf16 v[16:31], v[148:151], v[234:237], v[16:31]
	s_waitcnt lgkmcnt(2)
	v_mfma_f32_32x32x16_bf16 v[32:47], v[174:177], v[230:233], v[32:47]
	v_mfma_f32_32x32x16_bf16 v[48:63], v[174:177], v[234:237], v[48:63]
	s_waitcnt lgkmcnt(1)
	v_mfma_f32_32x32x16_bf16 v[64:79], v[182:185], v[230:233], v[64:79]
	v_mfma_f32_32x32x16_bf16 v[80:95], v[182:185], v[234:237], v[80:95]
	s_waitcnt lgkmcnt(0)
	v_mfma_f32_32x32x16_bf16 v[96:111], v[190:193], v[230:233], v[96:111]
	v_mfma_f32_32x32x16_bf16 v[112:127], v[190:193], v[234:237], v[112:127]
	v_xor_b32_e32 v138, 0x8000, v138
	v_xor_b32_e32 v139, 0x8000, v139
	v_xor_b32_e32 v140, 0x8000, v140
	v_xor_b32_e32 v141, 0x8000, v141
	s_xor_b32 s17, s17, 0x8000
	s_add_i32 s16, s16, 1
	s_cmp_eq_u32 s16, 16
	s_cbranch_scc0 .Lg_ph9_top
	s_waitcnt vmcnt(0)
	v_mov_b32_e32 v146, v180
	v_add_u32_e32 v209, 0x400, v157
	v_add_u32_e32 v208, 0x1000, v157
	v_add_u32_e32 v207, 0x1400, v157
	v_add_u32_e32 v206, 0x2000, v157
	v_add_u32_e32 v200, 0x2400, v157
	v_add_u32_e32 v201, 0x3000, v157
	v_add_u32_e32 v202, 0x3200, v157
	v_add_u32_e32 v203, 0x3400, v157
	v_add_u32_e32 v204, 0x3600, v157
	v_add_u32_e32 v205, 0x4000, v157
	v_add_u32_e32 v197, 0x4400, v157
	v_add_u32_e32 v198, 0x4800, v157
	v_add_u32_e32 v199, 0x5000, v157
	v_add_u32_e32 v194, 0x5400, v157
	v_add_u32_e32 v195, 0x5800, v157
	v_add_u32_e32 v196, 0x6000, v157
	v_add_u32_e32 v187, 0x6400, v157
	v_add_u32_e32 v189, 0x6800, v157
	v_add_u32_e32 v190, 0x7200, v157
	v_add_u32_e32 v191, 0x7400, v157
	v_add_u32_e32 v192, 0x7600, v157
	v_add_u32_e32 v193, 0x7800, v157
	v_add_u32_e32 v186, 0x8400, v157
	v_add_u32_e32 v185, 0x8800, v157
	v_add_u32_e32 v184, 0x9400, v157
	v_add_u32_e32 v183, 0x9800, v157
	v_add_u32_e32 v181, 0xa400, v157
	v_add_u32_e32 v174, 0xa800, v157
	v_add_u32_e32 v175, 0xb400, v157
	v_add_u32_e32 v176, 0xb600, v157
	v_add_u32_e32 v177, 0xb800, v157
	v_add_u32_e32 v178, 0xba00, v157
	s_waitcnt vmcnt(0)
	s_barrier
	s_and_saveexec_b64 s[16:17], s[6:7]
	s_cbranch_execz .LBB0_1025
	v_add_u32_e32 v130, 0xc400, v157
	ds_write2_b32 v157, v0, v16 offset1:32
	ds_write2_b32 v157, v1, v17 offset0:132 offset1:164
	ds_write2_b32 v209, v2, v18 offset0:8 offset1:40
	ds_write2_b32 v209, v3, v19 offset0:140 offset1:172
	ds_write2_b32 v208, v4, v20 offset0:32 offset1:64
	ds_write2_b32 v208, v5, v21 offset0:164 offset1:196
	ds_write2_b32 v207, v6, v22 offset0:40 offset1:72
	ds_write2_b32 v207, v7, v23 offset0:172 offset1:204
	ds_write2_b32 v206, v8, v24 offset0:64 offset1:96
	ds_write2_b32 v206, v9, v25 offset0:196 offset1:228
	ds_write2_b32 v200, v10, v26 offset0:72 offset1:104
	ds_write2_b32 v200, v11, v27 offset0:204 offset1:236
	ds_write2_b32 v201, v12, v28 offset0:96 offset1:128
	ds_write2_b32 v202, v13, v29 offset0:100 offset1:132
	ds_write2_b32 v203, v14, v30 offset0:104 offset1:136
	ds_write2_b32 v204, v15, v31 offset0:108 offset1:140
	ds_write2_b32 v205, v32, v48 offset0:128 offset1:160
	ds_write2_b32 v197, v33, v49 offset0:4 offset1:36
	ds_write2_b32 v197, v34, v50 offset0:136 offset1:168
	ds_write2_b32 v198, v35, v51 offset0:12 offset1:44
	ds_write2_b32 v199, v36, v52 offset0:160 offset1:192
	ds_write2_b32 v194, v37, v53 offset0:36 offset1:68
	ds_write2_b32 v194, v38, v54 offset0:168 offset1:200
	ds_write2_b32 v195, v39, v55 offset0:44 offset1:76
	ds_write2_b32 v196, v40, v56 offset0:192 offset1:224
	ds_write2_b32 v187, v41, v57 offset0:68 offset1:100
	ds_write2_b32 v187, v42, v58 offset0:200 offset1:232
	ds_write2_b32 v189, v43, v59 offset0:76 offset1:108
	ds_write2_b32 v190, v44, v60 offset0:96 offset1:128
	ds_write2_b32 v191, v45, v61 offset0:100 offset1:132
	ds_write2_b32 v192, v46, v62 offset0:104 offset1:136
	ds_write2_b32 v193, v47, v63 offset0:108 offset1:140
	ds_write2_b32 v186, v64, v80 offset1:32
	ds_write2_b32 v186, v65, v81 offset0:132 offset1:164
	ds_write2_b32 v185, v66, v82 offset0:8 offset1:40
	ds_write2_b32 v185, v67, v83 offset0:140 offset1:172
	ds_write2_b32 v184, v68, v84 offset0:32 offset1:64
	ds_write2_b32 v184, v69, v85 offset0:164 offset1:196
	ds_write2_b32 v183, v70, v86 offset0:40 offset1:72
	ds_write2_b32 v183, v71, v87 offset0:172 offset1:204
	ds_write2_b32 v181, v72, v88 offset0:64 offset1:96
	ds_write2_b32 v181, v73, v89 offset0:196 offset1:228
	ds_write2_b32 v174, v74, v90 offset0:72 offset1:104
	ds_write2_b32 v174, v75, v91 offset0:204 offset1:236
	ds_write2_b32 v175, v76, v92 offset0:96 offset1:128
	ds_write2_b32 v176, v77, v93 offset0:100 offset1:132
	ds_write2_b32 v177, v78, v94 offset0:104 offset1:136
	ds_write2_b32 v178, v79, v95 offset0:108 offset1:140
	ds_write2_b32 v130, v96, v112 offset0:128 offset1:160
	v_add_u32_e32 v130, 0xc800, v157
	ds_write2_b32 v130, v97, v113 offset0:4 offset1:36
	ds_write2_b32 v130, v98, v114 offset0:136 offset1:168
	v_add_u32_e32 v130, 0xcc00, v157
	ds_write2_b32 v130, v99, v115 offset0:12 offset1:44
	v_add_u32_e32 v130, 0xd400, v157
	ds_write2_b32 v130, v100, v116 offset0:160 offset1:192
	v_add_u32_e32 v130, 0xd800, v157
	ds_write2_b32 v130, v101, v117 offset0:36 offset1:68
	ds_write2_b32 v130, v102, v118 offset0:168 offset1:200
	v_add_u32_e32 v130, 0xdc00, v157
	ds_write2_b32 v130, v103, v119 offset0:44 offset1:76
	v_add_u32_e32 v130, 0xe400, v157
	ds_write2_b32 v130, v104, v120 offset0:192 offset1:224
	v_add_u32_e32 v130, 0xe800, v157
	ds_write2_b32 v130, v105, v121 offset0:68 offset1:100
	ds_write2_b32 v130, v106, v122 offset0:200 offset1:232
	v_add_u32_e32 v130, 0xec00, v157
	ds_write2_b32 v130, v107, v123 offset0:76 offset1:108
	v_add_u32_e32 v130, 0xf600, v157
	ds_write2_b32 v130, v108, v124 offset0:96 offset1:128
	v_add_u32_e32 v130, 0xf800, v157
	ds_write2_b32 v130, v109, v125 offset0:100 offset1:132
	v_add_u32_e32 v130, 0xfa00, v157
	ds_write2_b32 v130, v110, v126 offset0:104 offset1:136
	v_add_u32_e32 v130, 0xfc00, v157
	ds_write2_b32 v130, v111, v127 offset0:108 offset1:140

.LBB0_1028:
	v_cmp_lt_i32_e32 vcc, 10, v4
	s_and_saveexec_b64 s[2:3], vcc
	s_cbranch_execz .LBB0_1082
	s_waitcnt vmcnt(0)
	s_waitcnt lgkmcnt(0)
	v_mov_b32_e32 v254, 0x12000
	v_mov_b32_e32 v252, s97
	v_mov_b32_e32 v253, s96
	ds_write_b64 v254, v[252:253]
	s_waitcnt lgkmcnt(0)
	s_barrier
	s_mov_b64 s[4:5], exec
	v_readlane_b32 s6, v255, 5
	v_readlane_b32 s7, v255, 6
	s_and_b64 s[6:7], s[4:5], s[6:7]
	s_mov_b64 exec, s[6:7]
	s_cbranch_execz .LBB0_1081
	s_add_i32 s50, 0, 0x12000
	s_mov_b64 s[6:7], src_shared_base
	s_cmp_lg_u32 s50, -1
	s_cselect_b32 s6, s50, 0
	s_cselect_b32 s8, s7, 0
	s_add_i32 s51, 0, 0x12004
	s_cmp_lg_u32 s51, -1
	v_mov_b32_e32 v0, s6
	v_mov_b32_e32 v1, s8
	s_cselect_b32 s6, s51, 0
	s_cselect_b32 s7, s7, 0
	s_waitcnt vmcnt(0) expcnt(0) lgkmcnt(0)
	flat_load_dword v2, v[0:1] sc0 sc1
	s_waitcnt vmcnt(0)
	v_mov_b32_e32 v0, s6
	v_mov_b32_e32 v1, s7
	flat_load_dword v0, v[0:1] sc0 sc1
	s_waitcnt vmcnt(0) lgkmcnt(0)
	v_cmp_eq_u32_e32 vcc, 0, v2
	s_and_saveexec_b64 s[6:7], vcc
	s_cbranch_execz .LBB0_1045
	s_add_u32 s8, s94, 0x1d11e200
	s_addc_u32 s9, s95, 0
	s_add_u32 s10, s94, 0x1d11e400
	s_addc_u32 s11, s95, 0
	s_add_u32 s12, s94, 0x1d11e500
	s_addc_u32 s13, s95, 0
	s_add_u32 s14, s94, 0x1d11e600
	s_addc_u32 s15, s95, 0
	s_add_u32 s16, s94, 0x1d11e700
	s_addc_u32 s17, s95, 0
	s_add_u32 s18, s94, 0x1d11e800
	s_addc_u32 s19, s95, 0
	s_add_u32 s20, s94, 0x1d11e900
	s_addc_u32 s21, s95, 0
	s_add_u32 s22, s94, 0x1d11ea00
	s_addc_u32 s23, s95, 0
	s_add_u32 s24, s94, 0x1d11eb00
	s_addc_u32 s25, s95, 0
	s_add_u32 s26, s94, 0x1d11ec00
	s_addc_u32 s27, s95, 0
	s_add_u32 s28, s94, 0x1d11ed00
	s_addc_u32 s29, s95, 0
	s_add_u32 s30, s94, 0x1d11ee00
	s_addc_u32 s31, s95, 0
	s_add_u32 s34, s94, 0x1d11ef00
	s_addc_u32 s35, s95, 0
	s_add_u32 s36, s94, 0x1d11f000
	s_addc_u32 s37, s95, 0
	s_add_u32 s38, s94, 0x1d11f100
	s_addc_u32 s39, s95, 0
	s_add_u32 s40, s94, 0x1d11f200
	s_addc_u32 s41, s95, 0
	s_add_u32 s42, s94, 0x1d11f300
	s_addc_u32 s43, s95, 0
	s_mov_b32 s52, 1
	v_mov_b32_e32 v16, 0
	s_branch .LBB0_1033

.LBB0_1169:
	s_or_b64 exec, exec, s[0:1]
	v_readlane_b32 s0, v255, 4
	s_cmp_lt_i32 s0, 12
	s_cselect_b64 s[0:1], -1, 0
	v_cmp_lt_i32_e32 vcc, 11, v4
	s_and_b64 s[2:3], s[0:1], vcc
	s_and_saveexec_b64 s[0:1], s[2:3]
	s_cbranch_execz .LBB0_1245
	v_mov_b32_e32 v254, 0x12000
	ds_read_b64 v[252:253], v254
	s_waitcnt lgkmcnt(0)
	v_readfirstlane_b32 s97, v252
	v_readfirstlane_b32 s96, v253
	v_readlane_b32 s2, v255, 0
	s_cmpk_gt_u32 s2, 0x5ff
	v_readlane_b32 s3, v255, 1
	s_cbranch_scc1 .LBB0_1190
	v_lshrrev_b32_e32 v3, 4, v180
	v_xor_b32_e32 v3, v3, v180
	s_add_u32 s2, s94, 0x12ede000
	v_lshlrev_b32_e32 v3, 3, v3
	s_addc_u32 s3, s95, 0
	v_and_b32_e32 v128, 24, v3
	v_lshlrev_b32_e32 v3, 4, v180
	s_add_u32 s28, s94, 0x4a0000
	v_readlane_b32 s4, v255, 0
	v_lshrrev_b32_e32 v1, 5, v180
	v_and_b32_e32 v3, 0x3c00, v3
	v_bfe_u32 v4, v180, 2, 2
	s_addc_u32 s29, s95, 0
	s_lshr_b32 s31, s4, 3
	s_lshl_b32 s4, s4, 3
	v_add_u32_e32 v160, 0, v3
	v_bfe_u32 v3, v180, 5, 1
	v_bitop3_b32 v1, v1, v4, 1 bitop3:0x6c
	s_lshr_b32 s30, s33, 3
	s_and_b32 s34, s4, 56
	v_lshlrev_b32_e32 v161, 4, v1
	v_bitop3_b32 v1, v3, v4, 2 bitop3:0x36
	v_lshlrev_b32_e32 v0, 8, v180
	v_and_b32_e32 v2, 31, v180
	v_lshlrev_b32_e32 v162, 4, v1
	v_lshlrev_b32_e32 v1, 6, v180
	v_and_b32_e32 v4, 64, v180
	s_add_u32 s36, s94, 0xcede000
	v_and_b32_e32 v129, 0x3fc00, v0
	v_lshrrev_b32_e32 v0, 2, v180
	v_and_b32_e32 v163, 0xe7c0, v1
	v_and_b32_e32 v164, 0x17c0, v1
	v_lshrrev_b32_e32 v1, 3, v180
	v_lshlrev_b32_e32 v4, 2, v4
	v_lshlrev_b32_e32 v2, 2, v2
	s_addc_u32 s37, s95, 0
	v_readlane_b32 s5, v255, 1
	v_lshlrev_b32_e32 v0, 10, v0
	v_add3_u32 v165, 0, v4, v2
	s_movk_i32 s4, 0x80
	s_movk_i32 s8, 0x840
	v_and_b32_e32 v2, 0x380, v180
	v_or_b32_e32 v1, 0x7b, v1
	s_add_u32 s38, s94, 0xeede000
	v_mov_b32_e32 v131, 0
	s_mov_b32 s5, 0
	v_cmp_gt_u32_e64 s[6:7], s4, v180
	v_mad_u32_u24 v166, v3, s8, v165
	v_cmp_eq_u32_e64 s[8:9], s4, v2
	s_movk_i32 s35, 0x210
	v_mul_u32_u24_e32 v167, 0x210, v1
	s_addc_u32 s39, s95, 0
	s_mov_b32 s40, 0x20000
	s_mov_b32 s41, 0x40000
	s_mov_b32 s42, 0x60000
	v_lshlrev_b32_e32 v132, 1, v128
	v_add_u32_e32 v168, 0x1000, v160
	v_add_u32_e32 v169, 0x2000, v160
	v_add_u32_e32 v170, 0x3000, v160
	s_waitcnt lgkmcnt(0)
	s_mov_b64 s[10:11], 0x20000
	v_add_u32_e32 v171, 0x4000, v160
	v_add_u32_e32 v172, 0x5000, v160
	v_add_u32_e32 v173, 0x6000, v160
	v_add_u32_e32 v174, 0x7000, v160
	v_add_u32_e32 v175, 0x8000, v160
	v_add_u32_e32 v176, 0x9000, v160
	v_add_u32_e32 v177, 0xa000, v160
	s_mov_b64 s[12:13], 0x20040
	v_add_u32_e32 v178, 0xb000, v160
	s_mov_b64 s[14:15], 0x80
	s_mov_b64 s[16:17], 0x200000
	s_mov_b64 s[18:19], 0x400000
	s_mov_b64 s[20:21], 0x200040
	s_mov_b64 s[22:23], 0x400040
	v_lshlrev_b32_e32 v134, 1, v0
	s_branch .LBB0_1174

.LBB0_1174:
	s_and_b32 s4, s31, 0xff
	s_mulk_i32 s4, 0xab
	s_lshr_b32 s4, s4, 12
	s_add_i32 s24, s34, s4
	s_lshl_b32 s44, s24, 18
	v_or_b32_e32 v0, s44, v129
	v_or_b32_e32 v1, v0, v128
	s_mul_i32 s4, s4, 24
	v_lshlrev_b32_e32 v130, 1, v1
	v_add_lshl_u32 v1, v0, v128, 1
	s_sub_i32 s4, s31, s4
	v_add_u32_e32 v0, 0x20000, v1
	v_add_u32_e32 v2, 0x40000, v1
	v_add_u32_e32 v4, 0x60000, v1
	v_mov_b32_e32 v1, v131
	v_mov_b32_e32 v3, v131
	v_mov_b32_e32 v5, v131
	s_and_b32 s43, s4, 0xff
	v_lshl_add_u64 v[136:137], s[2:3], 0, v[130:131]
	v_lshl_add_u64 v[138:139], s[2:3], 0, v[0:1]
	v_lshl_add_u64 v[140:141], s[2:3], 0, v[2:3]
	v_lshl_add_u64 v[142:143], s[2:3], 0, v[4:5]
	s_cmp_gt_u32 s43, 15
	v_lshl_add_u64 v[150:151], v[136:137], 0, 64
	s_mov_b64 s[24:25], -1
	v_lshl_add_u64 v[148:149], v[138:139], 0, 64
	v_lshl_add_u64 v[146:147], v[140:141], 0, 64
	v_lshl_add_u64 v[144:145], v[142:143], 0, 64
	s_cbranch_scc0 .LBB0_1182
	s_lshl_b32 s4, s43, 7
	s_add_i32 s24, s4, 0xfffff800
	s_mov_b32 s25, s5
	v_readfirstlane_b32 s4, v160
	s_lshl_b64 s[26:27], s[24:25], 11
	s_mov_b32 m0, s4
	v_readfirstlane_b32 s4, v168
	s_add_u32 s26, s28, s26
	s_waitcnt vmcnt(0)
	s_barrier
	s_nop 0
	s_mov_b32 m0, s4
	v_readfirstlane_b32 s4, v169
	s_addc_u32 s27, s29, s27
	v_mov_b32_e32 v135, v131
	s_nop 0
	s_mov_b32 m0, s4
	v_readfirstlane_b32 s4, v170
	v_lshl_add_u64 v[0:1], s[26:27], 0, v[134:135]
	v_mov_b32_e32 v133, v131
	s_nop 0
	s_mov_b32 m0, s4
	v_readfirstlane_b32 s4, v171
	v_lshl_add_u64 v[152:153], v[0:1], 0, v[132:133]
	s_nop 0
	s_mov_b32 m0, s4
	v_readfirstlane_b32 s4, v172
	v_lshl_add_u64 v[154:155], v[152:153], 0, s[10:11]
	s_nop 0
	s_mov_b32 m0, s4
	v_readfirstlane_b32 s4, v173
	s_nop 0
	s_mov_b32 m0, s4
	v_readfirstlane_b32 s4, v174
	s_nop 0
	s_mov_b32 m0, s4
	v_readfirstlane_b32 s4, v175
	s_nop 0
	s_mov_b32 m0, s4
	v_readfirstlane_b32 s4, v176
	s_nop 0
	s_mov_b32 m0, s4
	v_readfirstlane_b32 s4, v177
	s_nop 0
	v_lshl_add_u64 v[0:1], v[152:153], 0, 64
	s_mov_b32 m0, s4
	v_readfirstlane_b32 s4, v178
	s_nop 0
	v_lshl_add_u64 v[0:1], v[152:153], 0, s[12:13]
	s_mov_b32 m0, s4
	s_mov_b32 s27, 2
	s_nop 0
	v_mov_b32_e32 v0, 0
	s_mov_b32 s26, 0
	s_mov_b32 s45, 0
	v_mov_b32_e32 v1, v0
	v_mov_b32_e32 v2, v0
	v_mov_b32_e32 v3, v0
	v_mov_b32_e32 v4, v0
	v_mov_b32_e32 v5, v0
	v_mov_b32_e32 v6, v0
	v_mov_b32_e32 v7, v0
	v_mov_b32_e32 v8, v0
	v_mov_b32_e32 v9, v0
	v_mov_b32_e32 v10, v0
	v_mov_b32_e32 v11, v0
	v_mov_b32_e32 v12, v0
	v_mov_b32_e32 v13, v0
	v_mov_b32_e32 v14, v0
	v_mov_b32_e32 v15, v0
	v_mov_b32_e32 v48, v0
	v_mov_b32_e32 v49, v0
	v_mov_b32_e32 v50, v0
	v_mov_b32_e32 v51, v0
	v_mov_b32_e32 v52, v0
	v_mov_b32_e32 v53, v0
	v_mov_b32_e32 v54, v0
	v_mov_b32_e32 v55, v0
	v_mov_b32_e32 v56, v0
	v_mov_b32_e32 v57, v0
	v_mov_b32_e32 v58, v0
	v_mov_b32_e32 v59, v0
	v_mov_b32_e32 v60, v0
	v_mov_b32_e32 v61, v0
	v_mov_b32_e32 v62, v0
	v_mov_b32_e32 v63, v0
	v_mov_b32_e32 v16, v0
	v_mov_b32_e32 v17, v0
	v_mov_b32_e32 v18, v0
	v_mov_b32_e32 v19, v0
	v_mov_b32_e32 v20, v0
	v_mov_b32_e32 v21, v0
	v_mov_b32_e32 v22, v0
	v_mov_b32_e32 v23, v0
	v_mov_b32_e32 v24, v0
	v_mov_b32_e32 v25, v0
	v_mov_b32_e32 v26, v0
	v_mov_b32_e32 v27, v0
	v_mov_b32_e32 v28, v0
	v_mov_b32_e32 v29, v0
	v_mov_b32_e32 v30, v0
	v_mov_b32_e32 v31, v0
	v_mov_b32_e32 v64, v0
	v_mov_b32_e32 v65, v0
	v_mov_b32_e32 v66, v0
	v_mov_b32_e32 v67, v0
	v_mov_b32_e32 v68, v0
	v_mov_b32_e32 v69, v0
	v_mov_b32_e32 v70, v0
	v_mov_b32_e32 v71, v0
	v_mov_b32_e32 v72, v0
	v_mov_b32_e32 v73, v0
	v_mov_b32_e32 v74, v0
	v_mov_b32_e32 v75, v0
	v_mov_b32_e32 v76, v0
	v_mov_b32_e32 v77, v0
	v_mov_b32_e32 v78, v0
	v_mov_b32_e32 v79, v0
	v_mov_b32_e32 v32, v0
	v_mov_b32_e32 v33, v0
	v_mov_b32_e32 v34, v0
	v_mov_b32_e32 v35, v0
	v_mov_b32_e32 v36, v0
	v_mov_b32_e32 v37, v0
	v_mov_b32_e32 v38, v0
	v_mov_b32_e32 v39, v0
	v_mov_b32_e32 v40, v0
	v_mov_b32_e32 v41, v0
	v_mov_b32_e32 v42, v0
	v_mov_b32_e32 v43, v0
	v_mov_b32_e32 v44, v0
	v_mov_b32_e32 v45, v0
	v_mov_b32_e32 v46, v0
	v_mov_b32_e32 v47, v0
	v_mov_b32_e32 v112, v0
	v_mov_b32_e32 v113, v0
	v_mov_b32_e32 v114, v0
	v_mov_b32_e32 v115, v0
	v_mov_b32_e32 v116, v0
	v_mov_b32_e32 v117, v0
	v_mov_b32_e32 v118, v0
	v_mov_b32_e32 v119, v0
	v_mov_b32_e32 v120, v0
	v_mov_b32_e32 v121, v0
	v_mov_b32_e32 v122, v0
	v_mov_b32_e32 v123, v0
	v_mov_b32_e32 v124, v0
	v_mov_b32_e32 v125, v0
	v_mov_b32_e32 v126, v0
	v_mov_b32_e32 v127, v0
	v_mov_b32_e32 v80, v0
	v_mov_b32_e32 v81, v0
	v_mov_b32_e32 v82, v0
	v_mov_b32_e32 v83, v0
	v_mov_b32_e32 v84, v0
	v_mov_b32_e32 v85, v0
	v_mov_b32_e32 v86, v0
	v_mov_b32_e32 v87, v0
	v_mov_b32_e32 v88, v0
	v_mov_b32_e32 v89, v0
	v_mov_b32_e32 v90, v0
	v_mov_b32_e32 v91, v0
	v_mov_b32_e32 v92, v0
	v_mov_b32_e32 v93, v0
	v_mov_b32_e32 v94, v0
	v_mov_b32_e32 v95, v0
	v_mov_b32_e32 v96, v0
	v_mov_b32_e32 v97, v0
	v_mov_b32_e32 v98, v0
	v_mov_b32_e32 v99, v0
	v_mov_b32_e32 v100, v0
	v_mov_b32_e32 v101, v0
	v_mov_b32_e32 v102, v0
	v_mov_b32_e32 v103, v0
	v_mov_b32_e32 v104, v0
	v_mov_b32_e32 v105, v0
	v_mov_b32_e32 v106, v0
	v_mov_b32_e32 v107, v0
	v_mov_b32_e32 v108, v0
	v_mov_b32_e32 v109, v0
	v_mov_b32_e32 v110, v0
	v_mov_b32_e32 v111, v0
	s_mov_b64 s[54:55], 0x80
	v_lshrrev_b32_e32 v182, 6, v180
	v_lshlrev_b32_e32 v192, 11, v182
	v_and_b32_e32 v156, 63, v180
	v_readfirstlane_b32 s53, v192
	v_lshrrev_b32_e32 v157, 5, v156
	v_bfe_u32 v158, v156, 1, 3
	v_xor_b32_e32 v158, v157, v158
	v_and_b32_e32 v159, 31, v156
	v_lshlrev_b32_e32 v159, 7, v159
	v_lshrrev_b32_e32 v159, 3, v156
	v_lshlrev_b32_e32 v192, 4, v159
	v_add_u32_e32 v193, 0x80, v192
	v_and_b32_e32 v159, 7, v156
	v_lshrrev_b32_e32 v157, 4, v156
	v_xor_b32_e32 v157, v159, v157
	v_lshrrev_b32_e32 v159, 5, v156
	v_sub_u32_e32 v194, v157, v159
	v_xor_b32_e32 v157, 4, v157
	v_add_u32_e32 v159, 2, v159
	v_sub_u32_e32 v196, v157, v159
	v_lshlrev_b32_e32 v194, 4, v194
	v_ashrrev_i32_e32 v195, 31, v194
	v_lshlrev_b32_e32 v196, 4, v196
	v_ashrrev_i32_e32 v197, 31, v196
	ds_bpermute_b32 v244, v192, v152
	ds_bpermute_b32 v245, v192, v153
	ds_bpermute_b32 v246, v193, v152
	ds_bpermute_b32 v247, v193, v153
	ds_bpermute_b32 v248, v192, v154
	ds_bpermute_b32 v249, v192, v155
	ds_bpermute_b32 v250, v193, v154
	ds_bpermute_b32 v251, v193, v155
	s_waitcnt lgkmcnt(0)
	ds_bpermute_b32 v186, v192, v136
	ds_bpermute_b32 v187, v192, v137
	ds_bpermute_b32 v234, v193, v136
	ds_bpermute_b32 v235, v193, v137
	ds_bpermute_b32 v236, v192, v138
	ds_bpermute_b32 v237, v192, v139
	ds_bpermute_b32 v238, v193, v138
	ds_bpermute_b32 v239, v193, v139
	ds_bpermute_b32 v240, v192, v140
	ds_bpermute_b32 v241, v192, v141
	ds_bpermute_b32 v242, v193, v140
	ds_bpermute_b32 v243, v193, v141
	ds_bpermute_b32 v152, v192, v142
	ds_bpermute_b32 v153, v192, v143
	ds_bpermute_b32 v154, v193, v142
	ds_bpermute_b32 v155, v193, v143
	s_waitcnt lgkmcnt(0)
	v_and_b32_e32 v159, 31, v156
	v_lshlrev_b32_e32 v159, 7, v159
	v_lshrrev_b32_e32 v157, 1, v182
	v_lshl_add_u32 v136, v157, 14, v159
	v_and_b32_e32 v157, 1, v182
	v_lshl_add_u32 v140, v157, 13, v159
	v_add_u32_e32 v140, 0x10000, v140
	v_xor_b32_e32 v159, 6, v158
	v_lshl_add_u32 v139, v159, 4, v136
	v_lshl_add_u32 v143, v159, 4, v140
	v_xor_b32_e32 v159, 4, v158
	v_lshl_add_u32 v138, v159, 4, v136
	v_lshl_add_u32 v142, v159, 4, v140
	v_xor_b32_e32 v159, 2, v158
	v_lshl_add_u32 v137, v159, 4, v136
	v_lshl_add_u32 v141, v159, 4, v140
	v_xor_b32_e32 v159, 0, v158
	v_lshl_add_u32 v136, v159, 4, v136
	v_lshl_add_u32 v140, v159, 4, v140
	v_lshl_add_u64 v[186:187], v[186:187], 0, v[194:195]
	v_lshl_add_u64 v[234:235], v[234:235], 0, v[196:197]
	v_lshl_add_u64 v[236:237], v[236:237], 0, v[194:195]
	v_lshl_add_u64 v[238:239], v[238:239], 0, v[196:197]
	v_lshl_add_u64 v[240:241], v[240:241], 0, v[194:195]
	v_lshl_add_u64 v[242:243], v[242:243], 0, v[196:197]
	v_lshl_add_u64 v[152:153], v[152:153], 0, v[194:195]
	v_lshl_add_u64 v[154:155], v[154:155], 0, v[196:197]
	v_lshl_add_u64 v[244:245], v[244:245], 0, v[194:195]
	v_lshl_add_u64 v[246:247], v[246:247], 0, v[196:197]
	v_lshl_add_u64 v[248:249], v[248:249], 0, v[194:195]
	v_lshl_add_u64 v[250:251], v[250:251], 0, v[196:197]
	s_mov_b32 s58, s53
	s_add_i32 m0, s58, 0x0
	s_nop 0
	global_load_lds_dwordx4 v[186:187], off
	s_add_i32 m0, s58, 0x400
	v_lshl_add_u64 v[186:187], v[186:187], 0, s[54:55]
	global_load_lds_dwordx4 v[234:235], off
	s_add_i32 m0, s58, 0x2000
	v_lshl_add_u64 v[234:235], v[234:235], 0, s[54:55]
	global_load_lds_dwordx4 v[236:237], off
	s_add_i32 m0, s58, 0x2400
	v_lshl_add_u64 v[236:237], v[236:237], 0, s[54:55]
	global_load_lds_dwordx4 v[238:239], off
	s_add_i32 m0, s58, 0x4000
	v_lshl_add_u64 v[238:239], v[238:239], 0, s[54:55]
	global_load_lds_dwordx4 v[240:241], off
	s_add_i32 m0, s58, 0x4400
	v_lshl_add_u64 v[240:241], v[240:241], 0, s[54:55]
	global_load_lds_dwordx4 v[242:243], off
	s_add_i32 m0, s58, 0x6000
	v_lshl_add_u64 v[242:243], v[242:243], 0, s[54:55]
	global_load_lds_dwordx4 v[152:153], off
	s_add_i32 m0, s58, 0x6400
	v_lshl_add_u64 v[152:153], v[152:153], 0, s[54:55]
	global_load_lds_dwordx4 v[154:155], off
	v_lshl_add_u64 v[154:155], v[154:155], 0, s[54:55]
	s_add_i32 s58, s53, 0x10000
	s_add_i32 m0, s58, 0x0
	s_nop 0
	global_load_lds_dwordx4 v[244:245], off
	s_add_i32 m0, s58, 0x400
	v_lshl_add_u64 v[244:245], v[244:245], 0, s[54:55]
	global_load_lds_dwordx4 v[246:247], off
	s_add_i32 m0, s58, 0x2000
	v_lshl_add_u64 v[246:247], v[246:247], 0, s[54:55]
	global_load_lds_dwordx4 v[248:249], off
	s_add_i32 m0, s58, 0x2400
	v_lshl_add_u64 v[248:249], v[248:249], 0, s[54:55]
	global_load_lds_dwordx4 v[250:251], off
	v_lshl_add_u64 v[250:251], v[250:251], 0, s[54:55]
	s_mov_b32 s26, 0
	s_mov_b32 s27, 0

.Lg_ph11a_noB:
	s_waitcnt lgkmcnt(3)
	v_mfma_f32_32x32x16_bf16 v[0:15], v[156:159], v[198:201], v[0:15]
	v_mfma_f32_32x32x16_bf16 v[48:63], v[156:159], v[202:205], v[48:63]
	ds_read_b128 v[156:159], v137
	s_waitcnt lgkmcnt(3)
	v_mfma_f32_32x32x16_bf16 v[16:31], v[182:185], v[198:201], v[16:31]
	v_mfma_f32_32x32x16_bf16 v[64:79], v[182:185], v[202:205], v[64:79]
	ds_read_b128 v[182:185], v137 offset:4096
	s_waitcnt lgkmcnt(3)
	v_mfma_f32_32x32x16_bf16 v[32:47], v[190:193], v[198:201], v[32:47]
	v_mfma_f32_32x32x16_bf16 v[112:127], v[190:193], v[202:205], v[112:127]
	ds_read_b128 v[190:193], v137 offset:8192
	s_waitcnt lgkmcnt(3)
	v_mfma_f32_32x32x16_bf16 v[80:95], v[194:197], v[198:201], v[80:95]
	v_mfma_f32_32x32x16_bf16 v[96:111], v[194:197], v[202:205], v[96:111]
	ds_read_b128 v[194:197], v137 offset:12288
	s_waitcnt lgkmcnt(3)
	v_mfma_f32_32x32x16_bf16 v[0:15], v[156:159], v[206:209], v[0:15]
	v_mfma_f32_32x32x16_bf16 v[48:63], v[156:159], v[214:217], v[48:63]
	ds_read_b128 v[156:159], v138
	s_waitcnt lgkmcnt(3)
	v_mfma_f32_32x32x16_bf16 v[16:31], v[182:185], v[206:209], v[16:31]
	v_mfma_f32_32x32x16_bf16 v[64:79], v[182:185], v[214:217], v[64:79]
	ds_read_b128 v[182:185], v138 offset:4096
	s_waitcnt lgkmcnt(3)
	v_mfma_f32_32x32x16_bf16 v[32:47], v[190:193], v[206:209], v[32:47]
	v_mfma_f32_32x32x16_bf16 v[112:127], v[190:193], v[214:217], v[112:127]
	ds_read_b128 v[190:193], v138 offset:8192
	s_waitcnt lgkmcnt(3)
	v_mfma_f32_32x32x16_bf16 v[80:95], v[194:197], v[206:209], v[80:95]
	v_mfma_f32_32x32x16_bf16 v[96:111], v[194:197], v[214:217], v[96:111]
	ds_read_b128 v[194:197], v138 offset:12288
	s_waitcnt lgkmcnt(3)
	v_mfma_f32_32x32x16_bf16 v[0:15], v[156:159], v[218:221], v[0:15]
	v_mfma_f32_32x32x16_bf16 v[48:63], v[156:159], v[222:225], v[48:63]
	ds_read_b128 v[156:159], v139
	s_waitcnt lgkmcnt(3)
	v_mfma_f32_32x32x16_bf16 v[16:31], v[182:185], v[218:221], v[16:31]
	v_mfma_f32_32x32x16_bf16 v[64:79], v[182:185], v[222:225], v[64:79]
	ds_read_b128 v[182:185], v139 offset:4096
	s_waitcnt lgkmcnt(3)
	v_mfma_f32_32x32x16_bf16 v[32:47], v[190:193], v[218:221], v[32:47]
	v_mfma_f32_32x32x16_bf16 v[112:127], v[190:193], v[222:225], v[112:127]
	ds_read_b128 v[190:193], v139 offset:8192
	s_waitcnt lgkmcnt(3)
	v_mfma_f32_32x32x16_bf16 v[80:95], v[194:197], v[218:221], v[80:95]
	v_mfma_f32_32x32x16_bf16 v[96:111], v[194:197], v[222:225], v[96:111]
	ds_read_b128 v[194:197], v139 offset:12288
	s_waitcnt lgkmcnt(3)
	v_mfma_f32_32x32x16_bf16 v[0:15], v[156:159], v[226:229], v[0:15]
	v_mfma_f32_32x32x16_bf16 v[48:63], v[156:159], v[230:233], v[48:63]
	s_waitcnt lgkmcnt(2)
	v_mfma_f32_32x32x16_bf16 v[16:31], v[182:185], v[226:229], v[16:31]
	v_mfma_f32_32x32x16_bf16 v[64:79], v[182:185], v[230:233], v[64:79]
	s_waitcnt lgkmcnt(1)
	v_mfma_f32_32x32x16_bf16 v[32:47], v[190:193], v[226:229], v[32:47]
	v_mfma_f32_32x32x16_bf16 v[112:127], v[190:193], v[230:233], v[112:127]
	s_waitcnt lgkmcnt(0)
	v_mfma_f32_32x32x16_bf16 v[80:95], v[194:197], v[226:229], v[80:95]
	v_mfma_f32_32x32x16_bf16 v[96:111], v[194:197], v[230:233], v[96:111]
	v_xor_b32_e32 v136, 0x8000, v136
	v_xor_b32_e32 v137, 0x8000, v137
	v_xor_b32_e32 v138, 0x8000, v138
	v_xor_b32_e32 v139, 0x8000, v139
	s_xor_b32 s27, s27, 0x8000
	s_add_i32 s26, s26, 1
	s_cmp_eq_u32 s26, 16
	s_cbranch_scc0 .Lg_ph11a_top
	s_waitcnt vmcnt(0)
	v_mov_b32_e32 v130, v180
	s_waitcnt vmcnt(0)
	s_barrier
	s_and_saveexec_b64 s[26:27], s[6:7]
	s_cbranch_execz .LBB0_1179
	v_add_u32_e32 v133, 0x400, v166
	ds_write2_b32 v166, v0, v48 offset1:32
	ds_write2_b32 v166, v1, v49 offset0:132 offset1:164
	ds_write2_b32 v133, v2, v50 offset0:8 offset1:40
	ds_write2_b32 v133, v3, v51 offset0:140 offset1:172
	v_add_u32_e32 v133, 0x1000, v166
	ds_write2_b32 v133, v4, v52 offset0:32 offset1:64
	ds_write2_b32 v133, v5, v53 offset0:164 offset1:196
	v_add_u32_e32 v133, 0x1400, v166
	ds_write2_b32 v133, v6, v54 offset0:40 offset1:72
	ds_write2_b32 v133, v7, v55 offset0:172 offset1:204
	v_add_u32_e32 v133, 0x2000, v166
	ds_write2_b32 v133, v8, v56 offset0:64 offset1:96
	ds_write2_b32 v133, v9, v57 offset0:196 offset1:228
	v_add_u32_e32 v133, 0x2400, v166
	ds_write2_b32 v133, v10, v58 offset0:72 offset1:104
	ds_write2_b32 v133, v11, v59 offset0:204 offset1:236
	v_add_u32_e32 v133, 0x3000, v166
	ds_write2_b32 v133, v12, v60 offset0:96 offset1:128
	v_add_u32_e32 v133, 0x3200, v166
	ds_write2_b32 v133, v13, v61 offset0:100 offset1:132
	v_add_u32_e32 v133, 0x3400, v166
	ds_write2_b32 v133, v14, v62 offset0:104 offset1:136
	v_add_u32_e32 v133, 0x3600, v166
	ds_write2_b32 v133, v15, v63 offset0:108 offset1:140
	v_add_u32_e32 v133, 0x4000, v166
	ds_write2_b32 v133, v16, v64 offset0:128 offset1:160
	v_add_u32_e32 v133, 0x4400, v166
	ds_write2_b32 v133, v17, v65 offset0:4 offset1:36
	ds_write2_b32 v133, v18, v66 offset0:136 offset1:168
	v_add_u32_e32 v133, 0x4800, v166
	ds_write2_b32 v133, v19, v67 offset0:12 offset1:44
	v_add_u32_e32 v133, 0x5000, v166
	ds_write2_b32 v133, v20, v68 offset0:160 offset1:192
	v_add_u32_e32 v133, 0x5400, v166
	ds_write2_b32 v133, v21, v69 offset0:36 offset1:68
	ds_write2_b32 v133, v22, v70 offset0:168 offset1:200
	v_add_u32_e32 v133, 0x5800, v166
	ds_write2_b32 v133, v23, v71 offset0:44 offset1:76
	v_add_u32_e32 v133, 0x6000, v166
	ds_write2_b32 v133, v24, v72 offset0:192 offset1:224
	v_add_u32_e32 v133, 0x6400, v166
	ds_write2_b32 v133, v25, v73 offset0:68 offset1:100
	ds_write2_b32 v133, v26, v74 offset0:200 offset1:232
	v_add_u32_e32 v133, 0x6800, v166
	ds_write2_b32 v133, v27, v75 offset0:76 offset1:108
	v_add_u32_e32 v133, 0x7200, v166
	ds_write2_b32 v133, v28, v76 offset0:96 offset1:128
	v_add_u32_e32 v133, 0x7400, v166
	ds_write2_b32 v133, v29, v77 offset0:100 offset1:132
	v_add_u32_e32 v133, 0x7600, v166
	ds_write2_b32 v133, v30, v78 offset0:104 offset1:136
	v_add_u32_e32 v133, 0x7800, v166
	ds_write2_b32 v133, v31, v79 offset0:108 offset1:140
	v_add_u32_e32 v133, 0x8400, v166
	ds_write2_b32 v133, v32, v112 offset1:32
	ds_write2_b32 v133, v33, v113 offset0:132 offset1:164
	v_add_u32_e32 v133, 0x8800, v166
	ds_write2_b32 v133, v34, v114 offset0:8 offset1:40
	ds_write2_b32 v133, v35, v115 offset0:140 offset1:172
	v_add_u32_e32 v133, 0x9400, v166
	ds_write2_b32 v133, v36, v116 offset0:32 offset1:64
	ds_write2_b32 v133, v37, v117 offset0:164 offset1:196
	v_add_u32_e32 v133, 0x9800, v166
	ds_write2_b32 v133, v38, v118 offset0:40 offset1:72
	ds_write2_b32 v133, v39, v119 offset0:172 offset1:204
	v_add_u32_e32 v133, 0xa400, v166
	ds_write2_b32 v133, v40, v120 offset0:64 offset1:96
	ds_write2_b32 v133, v41, v121 offset0:196 offset1:228
	v_add_u32_e32 v133, 0xa800, v166
	ds_write2_b32 v133, v42, v122 offset0:72 offset1:104
	ds_write2_b32 v133, v43, v123 offset0:204 offset1:236
	v_add_u32_e32 v133, 0xb400, v166
	ds_write2_b32 v133, v44, v124 offset0:96 offset1:128
	v_add_u32_e32 v133, 0xb600, v166
	ds_write2_b32 v133, v45, v125 offset0:100 offset1:132
	v_add_u32_e32 v133, 0xb800, v166
	ds_write2_b32 v133, v46, v126 offset0:104 offset1:136
	v_add_u32_e32 v133, 0xba00, v166
	ds_write2_b32 v133, v47, v127 offset0:108 offset1:140
	v_add_u32_e32 v133, 0xc400, v166
	ds_write2_b32 v133, v80, v96 offset0:128 offset1:160
	v_add_u32_e32 v133, 0xc800, v166
	ds_write2_b32 v133, v81, v97 offset0:4 offset1:36
	ds_write2_b32 v133, v82, v98 offset0:136 offset1:168
	v_add_u32_e32 v133, 0xcc00, v166
	ds_write2_b32 v133, v83, v99 offset0:12 offset1:44
	v_add_u32_e32 v133, 0xd400, v166
	ds_write2_b32 v133, v84, v100 offset0:160 offset1:192
	v_add_u32_e32 v133, 0xd800, v166
	ds_write2_b32 v133, v85, v101 offset0:36 offset1:68
	ds_write2_b32 v133, v86, v102 offset0:168 offset1:200
	v_add_u32_e32 v133, 0xdc00, v166
	ds_write2_b32 v133, v87, v103 offset0:44 offset1:76
	v_add_u32_e32 v133, 0xe400, v166
	ds_write2_b32 v133, v88, v104 offset0:192 offset1:224
	v_add_u32_e32 v133, 0xe800, v166
	ds_write2_b32 v133, v89, v105 offset0:68 offset1:100
	ds_write2_b32 v133, v90, v106 offset0:200 offset1:232
	v_add_u32_e32 v133, 0xec00, v166
	ds_write2_b32 v133, v91, v107 offset0:76 offset1:108
	v_add_u32_e32 v133, 0xf600, v166
	ds_write2_b32 v133, v92, v108 offset0:96 offset1:128
	v_add_u32_e32 v133, 0xf800, v166
	ds_write2_b32 v133, v93, v109 offset0:100 offset1:132
	v_add_u32_e32 v133, 0xfa00, v166
	ds_write2_b32 v133, v94, v110 offset0:104 offset1:136
	v_add_u32_e32 v133, 0xfc00, v166
	ds_write2_b32 v133, v95, v111 offset0:108 offset1:140

.LBB0_1182:
	s_and_b64 vcc, exec, s[24:25]
	s_cbranch_vccz .LBB0_1173
	s_lshl_b32 s4, s43, 17
	s_add_u32 s24, s28, s4
	v_readfirstlane_b32 s4, v160
	s_mov_b32 m0, s4
	v_readfirstlane_b32 s4, v168
	s_addc_u32 s25, s29, 0
	v_mov_b32_e32 v135, v131
	s_waitcnt vmcnt(0)
	s_barrier
	s_nop 0
	s_mov_b32 m0, s4
	v_readfirstlane_b32 s4, v169
	v_lshl_add_u64 v[0:1], s[24:25], 0, v[134:135]
	v_mov_b32_e32 v133, v131
	s_nop 0
	s_mov_b32 m0, s4
	v_readfirstlane_b32 s4, v170
	v_lshl_add_u64 v[0:1], v[0:1], 0, v[132:133]
	s_nop 0
	s_mov_b32 m0, s4
	v_readfirstlane_b32 s4, v171
	v_lshl_add_u64 v[152:153], v[0:1], 0, s[16:17]
	s_nop 0
	s_mov_b32 m0, s4
	v_readfirstlane_b32 s4, v172
	v_lshl_add_u64 v[154:155], v[0:1], 0, s[18:19]
	s_nop 0
	s_mov_b32 m0, s4
	v_readfirstlane_b32 s4, v173
	s_nop 0
	s_mov_b32 m0, s4
	v_readfirstlane_b32 s4, v174
	s_nop 0
	s_mov_b32 m0, s4
	v_readfirstlane_b32 s4, v175
	s_nop 0
	s_mov_b32 m0, s4
	v_readfirstlane_b32 s4, v176
	s_nop 0
	s_mov_b32 m0, s4
	v_readfirstlane_b32 s4, v177
	s_nop 0
	v_lshl_add_u64 v[2:3], v[0:1], 0, s[20:21]
	s_mov_b32 m0, s4
	v_readfirstlane_b32 s4, v178
	s_nop 0
	v_lshl_add_u64 v[0:1], v[0:1], 0, s[22:23]
	s_mov_b32 m0, s4
	s_mov_b32 s25, 2
	s_nop 0
	v_mov_b32_e32 v0, 0
	s_mov_b32 s24, 0
	s_mov_b32 s26, 0
	v_mov_b32_e32 v1, v0
	v_mov_b32_e32 v2, v0
	v_mov_b32_e32 v3, v0
	v_mov_b32_e32 v4, v0
	v_mov_b32_e32 v5, v0
	v_mov_b32_e32 v6, v0
	v_mov_b32_e32 v7, v0
	v_mov_b32_e32 v8, v0
	v_mov_b32_e32 v9, v0
	v_mov_b32_e32 v10, v0
	v_mov_b32_e32 v11, v0
	v_mov_b32_e32 v12, v0
	v_mov_b32_e32 v13, v0
	v_mov_b32_e32 v14, v0
	v_mov_b32_e32 v15, v0
	v_mov_b32_e32 v16, v0
	v_mov_b32_e32 v17, v0
	v_mov_b32_e32 v18, v0
	v_mov_b32_e32 v19, v0
	v_mov_b32_e32 v20, v0
	v_mov_b32_e32 v21, v0
	v_mov_b32_e32 v22, v0
	v_mov_b32_e32 v23, v0
	v_mov_b32_e32 v24, v0
	v_mov_b32_e32 v25, v0
	v_mov_b32_e32 v26, v0
	v_mov_b32_e32 v27, v0
	v_mov_b32_e32 v28, v0
	v_mov_b32_e32 v29, v0
	v_mov_b32_e32 v30, v0
	v_mov_b32_e32 v31, v0
	v_mov_b32_e32 v32, v0
	v_mov_b32_e32 v33, v0
	v_mov_b32_e32 v34, v0
	v_mov_b32_e32 v35, v0
	v_mov_b32_e32 v36, v0
	v_mov_b32_e32 v37, v0
	v_mov_b32_e32 v38, v0
	v_mov_b32_e32 v39, v0
	v_mov_b32_e32 v40, v0
	v_mov_b32_e32 v41, v0
	v_mov_b32_e32 v42, v0
	v_mov_b32_e32 v43, v0
	v_mov_b32_e32 v44, v0
	v_mov_b32_e32 v45, v0
	v_mov_b32_e32 v46, v0
	v_mov_b32_e32 v47, v0
	v_mov_b32_e32 v48, v0
	v_mov_b32_e32 v49, v0
	v_mov_b32_e32 v50, v0
	v_mov_b32_e32 v51, v0
	v_mov_b32_e32 v52, v0
	v_mov_b32_e32 v53, v0
	v_mov_b32_e32 v54, v0
	v_mov_b32_e32 v55, v0
	v_mov_b32_e32 v56, v0
	v_mov_b32_e32 v57, v0
	v_mov_b32_e32 v58, v0
	v_mov_b32_e32 v59, v0
	v_mov_b32_e32 v60, v0
	v_mov_b32_e32 v61, v0
	v_mov_b32_e32 v62, v0
	v_mov_b32_e32 v63, v0
	v_mov_b32_e32 v64, v0
	v_mov_b32_e32 v65, v0
	v_mov_b32_e32 v66, v0
	v_mov_b32_e32 v67, v0
	v_mov_b32_e32 v68, v0
	v_mov_b32_e32 v69, v0
	v_mov_b32_e32 v70, v0
	v_mov_b32_e32 v71, v0
	v_mov_b32_e32 v72, v0
	v_mov_b32_e32 v73, v0
	v_mov_b32_e32 v74, v0
	v_mov_b32_e32 v75, v0
	v_mov_b32_e32 v76, v0
	v_mov_b32_e32 v77, v0
	v_mov_b32_e32 v78, v0
	v_mov_b32_e32 v79, v0
	v_mov_b32_e32 v112, v0
	v_mov_b32_e32 v113, v0
	v_mov_b32_e32 v114, v0
	v_mov_b32_e32 v115, v0
	v_mov_b32_e32 v116, v0
	v_mov_b32_e32 v117, v0
	v_mov_b32_e32 v118, v0
	v_mov_b32_e32 v119, v0
	v_mov_b32_e32 v120, v0
	v_mov_b32_e32 v121, v0
	v_mov_b32_e32 v122, v0
	v_mov_b32_e32 v123, v0
	v_mov_b32_e32 v124, v0
	v_mov_b32_e32 v125, v0
	v_mov_b32_e32 v126, v0
	v_mov_b32_e32 v127, v0
	v_mov_b32_e32 v80, v0
	v_mov_b32_e32 v81, v0
	v_mov_b32_e32 v82, v0
	v_mov_b32_e32 v83, v0
	v_mov_b32_e32 v84, v0
	v_mov_b32_e32 v85, v0
	v_mov_b32_e32 v86, v0
	v_mov_b32_e32 v87, v0
	v_mov_b32_e32 v88, v0
	v_mov_b32_e32 v89, v0
	v_mov_b32_e32 v90, v0
	v_mov_b32_e32 v91, v0
	v_mov_b32_e32 v92, v0
	v_mov_b32_e32 v93, v0
	v_mov_b32_e32 v94, v0
	v_mov_b32_e32 v95, v0
	v_mov_b32_e32 v96, v0
	v_mov_b32_e32 v97, v0
	v_mov_b32_e32 v98, v0
	v_mov_b32_e32 v99, v0
	v_mov_b32_e32 v100, v0
	v_mov_b32_e32 v101, v0
	v_mov_b32_e32 v102, v0
	v_mov_b32_e32 v103, v0
	v_mov_b32_e32 v104, v0
	v_mov_b32_e32 v105, v0
	v_mov_b32_e32 v106, v0
	v_mov_b32_e32 v107, v0
	v_mov_b32_e32 v108, v0
	v_mov_b32_e32 v109, v0
	v_mov_b32_e32 v110, v0
	v_mov_b32_e32 v111, v0
	s_mov_b64 s[54:55], 0x80
	v_lshrrev_b32_e32 v148, 6, v180
	v_lshlrev_b32_e32 v158, 11, v148
	v_and_b32_e32 v144, 63, v180
	v_readfirstlane_b32 s53, v158
	v_lshrrev_b32_e32 v145, 5, v144
	v_bfe_u32 v146, v144, 1, 3
	v_xor_b32_e32 v146, v145, v146
	v_and_b32_e32 v147, 31, v144
	v_lshlrev_b32_e32 v147, 7, v147
	v_lshrrev_b32_e32 v147, 3, v144
	v_lshlrev_b32_e32 v158, 4, v147
	v_add_u32_e32 v159, 0x80, v158
	v_and_b32_e32 v147, 7, v144
	v_lshrrev_b32_e32 v145, 4, v144
	v_xor_b32_e32 v145, v147, v145
	v_lshrrev_b32_e32 v147, 5, v144
	v_sub_u32_e32 v182, v145, v147
	v_xor_b32_e32 v145, 4, v145
	v_add_u32_e32 v147, 2, v147
	v_sub_u32_e32 v184, v145, v147
	v_lshlrev_b32_e32 v182, 4, v182
	v_ashrrev_i32_e32 v183, 31, v182
	v_lshlrev_b32_e32 v184, 4, v184
	v_ashrrev_i32_e32 v185, 31, v184
	ds_bpermute_b32 v244, v158, v152
	ds_bpermute_b32 v245, v158, v153
	ds_bpermute_b32 v246, v159, v152
	ds_bpermute_b32 v247, v159, v153
	ds_bpermute_b32 v248, v158, v154
	ds_bpermute_b32 v249, v158, v155
	ds_bpermute_b32 v250, v159, v154
	ds_bpermute_b32 v251, v159, v155
	s_waitcnt lgkmcnt(0)
	ds_bpermute_b32 v186, v158, v136
	ds_bpermute_b32 v187, v158, v137
	ds_bpermute_b32 v234, v159, v136
	ds_bpermute_b32 v235, v159, v137
	ds_bpermute_b32 v236, v158, v138
	ds_bpermute_b32 v237, v158, v139
	ds_bpermute_b32 v238, v159, v138
	ds_bpermute_b32 v239, v159, v139
	ds_bpermute_b32 v240, v158, v140
	ds_bpermute_b32 v241, v158, v141
	ds_bpermute_b32 v242, v159, v140
	ds_bpermute_b32 v243, v159, v141
	ds_bpermute_b32 v152, v158, v142
	ds_bpermute_b32 v153, v158, v143
	ds_bpermute_b32 v154, v159, v142
	ds_bpermute_b32 v155, v159, v143
	s_waitcnt lgkmcnt(0)
	v_and_b32_e32 v147, 31, v144
	v_lshlrev_b32_e32 v147, 7, v147
	v_lshrrev_b32_e32 v145, 1, v148
	v_lshl_add_u32 v136, v145, 14, v147
	v_and_b32_e32 v145, 1, v148
	v_lshl_add_u32 v140, v145, 13, v147
	v_add_u32_e32 v140, 0x10000, v140
	v_xor_b32_e32 v147, 6, v146
	v_lshl_add_u32 v139, v147, 4, v136
	v_lshl_add_u32 v143, v147, 4, v140
	v_xor_b32_e32 v147, 4, v146
	v_lshl_add_u32 v138, v147, 4, v136
	v_lshl_add_u32 v142, v147, 4, v140
	v_xor_b32_e32 v147, 2, v146
	v_lshl_add_u32 v137, v147, 4, v136
	v_lshl_add_u32 v141, v147, 4, v140
	v_xor_b32_e32 v147, 0, v146
	v_lshl_add_u32 v136, v147, 4, v136
	v_lshl_add_u32 v140, v147, 4, v140
	v_lshl_add_u64 v[186:187], v[186:187], 0, v[182:183]
	v_lshl_add_u64 v[234:235], v[234:235], 0, v[184:185]
	v_lshl_add_u64 v[236:237], v[236:237], 0, v[182:183]
	v_lshl_add_u64 v[238:239], v[238:239], 0, v[184:185]
	v_lshl_add_u64 v[240:241], v[240:241], 0, v[182:183]
	v_lshl_add_u64 v[242:243], v[242:243], 0, v[184:185]
	v_lshl_add_u64 v[152:153], v[152:153], 0, v[182:183]
	v_lshl_add_u64 v[154:155], v[154:155], 0, v[184:185]
	v_lshl_add_u64 v[244:245], v[244:245], 0, v[182:183]
	v_lshl_add_u64 v[246:247], v[246:247], 0, v[184:185]
	v_lshl_add_u64 v[248:249], v[248:249], 0, v[182:183]
	v_lshl_add_u64 v[250:251], v[250:251], 0, v[184:185]
	s_mov_b32 s58, s53
	s_add_i32 m0, s58, 0x0
	s_nop 0
	global_load_lds_dwordx4 v[186:187], off
	s_add_i32 m0, s58, 0x400
	v_lshl_add_u64 v[186:187], v[186:187], 0, s[54:55]
	global_load_lds_dwordx4 v[234:235], off
	s_add_i32 m0, s58, 0x2000
	v_lshl_add_u64 v[234:235], v[234:235], 0, s[54:55]
	global_load_lds_dwordx4 v[236:237], off
	s_add_i32 m0, s58, 0x2400
	v_lshl_add_u64 v[236:237], v[236:237], 0, s[54:55]
	global_load_lds_dwordx4 v[238:239], off
	s_add_i32 m0, s58, 0x4000
	v_lshl_add_u64 v[238:239], v[238:239], 0, s[54:55]
	global_load_lds_dwordx4 v[240:241], off
	s_add_i32 m0, s58, 0x4400
	v_lshl_add_u64 v[240:241], v[240:241], 0, s[54:55]
	global_load_lds_dwordx4 v[242:243], off
	s_add_i32 m0, s58, 0x6000
	v_lshl_add_u64 v[242:243], v[242:243], 0, s[54:55]
	global_load_lds_dwordx4 v[152:153], off
	s_add_i32 m0, s58, 0x6400
	v_lshl_add_u64 v[152:153], v[152:153], 0, s[54:55]
	global_load_lds_dwordx4 v[154:155], off
	v_lshl_add_u64 v[154:155], v[154:155], 0, s[54:55]
	s_add_i32 s58, s53, 0x10000
	s_add_i32 m0, s58, 0x0
	s_nop 0
	global_load_lds_dwordx4 v[244:245], off
	s_add_i32 m0, s58, 0x400
	v_lshl_add_u64 v[244:245], v[244:245], 0, s[54:55]
	global_load_lds_dwordx4 v[246:247], off
	s_add_i32 m0, s58, 0x2000
	v_lshl_add_u64 v[246:247], v[246:247], 0, s[54:55]
	global_load_lds_dwordx4 v[248:249], off
	s_add_i32 m0, s58, 0x2400
	v_lshl_add_u64 v[248:249], v[248:249], 0, s[54:55]
	global_load_lds_dwordx4 v[250:251], off
	v_lshl_add_u64 v[250:251], v[250:251], 0, s[54:55]
	s_mov_b32 s24, 0
	s_mov_b32 s25, 0

.Lg_ph11b_noB:
	s_waitcnt lgkmcnt(3)
	v_mfma_f32_32x32x16_bf16 v[0:15], v[144:147], v[190:193], v[0:15]
	v_mfma_f32_32x32x16_bf16 v[16:31], v[144:147], v[194:197], v[16:31]
	ds_read_b128 v[144:147], v137
	s_waitcnt lgkmcnt(3)
	v_mfma_f32_32x32x16_bf16 v[32:47], v[148:151], v[190:193], v[32:47]
	v_mfma_f32_32x32x16_bf16 v[48:63], v[148:151], v[194:197], v[48:63]
	ds_read_b128 v[148:151], v137 offset:4096
	s_waitcnt lgkmcnt(3)
	v_mfma_f32_32x32x16_bf16 v[64:79], v[156:159], v[190:193], v[64:79]
	v_mfma_f32_32x32x16_bf16 v[112:127], v[156:159], v[194:197], v[112:127]
	ds_read_b128 v[156:159], v137 offset:8192
	s_waitcnt lgkmcnt(3)
	v_mfma_f32_32x32x16_bf16 v[80:95], v[182:185], v[190:193], v[80:95]
	v_mfma_f32_32x32x16_bf16 v[96:111], v[182:185], v[194:197], v[96:111]
	ds_read_b128 v[182:185], v137 offset:12288
	s_waitcnt lgkmcnt(3)
	v_mfma_f32_32x32x16_bf16 v[0:15], v[144:147], v[198:201], v[0:15]
	v_mfma_f32_32x32x16_bf16 v[16:31], v[144:147], v[202:205], v[16:31]
	ds_read_b128 v[144:147], v138
	s_waitcnt lgkmcnt(3)
	v_mfma_f32_32x32x16_bf16 v[32:47], v[148:151], v[198:201], v[32:47]
	v_mfma_f32_32x32x16_bf16 v[48:63], v[148:151], v[202:205], v[48:63]
	ds_read_b128 v[148:151], v138 offset:4096
	s_waitcnt lgkmcnt(3)
	v_mfma_f32_32x32x16_bf16 v[64:79], v[156:159], v[198:201], v[64:79]
	v_mfma_f32_32x32x16_bf16 v[112:127], v[156:159], v[202:205], v[112:127]
	ds_read_b128 v[156:159], v138 offset:8192
	s_waitcnt lgkmcnt(3)
	v_mfma_f32_32x32x16_bf16 v[80:95], v[182:185], v[198:201], v[80:95]
	v_mfma_f32_32x32x16_bf16 v[96:111], v[182:185], v[202:205], v[96:111]
	ds_read_b128 v[182:185], v138 offset:12288
	s_waitcnt lgkmcnt(3)
	v_mfma_f32_32x32x16_bf16 v[0:15], v[144:147], v[206:209], v[0:15]
	v_mfma_f32_32x32x16_bf16 v[16:31], v[144:147], v[222:225], v[16:31]
	ds_read_b128 v[144:147], v139
	s_waitcnt lgkmcnt(3)
	v_mfma_f32_32x32x16_bf16 v[32:47], v[148:151], v[206:209], v[32:47]
	v_mfma_f32_32x32x16_bf16 v[48:63], v[148:151], v[222:225], v[48:63]
	ds_read_b128 v[148:151], v139 offset:4096
	s_waitcnt lgkmcnt(3)
	v_mfma_f32_32x32x16_bf16 v[64:79], v[156:159], v[206:209], v[64:79]
	v_mfma_f32_32x32x16_bf16 v[112:127], v[156:159], v[222:225], v[112:127]
	ds_read_b128 v[156:159], v139 offset:8192
	s_waitcnt lgkmcnt(3)
	v_mfma_f32_32x32x16_bf16 v[80:95], v[182:185], v[206:209], v[80:95]
	v_mfma_f32_32x32x16_bf16 v[96:111], v[182:185], v[222:225], v[96:111]
	ds_read_b128 v[182:185], v139 offset:12288
	s_waitcnt lgkmcnt(3)
	v_mfma_f32_32x32x16_bf16 v[0:15], v[144:147], v[226:229], v[0:15]
	v_mfma_f32_32x32x16_bf16 v[16:31], v[144:147], v[230:233], v[16:31]
	s_waitcnt lgkmcnt(2)
	v_mfma_f32_32x32x16_bf16 v[32:47], v[148:151], v[226:229], v[32:47]
	v_mfma_f32_32x32x16_bf16 v[48:63], v[148:151], v[230:233], v[48:63]
	s_waitcnt lgkmcnt(1)
	v_mfma_f32_32x32x16_bf16 v[64:79], v[156:159], v[226:229], v[64:79]
	v_mfma_f32_32x32x16_bf16 v[112:127], v[156:159], v[230:233], v[112:127]
	s_waitcnt lgkmcnt(0)
	v_mfma_f32_32x32x16_bf16 v[80:95], v[182:185], v[226:229], v[80:95]
	v_mfma_f32_32x32x16_bf16 v[96:111], v[182:185], v[230:233], v[96:111]
	v_xor_b32_e32 v136, 0x8000, v136
	v_xor_b32_e32 v137, 0x8000, v137
	v_xor_b32_e32 v138, 0x8000, v138
	v_xor_b32_e32 v139, 0x8000, v139
	s_xor_b32 s25, s25, 0x8000
	s_add_i32 s24, s24, 1
	s_cmp_eq_u32 s24, 16
	s_cbranch_scc0 .Lg_ph11b_top
	s_waitcnt vmcnt(0)
	v_mov_b32_e32 v130, v180
	v_add_u32_e32 v192, 0x400, v166
	v_add_u32_e32 v191, 0x1000, v166
	v_add_u32_e32 v190, 0x1400, v166
	v_add_u32_e32 v189, 0x2000, v166
	v_add_u32_e32 v182, 0x2400, v166
	v_add_u32_e32 v183, 0x3000, v166
	v_add_u32_e32 v184, 0x3200, v166
	v_add_u32_e32 v185, 0x3400, v166
	v_add_u32_e32 v186, 0x3600, v166
	v_add_u32_e32 v187, 0x4000, v166
	v_add_u32_e32 v159, 0x4400, v166
	v_add_u32_e32 v179, 0x4800, v166
	v_add_u32_e32 v181, 0x5000, v166
	v_add_u32_e32 v156, 0x5400, v166
	v_add_u32_e32 v157, 0x5800, v166
	v_add_u32_e32 v158, 0x6000, v166
	v_add_u32_e32 v150, 0x6400, v166
	v_add_u32_e32 v151, 0x6800, v166
	v_add_u32_e32 v152, 0x7200, v166
	v_add_u32_e32 v153, 0x7400, v166
	v_add_u32_e32 v154, 0x7600, v166
	v_add_u32_e32 v155, 0x7800, v166
	v_add_u32_e32 v149, 0x8400, v166
	v_add_u32_e32 v148, 0x8800, v166
	v_add_u32_e32 v147, 0x9400, v166
	v_add_u32_e32 v146, 0x9800, v166
	v_add_u32_e32 v145, 0xa400, v166
	v_add_u32_e32 v140, 0xa800, v166
	v_add_u32_e32 v141, 0xb400, v166
	v_add_u32_e32 v142, 0xb600, v166
	v_add_u32_e32 v143, 0xb800, v166
	v_add_u32_e32 v144, 0xba00, v166
	s_waitcnt vmcnt(0)
	s_barrier
	s_and_saveexec_b64 s[24:25], s[6:7]
	s_cbranch_execz .LBB0_1187
	v_add_u32_e32 v133, 0xc400, v166
	ds_write2_b32 v166, v0, v16 offset1:32
	ds_write2_b32 v166, v1, v17 offset0:132 offset1:164
	ds_write2_b32 v192, v2, v18 offset0:8 offset1:40
	ds_write2_b32 v192, v3, v19 offset0:140 offset1:172
	ds_write2_b32 v191, v4, v20 offset0:32 offset1:64
	ds_write2_b32 v191, v5, v21 offset0:164 offset1:196
	ds_write2_b32 v190, v6, v22 offset0:40 offset1:72
	ds_write2_b32 v190, v7, v23 offset0:172 offset1:204
	ds_write2_b32 v189, v8, v24 offset0:64 offset1:96
	ds_write2_b32 v189, v9, v25 offset0:196 offset1:228
	ds_write2_b32 v182, v10, v26 offset0:72 offset1:104
	ds_write2_b32 v182, v11, v27 offset0:204 offset1:236
	ds_write2_b32 v183, v12, v28 offset0:96 offset1:128
	ds_write2_b32 v184, v13, v29 offset0:100 offset1:132
	ds_write2_b32 v185, v14, v30 offset0:104 offset1:136
	ds_write2_b32 v186, v15, v31 offset0:108 offset1:140
	ds_write2_b32 v187, v32, v48 offset0:128 offset1:160
	ds_write2_b32 v159, v33, v49 offset0:4 offset1:36
	ds_write2_b32 v159, v34, v50 offset0:136 offset1:168
	ds_write2_b32 v179, v35, v51 offset0:12 offset1:44
	ds_write2_b32 v181, v36, v52 offset0:160 offset1:192
	ds_write2_b32 v156, v37, v53 offset0:36 offset1:68
	ds_write2_b32 v156, v38, v54 offset0:168 offset1:200
	ds_write2_b32 v157, v39, v55 offset0:44 offset1:76
	ds_write2_b32 v158, v40, v56 offset0:192 offset1:224
	ds_write2_b32 v150, v41, v57 offset0:68 offset1:100
	ds_write2_b32 v150, v42, v58 offset0:200 offset1:232
	ds_write2_b32 v151, v43, v59 offset0:76 offset1:108
	ds_write2_b32 v152, v44, v60 offset0:96 offset1:128
	ds_write2_b32 v153, v45, v61 offset0:100 offset1:132
	ds_write2_b32 v154, v46, v62 offset0:104 offset1:136
	ds_write2_b32 v155, v47, v63 offset0:108 offset1:140
	ds_write2_b32 v149, v64, v112 offset1:32
	ds_write2_b32 v149, v65, v113 offset0:132 offset1:164
	ds_write2_b32 v148, v66, v114 offset0:8 offset1:40
	ds_write2_b32 v148, v67, v115 offset0:140 offset1:172
	ds_write2_b32 v147, v68, v116 offset0:32 offset1:64
	ds_write2_b32 v147, v69, v117 offset0:164 offset1:196
	ds_write2_b32 v146, v70, v118 offset0:40 offset1:72
	ds_write2_b32 v146, v71, v119 offset0:172 offset1:204
	ds_write2_b32 v145, v72, v120 offset0:64 offset1:96
	ds_write2_b32 v145, v73, v121 offset0:196 offset1:228
	ds_write2_b32 v140, v74, v122 offset0:72 offset1:104
	ds_write2_b32 v140, v75, v123 offset0:204 offset1:236
	ds_write2_b32 v141, v76, v124 offset0:96 offset1:128
	ds_write2_b32 v142, v77, v125 offset0:100 offset1:132
	ds_write2_b32 v143, v78, v126 offset0:104 offset1:136
	ds_write2_b32 v144, v79, v127 offset0:108 offset1:140
	ds_write2_b32 v133, v80, v96 offset0:128 offset1:160
	v_add_u32_e32 v133, 0xc800, v166
	ds_write2_b32 v133, v81, v97 offset0:4 offset1:36
	ds_write2_b32 v133, v82, v98 offset0:136 offset1:168
	v_add_u32_e32 v133, 0xcc00, v166
	ds_write2_b32 v133, v83, v99 offset0:12 offset1:44
	v_add_u32_e32 v133, 0xd400, v166
	ds_write2_b32 v133, v84, v100 offset0:160 offset1:192
	v_add_u32_e32 v133, 0xd800, v166
	ds_write2_b32 v133, v85, v101 offset0:36 offset1:68
	ds_write2_b32 v133, v86, v102 offset0:168 offset1:200
	v_add_u32_e32 v133, 0xdc00, v166
	ds_write2_b32 v133, v87, v103 offset0:44 offset1:76
	v_add_u32_e32 v133, 0xe400, v166
	ds_write2_b32 v133, v88, v104 offset0:192 offset1:224
	v_add_u32_e32 v133, 0xe800, v166
	ds_write2_b32 v133, v89, v105 offset0:68 offset1:100
	ds_write2_b32 v133, v90, v106 offset0:200 offset1:232
	v_add_u32_e32 v133, 0xec00, v166
	ds_write2_b32 v133, v91, v107 offset0:76 offset1:108
	v_add_u32_e32 v133, 0xf600, v166
	ds_write2_b32 v133, v92, v108 offset0:96 offset1:128
	v_add_u32_e32 v133, 0xf800, v166
	ds_write2_b32 v133, v93, v109 offset0:100 offset1:132
	v_add_u32_e32 v133, 0xfa00, v166
	ds_write2_b32 v133, v94, v110 offset0:104 offset1:136
	v_add_u32_e32 v133, 0xfc00, v166
	ds_write2_b32 v133, v95, v111 offset0:108 offset1:140

.LBB0_1190:
	v_cmp_lt_i32_e32 vcc, 12, v4
	s_and_saveexec_b64 s[2:3], vcc
	s_cbranch_execz .LBB0_1244
	s_waitcnt vmcnt(0)
	s_waitcnt lgkmcnt(0)
	v_mov_b32_e32 v254, 0x12000
	v_mov_b32_e32 v252, s97
	v_mov_b32_e32 v253, s96
	ds_write_b64 v254, v[252:253]
	s_waitcnt lgkmcnt(0)
	s_barrier
	s_mov_b64 s[4:5], exec
	v_readlane_b32 s6, v255, 5
	v_readlane_b32 s7, v255, 6
	s_and_b64 s[6:7], s[4:5], s[6:7]
	s_mov_b64 exec, s[6:7]
	s_cbranch_execz .LBB0_1243
	s_add_i32 s50, 0, 0x12000
	s_mov_b64 s[6:7], src_shared_base
	s_cmp_lg_u32 s50, -1
	s_cselect_b32 s6, s50, 0
	s_cselect_b32 s8, s7, 0
	s_add_i32 s51, 0, 0x12004
	s_cmp_lg_u32 s51, -1
	v_mov_b32_e32 v0, s6
	v_mov_b32_e32 v1, s8
	s_cselect_b32 s6, s51, 0
	s_cselect_b32 s7, s7, 0
	s_waitcnt vmcnt(0) expcnt(0) lgkmcnt(0)
	flat_load_dword v2, v[0:1] sc0 sc1
	s_waitcnt vmcnt(0)
	v_mov_b32_e32 v0, s6
	v_mov_b32_e32 v1, s7
	flat_load_dword v0, v[0:1] sc0 sc1
	s_waitcnt vmcnt(0) lgkmcnt(0)
	v_cmp_eq_u32_e32 vcc, 0, v2
	s_and_saveexec_b64 s[6:7], vcc
	s_cbranch_execz .LBB0_1207
	s_add_u32 s8, s94, 0x1d11e200
	s_addc_u32 s9, s95, 0
	s_add_u32 s10, s94, 0x1d11e400
	s_addc_u32 s11, s95, 0
	s_add_u32 s12, s94, 0x1d11e500
	s_addc_u32 s13, s95, 0
	s_add_u32 s14, s94, 0x1d11e600
	s_addc_u32 s15, s95, 0
	s_add_u32 s16, s94, 0x1d11e700
	s_addc_u32 s17, s95, 0
	s_add_u32 s18, s94, 0x1d11e800
	s_addc_u32 s19, s95, 0
	s_add_u32 s20, s94, 0x1d11e900
	s_addc_u32 s21, s95, 0
	s_add_u32 s22, s94, 0x1d11ea00
	s_addc_u32 s23, s95, 0
	s_add_u32 s24, s94, 0x1d11eb00
	s_addc_u32 s25, s95, 0
	s_add_u32 s26, s94, 0x1d11ec00
	s_addc_u32 s27, s95, 0
	s_add_u32 s28, s94, 0x1d11ed00
	s_addc_u32 s29, s95, 0
	s_add_u32 s30, s94, 0x1d11ee00
	s_addc_u32 s31, s95, 0
	s_add_u32 s34, s94, 0x1d11ef00
	s_addc_u32 s35, s95, 0
	s_add_u32 s36, s94, 0x1d11f000
	s_addc_u32 s37, s95, 0
	s_add_u32 s38, s94, 0x1d11f100
	s_addc_u32 s39, s95, 0
	s_add_u32 s40, s94, 0x1d11f200
	s_addc_u32 s41, s95, 0
	s_add_u32 s42, s94, 0x1d11f300
	s_addc_u32 s43, s95, 0
	s_mov_b32 s52, 1
	v_mov_b32_e32 v16, 0
	s_branch .LBB0_1195

.LBB0_1311:
	s_or_b64 exec, exec, s[0:1]
	v_readlane_b32 s0, v255, 4
	s_cmp_lt_i32 s0, 14
	s_cselect_b64 s[0:1], -1, 0
	v_cmp_lt_i32_e32 vcc, 13, v4
	s_and_b64 s[2:3], s[0:1], vcc
	s_and_saveexec_b64 s[0:1], s[2:3]
	s_cbranch_execz .LBB0_1377
	v_mov_b32_e32 v254, 0x12000
	ds_read_b64 v[252:253], v254
	s_waitcnt lgkmcnt(0)
	v_readfirstlane_b32 s97, v252
	v_readfirstlane_b32 s96, v253
	v_readlane_b32 s2, v255, 0
	s_cmpk_gt_u32 s2, 0x1ff
	v_readlane_b32 s3, v255, 1
	s_cbranch_scc1 .LBB0_1322
	v_lshrrev_b32_e32 v3, 4, v180
	v_xor_b32_e32 v3, v3, v180
	v_lshlrev_b32_e32 v3, 3, v3
	v_and_b32_e32 v128, 24, v3
	v_lshlrev_b32_e32 v3, 4, v180
	s_add_u32 s2, s94, 0x10ede000
	v_lshrrev_b32_e32 v1, 5, v180
	v_and_b32_e32 v3, 0x3c00, v3
	v_bfe_u32 v4, v180, 2, 2
	s_addc_u32 s3, s95, 0
	v_add_u32_e32 v148, 0, v3
	v_bfe_u32 v3, v180, 5, 1
	v_bitop3_b32 v1, v1, v4, 1 bitop3:0x6c
	s_add_u32 s18, s94, 0xaa0000
	v_lshlrev_b32_e32 v149, 4, v1
	v_bitop3_b32 v1, v3, v4, 2 bitop3:0x36
	s_addc_u32 s19, s95, 0
	v_and_b32_e32 v2, 31, v180
	v_lshlrev_b32_e32 v150, 4, v1
	v_lshlrev_b32_e32 v1, 6, v180
	v_and_b32_e32 v4, 64, v180
	s_add_u32 s20, s94, 0x14ede000
	v_readlane_b32 s4, v255, 0
	v_lshlrev_b32_e32 v0, 8, v180
	v_and_b32_e32 v151, 0xe7c0, v1
	v_and_b32_e32 v152, 0x17c0, v1
	v_lshrrev_b32_e32 v1, 3, v180
	v_lshlrev_b32_e32 v4, 2, v4
	v_lshlrev_b32_e32 v2, 2, v2
	s_addc_u32 s21, s95, 0
	s_lshr_b32 s23, s4, 3
	s_lshl_b32 s4, s4, 3
	v_and_b32_e32 v129, 0x3fc00, v0
	v_lshrrev_b32_e32 v0, 2, v180
	v_add3_u32 v2, 0, v4, v2
	s_movk_i32 s8, 0x840
	v_or_b32_e32 v1, 0x7b, v1
	v_readlane_b32 s5, v255, 1
	s_and_b32 s24, s4, 56
	v_lshlrev_b32_e32 v0, 10, v0
	v_mov_b32_e32 v131, 0
	s_movk_i32 s4, 0x80
	v_mad_u32_u24 v153, v3, s8, v2
	v_and_b32_e32 v3, 0x380, v180
	v_mul_u32_u24_e32 v1, 0x210, v1
	s_lshr_b32 s22, s33, 3
	s_mov_b32 s5, 0
	v_cmp_gt_u32_e64 s[6:7], s4, v180
	v_cmp_eq_u32_e64 s[8:9], s4, v3
	s_movk_i32 s25, 0x210
	v_or_b32_e32 v154, 0x10000, v128
	s_mov_b32 s26, 0x20000
	v_or_b32_e32 v155, 0x20000, v128
	v_or_b32_e32 v156, 0x30000, v128
	v_lshlrev_b32_e32 v132, 1, v0
	v_mov_b32_e32 v133, v131
	v_lshlrev_b32_e32 v134, 1, v128
	v_mov_b32_e32 v135, v131
	v_add_u32_e32 v157, 0x1000, v148
	v_add_u32_e32 v158, 0x2000, v148
	v_add_u32_e32 v159, 0x3000, v148
	s_waitcnt lgkmcnt(0)
	s_mov_b64 s[10:11], 0x20000
	v_add_u32_e32 v160, 0x4000, v148
	v_add_u32_e32 v161, 0x5000, v148
	v_add_u32_e32 v162, 0x6000, v148
	v_add_u32_e32 v163, 0x7000, v148
	v_add_u32_e32 v164, 0x8000, v148
	v_add_u32_e32 v165, 0x9000, v148
	v_add_u32_e32 v166, 0xa000, v148
	s_mov_b64 s[12:13], 0x20040
	v_add_u32_e32 v167, 0xb000, v148
	s_mov_b64 s[14:15], 0x80
	v_add_u32_e32 v168, v2, v1
	s_mov_b32 s27, 0x40000
	s_mov_b32 s28, 0x60000
	s_branch .LBB0_1315

.LBB0_1315:
	s_lshr_b32 s4, s23, 3
	s_or_b32 s4, s4, s24
	s_lshl_b32 s30, s4, 18
	s_and_b32 s29, s23, 7
	v_or_b32_e32 v1, s30, v129
	s_lshl_b32 s4, s29, 18
	s_add_u32 s16, s18, s4
	v_or_b32_e32 v0, v1, v128
	v_readfirstlane_b32 s4, v148
	v_lshlrev_b32_e32 v130, 1, v0
	s_mov_b32 m0, s4
	v_readfirstlane_b32 s4, v157
	v_add_lshl_u32 v0, v1, v154, 1
	s_waitcnt vmcnt(0)
	s_barrier
	s_nop 0
	s_mov_b32 m0, s4
	v_readfirstlane_b32 s4, v158
	s_addc_u32 s17, s19, 0
	v_add_lshl_u32 v2, v1, v155, 1
	s_nop 0
	s_mov_b32 m0, s4
	v_readfirstlane_b32 s4, v159
	v_add_lshl_u32 v4, v1, v156, 1
	v_lshl_add_u64 v[6:7], s[16:17], 0, v[132:133]
	s_nop 0
	s_mov_b32 m0, s4
	v_readfirstlane_b32 s4, v160
	v_lshl_add_u64 v[136:137], v[6:7], 0, v[134:135]
	s_nop 0
	s_mov_b32 m0, s4
	v_readfirstlane_b32 s4, v161
	v_lshl_add_u64 v[138:139], s[2:3], 0, v[130:131]
	v_mov_b32_e32 v1, v131
	v_lshl_add_u64 v[146:147], v[136:137], 0, s[10:11]
	s_nop 0
	s_mov_b32 m0, s4
	v_readfirstlane_b32 s4, v162
	v_lshl_add_u64 v[140:141], s[2:3], 0, v[0:1]
	v_mov_b32_e32 v3, v131
	s_nop 0
	v_lshl_add_u64 v[0:1], v[138:139], 0, 64
	s_mov_b32 m0, s4
	v_readfirstlane_b32 s4, v163
	v_lshl_add_u64 v[142:143], s[2:3], 0, v[2:3]
	v_mov_b32_e32 v5, v131
	s_nop 0
	v_lshl_add_u64 v[0:1], v[140:141], 0, 64
	s_mov_b32 m0, s4
	v_readfirstlane_b32 s4, v164
	v_lshl_add_u64 v[144:145], s[2:3], 0, v[4:5]
	s_nop 0
	v_lshl_add_u64 v[0:1], v[142:143], 0, 64
	s_mov_b32 m0, s4
	v_readfirstlane_b32 s4, v165
	s_nop 0
	v_lshl_add_u64 v[0:1], v[144:145], 0, 64
	s_mov_b32 m0, s4
	v_readfirstlane_b32 s4, v166
	s_nop 0
	v_lshl_add_u64 v[0:1], v[136:137], 0, 64
	s_mov_b32 m0, s4
	v_readfirstlane_b32 s4, v167
	s_nop 0
	v_lshl_add_u64 v[0:1], v[136:137], 0, s[12:13]
	s_mov_b32 m0, s4
	s_mov_b32 s16, s5
	s_nop 0
	s_mov_b32 s17, 2
	s_mov_b32 s31, s5
	v_mov_b32_e32 v0, 0
	v_mov_b32_e32 v1, v131
	v_mov_b32_e32 v2, v131
	v_mov_b32_e32 v4, v131
	v_mov_b32_e32 v6, v131
	v_mov_b32_e32 v7, v131
	v_mov_b32_e32 v8, v131
	v_mov_b32_e32 v9, v131
	v_mov_b32_e32 v10, v131
	v_mov_b32_e32 v11, v131
	v_mov_b32_e32 v12, v131
	v_mov_b32_e32 v13, v131
	v_mov_b32_e32 v14, v131
	v_mov_b32_e32 v15, v131
	v_mov_b32_e32 v16, 0
	v_mov_b32_e32 v17, v131
	v_mov_b32_e32 v18, v131
	v_mov_b32_e32 v19, v131
	v_mov_b32_e32 v20, v131
	v_mov_b32_e32 v21, v131
	v_mov_b32_e32 v22, v131
	v_mov_b32_e32 v23, v131
	v_mov_b32_e32 v24, v131
	v_mov_b32_e32 v25, v131
	v_mov_b32_e32 v26, v131
	v_mov_b32_e32 v27, v131
	v_mov_b32_e32 v28, v131
	v_mov_b32_e32 v29, v131
	v_mov_b32_e32 v30, v131
	v_mov_b32_e32 v31, v131
	v_mov_b32_e32 v32, 0
	v_mov_b32_e32 v33, v131
	v_mov_b32_e32 v34, v131
	v_mov_b32_e32 v35, v131
	v_mov_b32_e32 v36, v131
	v_mov_b32_e32 v37, v131
	v_mov_b32_e32 v38, v131
	v_mov_b32_e32 v39, v131
	v_mov_b32_e32 v40, v131
	v_mov_b32_e32 v41, v131
	v_mov_b32_e32 v42, v131
	v_mov_b32_e32 v43, v131
	v_mov_b32_e32 v44, v131
	v_mov_b32_e32 v45, v131
	v_mov_b32_e32 v46, v131
	v_mov_b32_e32 v47, v131
	v_mov_b32_e32 v48, 0
	v_mov_b32_e32 v49, v131
	v_mov_b32_e32 v50, v131
	v_mov_b32_e32 v51, v131
	v_mov_b32_e32 v52, v131
	v_mov_b32_e32 v53, v131
	v_mov_b32_e32 v54, v131
	v_mov_b32_e32 v55, v131
	v_mov_b32_e32 v56, v131
	v_mov_b32_e32 v57, v131
	v_mov_b32_e32 v58, v131
	v_mov_b32_e32 v59, v131
	v_mov_b32_e32 v60, v131
	v_mov_b32_e32 v61, v131
	v_mov_b32_e32 v62, v131
	v_mov_b32_e32 v63, v131
	v_mov_b32_e32 v64, 0
	v_mov_b32_e32 v65, v131
	v_mov_b32_e32 v66, v131
	v_mov_b32_e32 v67, v131
	v_mov_b32_e32 v68, v131
	v_mov_b32_e32 v69, v131
	v_mov_b32_e32 v70, v131
	v_mov_b32_e32 v71, v131
	v_mov_b32_e32 v72, v131
	v_mov_b32_e32 v73, v131
	v_mov_b32_e32 v74, v131
	v_mov_b32_e32 v75, v131
	v_mov_b32_e32 v76, v131
	v_mov_b32_e32 v77, v131
	v_mov_b32_e32 v78, v131
	v_mov_b32_e32 v79, v131
	v_mov_b32_e32 v80, 0
	v_mov_b32_e32 v81, v131
	v_mov_b32_e32 v82, v131
	v_mov_b32_e32 v83, v131
	v_mov_b32_e32 v84, v131
	v_mov_b32_e32 v85, v131
	v_mov_b32_e32 v86, v131
	v_mov_b32_e32 v87, v131
	v_mov_b32_e32 v88, v131
	v_mov_b32_e32 v89, v131
	v_mov_b32_e32 v90, v131
	v_mov_b32_e32 v91, v131
	v_mov_b32_e32 v92, v131
	v_mov_b32_e32 v93, v131
	v_mov_b32_e32 v94, v131
	v_mov_b32_e32 v95, v131
	v_mov_b32_e32 v96, 0
	v_mov_b32_e32 v97, v131
	v_mov_b32_e32 v98, v131
	v_mov_b32_e32 v99, v131
	v_mov_b32_e32 v100, v131
	v_mov_b32_e32 v101, v131
	v_mov_b32_e32 v102, v131
	v_mov_b32_e32 v103, v131
	v_mov_b32_e32 v104, v131
	v_mov_b32_e32 v105, v131
	v_mov_b32_e32 v106, v131
	v_mov_b32_e32 v107, v131
	v_mov_b32_e32 v108, v131
	v_mov_b32_e32 v109, v131
	v_mov_b32_e32 v110, v131
	v_mov_b32_e32 v111, v131
	v_mov_b32_e32 v112, 0
	v_mov_b32_e32 v113, v131
	v_mov_b32_e32 v114, v131
	v_mov_b32_e32 v115, v131
	v_mov_b32_e32 v116, v131
	v_mov_b32_e32 v117, v131
	v_mov_b32_e32 v118, v131
	v_mov_b32_e32 v119, v131
	v_mov_b32_e32 v120, v131
	v_mov_b32_e32 v121, v131
	v_mov_b32_e32 v122, v131
	v_mov_b32_e32 v123, v131
	v_mov_b32_e32 v124, v131
	v_mov_b32_e32 v125, v131
	v_mov_b32_e32 v126, v131
	v_mov_b32_e32 v127, v131
	s_mov_b64 s[54:55], 0x80
	v_lshrrev_b32_e32 v174, 6, v180
	v_lshlrev_b32_e32 v184, 11, v174
	v_and_b32_e32 v170, 63, v180
	v_readfirstlane_b32 s53, v184
	v_lshrrev_b32_e32 v171, 5, v170
	v_bfe_u32 v172, v170, 1, 3
	v_xor_b32_e32 v172, v171, v172
	v_and_b32_e32 v173, 31, v170
	v_lshlrev_b32_e32 v173, 7, v173
	v_lshrrev_b32_e32 v173, 3, v170
	v_lshlrev_b32_e32 v184, 4, v173
	v_add_u32_e32 v185, 0x80, v184
	v_and_b32_e32 v173, 7, v170
	v_lshrrev_b32_e32 v171, 4, v170
	v_xor_b32_e32 v171, v173, v171
	v_lshrrev_b32_e32 v173, 5, v170
	v_sub_u32_e32 v190, v171, v173
	v_xor_b32_e32 v171, 4, v171
	v_add_u32_e32 v173, 2, v173
	v_sub_u32_e32 v192, v171, v173
	v_lshlrev_b32_e32 v190, 4, v190
	v_ashrrev_i32_e32 v191, 31, v190
	v_lshlrev_b32_e32 v192, 4, v192
	v_ashrrev_i32_e32 v193, 31, v192
	ds_bpermute_b32 v242, v184, v136
	ds_bpermute_b32 v243, v184, v137
	ds_bpermute_b32 v244, v185, v136
	ds_bpermute_b32 v245, v185, v137
	ds_bpermute_b32 v246, v184, v146
	ds_bpermute_b32 v247, v184, v147
	ds_bpermute_b32 v248, v185, v146
	ds_bpermute_b32 v249, v185, v147
	s_waitcnt lgkmcnt(0)
	ds_bpermute_b32 v178, v184, v138
	ds_bpermute_b32 v179, v184, v139
	ds_bpermute_b32 v186, v185, v138
	ds_bpermute_b32 v187, v185, v139
	ds_bpermute_b32 v234, v184, v140
	ds_bpermute_b32 v235, v184, v141
	ds_bpermute_b32 v236, v185, v140
	ds_bpermute_b32 v237, v185, v141
	ds_bpermute_b32 v238, v184, v142
	ds_bpermute_b32 v239, v184, v143
	ds_bpermute_b32 v240, v185, v142
	ds_bpermute_b32 v241, v185, v143
	ds_bpermute_b32 v136, v184, v144
	ds_bpermute_b32 v137, v184, v145
	ds_bpermute_b32 v146, v185, v144
	ds_bpermute_b32 v147, v185, v145
	s_waitcnt lgkmcnt(0)
	v_and_b32_e32 v173, 31, v170
	v_lshlrev_b32_e32 v173, 7, v173
	v_lshrrev_b32_e32 v171, 1, v174
	v_lshl_add_u32 v138, v171, 14, v173
	v_and_b32_e32 v171, 1, v174
	v_lshl_add_u32 v142, v171, 13, v173
	v_add_u32_e32 v142, 0x10000, v142
	v_xor_b32_e32 v173, 6, v172
	v_lshl_add_u32 v141, v173, 4, v138
	v_lshl_add_u32 v145, v173, 4, v142
	v_xor_b32_e32 v173, 4, v172
	v_lshl_add_u32 v140, v173, 4, v138
	v_lshl_add_u32 v144, v173, 4, v142
	v_xor_b32_e32 v173, 2, v172
	v_lshl_add_u32 v139, v173, 4, v138
	v_lshl_add_u32 v143, v173, 4, v142
	v_xor_b32_e32 v173, 0, v172
	v_lshl_add_u32 v138, v173, 4, v138
	v_lshl_add_u32 v142, v173, 4, v142
	v_lshl_add_u64 v[178:179], v[178:179], 0, v[190:191]
	v_lshl_add_u64 v[186:187], v[186:187], 0, v[192:193]
	v_lshl_add_u64 v[234:235], v[234:235], 0, v[190:191]
	v_lshl_add_u64 v[236:237], v[236:237], 0, v[192:193]
	v_lshl_add_u64 v[238:239], v[238:239], 0, v[190:191]
	v_lshl_add_u64 v[240:241], v[240:241], 0, v[192:193]
	v_lshl_add_u64 v[136:137], v[136:137], 0, v[190:191]
	v_lshl_add_u64 v[146:147], v[146:147], 0, v[192:193]
	v_lshl_add_u64 v[242:243], v[242:243], 0, v[190:191]
	v_lshl_add_u64 v[244:245], v[244:245], 0, v[192:193]
	v_lshl_add_u64 v[246:247], v[246:247], 0, v[190:191]
	v_lshl_add_u64 v[248:249], v[248:249], 0, v[192:193]
	s_mov_b32 s58, s53
	s_add_i32 m0, s58, 0x0
	s_nop 0
	global_load_lds_dwordx4 v[178:179], off
	s_add_i32 m0, s58, 0x400
	v_lshl_add_u64 v[178:179], v[178:179], 0, s[54:55]
	global_load_lds_dwordx4 v[186:187], off
	s_add_i32 m0, s58, 0x2000
	v_lshl_add_u64 v[186:187], v[186:187], 0, s[54:55]
	global_load_lds_dwordx4 v[234:235], off
	s_add_i32 m0, s58, 0x2400
	v_lshl_add_u64 v[234:235], v[234:235], 0, s[54:55]
	global_load_lds_dwordx4 v[236:237], off
	s_add_i32 m0, s58, 0x4000
	v_lshl_add_u64 v[236:237], v[236:237], 0, s[54:55]
	global_load_lds_dwordx4 v[238:239], off
	s_add_i32 m0, s58, 0x4400
	v_lshl_add_u64 v[238:239], v[238:239], 0, s[54:55]
	global_load_lds_dwordx4 v[240:241], off
	s_add_i32 m0, s58, 0x6000
	v_lshl_add_u64 v[240:241], v[240:241], 0, s[54:55]
	global_load_lds_dwordx4 v[136:137], off
	s_add_i32 m0, s58, 0x6400
	v_lshl_add_u64 v[136:137], v[136:137], 0, s[54:55]
	global_load_lds_dwordx4 v[146:147], off
	v_lshl_add_u64 v[146:147], v[146:147], 0, s[54:55]
	s_add_i32 s58, s53, 0x10000
	s_add_i32 m0, s58, 0x0
	s_nop 0
	global_load_lds_dwordx4 v[242:243], off
	s_add_i32 m0, s58, 0x400
	v_lshl_add_u64 v[242:243], v[242:243], 0, s[54:55]
	global_load_lds_dwordx4 v[244:245], off
	s_add_i32 m0, s58, 0x2000
	v_lshl_add_u64 v[244:245], v[244:245], 0, s[54:55]
	global_load_lds_dwordx4 v[246:247], off
	s_add_i32 m0, s58, 0x2400
	v_lshl_add_u64 v[246:247], v[246:247], 0, s[54:55]
	global_load_lds_dwordx4 v[248:249], off
	v_lshl_add_u64 v[248:249], v[248:249], 0, s[54:55]
	s_mov_b32 s16, 0
	s_mov_b32 s17, 0

.Lg_ph13_noB:
	s_waitcnt lgkmcnt(3)
	v_mfma_f32_32x32x16_bf16 v[0:15], v[170:173], v[194:197], v[0:15]
	v_mfma_f32_32x32x16_bf16 v[16:31], v[170:173], v[198:201], v[16:31]
	ds_read_b128 v[170:173], v139
	s_waitcnt lgkmcnt(3)
	v_mfma_f32_32x32x16_bf16 v[32:47], v[174:177], v[194:197], v[32:47]
	v_mfma_f32_32x32x16_bf16 v[48:63], v[174:177], v[198:201], v[48:63]
	ds_read_b128 v[174:177], v139 offset:4096
	s_waitcnt lgkmcnt(3)
	v_mfma_f32_32x32x16_bf16 v[64:79], v[182:185], v[194:197], v[64:79]
	v_mfma_f32_32x32x16_bf16 v[80:95], v[182:185], v[198:201], v[80:95]
	ds_read_b128 v[182:185], v139 offset:8192
	s_waitcnt lgkmcnt(3)
	v_mfma_f32_32x32x16_bf16 v[96:111], v[190:193], v[194:197], v[96:111]
	v_mfma_f32_32x32x16_bf16 v[112:127], v[190:193], v[198:201], v[112:127]
	ds_read_b128 v[190:193], v139 offset:12288
	s_waitcnt lgkmcnt(3)
	v_mfma_f32_32x32x16_bf16 v[0:15], v[170:173], v[202:205], v[0:15]
	v_mfma_f32_32x32x16_bf16 v[16:31], v[170:173], v[206:209], v[16:31]
	ds_read_b128 v[170:173], v140
	s_waitcnt lgkmcnt(3)
	v_mfma_f32_32x32x16_bf16 v[32:47], v[174:177], v[202:205], v[32:47]
	v_mfma_f32_32x32x16_bf16 v[48:63], v[174:177], v[206:209], v[48:63]
	ds_read_b128 v[174:177], v140 offset:4096
	s_waitcnt lgkmcnt(3)
	v_mfma_f32_32x32x16_bf16 v[64:79], v[182:185], v[202:205], v[64:79]
	v_mfma_f32_32x32x16_bf16 v[80:95], v[182:185], v[206:209], v[80:95]
	ds_read_b128 v[182:185], v140 offset:8192
	s_waitcnt lgkmcnt(3)
	v_mfma_f32_32x32x16_bf16 v[96:111], v[190:193], v[202:205], v[96:111]
	v_mfma_f32_32x32x16_bf16 v[112:127], v[190:193], v[206:209], v[112:127]
	ds_read_b128 v[190:193], v140 offset:12288
	s_waitcnt lgkmcnt(3)
	v_mfma_f32_32x32x16_bf16 v[0:15], v[170:173], v[214:217], v[0:15]
	v_mfma_f32_32x32x16_bf16 v[16:31], v[170:173], v[222:225], v[16:31]
	ds_read_b128 v[170:173], v141
	s_waitcnt lgkmcnt(3)
	v_mfma_f32_32x32x16_bf16 v[32:47], v[174:177], v[214:217], v[32:47]
	v_mfma_f32_32x32x16_bf16 v[48:63], v[174:177], v[222:225], v[48:63]
	ds_read_b128 v[174:177], v141 offset:4096
	s_waitcnt lgkmcnt(3)
	v_mfma_f32_32x32x16_bf16 v[64:79], v[182:185], v[214:217], v[64:79]
	v_mfma_f32_32x32x16_bf16 v[80:95], v[182:185], v[222:225], v[80:95]
	ds_read_b128 v[182:185], v141 offset:8192
	s_waitcnt lgkmcnt(3)
	v_mfma_f32_32x32x16_bf16 v[96:111], v[190:193], v[214:217], v[96:111]
	v_mfma_f32_32x32x16_bf16 v[112:127], v[190:193], v[222:225], v[112:127]
	ds_read_b128 v[190:193], v141 offset:12288
	s_waitcnt lgkmcnt(3)
	v_mfma_f32_32x32x16_bf16 v[0:15], v[170:173], v[226:229], v[0:15]
	v_mfma_f32_32x32x16_bf16 v[16:31], v[170:173], v[230:233], v[16:31]
	s_waitcnt lgkmcnt(2)
	v_mfma_f32_32x32x16_bf16 v[32:47], v[174:177], v[226:229], v[32:47]
	v_mfma_f32_32x32x16_bf16 v[48:63], v[174:177], v[230:233], v[48:63]
	s_waitcnt lgkmcnt(1)
	v_mfma_f32_32x32x16_bf16 v[64:79], v[182:185], v[226:229], v[64:79]
	v_mfma_f32_32x32x16_bf16 v[80:95], v[182:185], v[230:233], v[80:95]
	s_waitcnt lgkmcnt(0)
	v_mfma_f32_32x32x16_bf16 v[96:111], v[190:193], v[226:229], v[96:111]
	v_mfma_f32_32x32x16_bf16 v[112:127], v[190:193], v[230:233], v[112:127]
	v_xor_b32_e32 v138, 0x8000, v138
	v_xor_b32_e32 v139, 0x8000, v139
	v_xor_b32_e32 v140, 0x8000, v140
	v_xor_b32_e32 v141, 0x8000, v141
	s_xor_b32 s17, s17, 0x8000
	s_add_i32 s16, s16, 1
	s_cmp_eq_u32 s16, 16
	s_cbranch_scc0 .Lg_ph13_top
	s_waitcnt vmcnt(0)
	v_mov_b32_e32 v130, v180
	v_add_u32_e32 v202, 0x400, v153
	v_add_u32_e32 v201, 0x1000, v153
	v_add_u32_e32 v200, 0x1400, v153
	v_add_u32_e32 v199, 0x2000, v153
	v_add_u32_e32 v193, 0x2400, v153
	v_add_u32_e32 v194, 0x3000, v153
	v_add_u32_e32 v195, 0x3200, v153
	v_add_u32_e32 v196, 0x3400, v153
	v_add_u32_e32 v197, 0x3600, v153
	v_add_u32_e32 v198, 0x4000, v153
	v_add_u32_e32 v190, 0x4400, v153
	v_add_u32_e32 v191, 0x4800, v153
	v_add_u32_e32 v192, 0x5000, v153
	v_add_u32_e32 v186, 0x5400, v153
	v_add_u32_e32 v187, 0x5800, v153
	v_add_u32_e32 v189, 0x6000, v153
	v_add_u32_e32 v179, 0x6400, v153
	v_add_u32_e32 v181, 0x6800, v153
	v_add_u32_e32 v182, 0x7200, v153
	v_add_u32_e32 v183, 0x7400, v153
	v_add_u32_e32 v184, 0x7600, v153
	v_add_u32_e32 v185, 0x7800, v153
	v_add_u32_e32 v178, 0x8400, v153
	v_add_u32_e32 v177, 0x8800, v153
	v_add_u32_e32 v176, 0x9400, v153
	v_add_u32_e32 v175, 0x9800, v153
	v_add_u32_e32 v174, 0xa400, v153
	v_add_u32_e32 v147, 0xa800, v153
	v_add_u32_e32 v169, 0xb400, v153
	v_add_u32_e32 v170, 0xb600, v153
	v_add_u32_e32 v171, 0xb800, v153
	v_add_u32_e32 v172, 0xba00, v153
	s_waitcnt vmcnt(0)
	s_barrier
	s_and_saveexec_b64 s[16:17], s[6:7]
	s_cbranch_execz .LBB0_1319
	v_add_u32_e32 v136, 0xc400, v153
	ds_write2_b32 v153, v0, v16 offset1:32
	ds_write2_b32 v153, v1, v17 offset0:132 offset1:164
	ds_write2_b32 v202, v2, v18 offset0:8 offset1:40
	ds_write2_b32 v202, v3, v19 offset0:140 offset1:172
	ds_write2_b32 v201, v4, v20 offset0:32 offset1:64
	ds_write2_b32 v201, v5, v21 offset0:164 offset1:196
	ds_write2_b32 v200, v6, v22 offset0:40 offset1:72
	ds_write2_b32 v200, v7, v23 offset0:172 offset1:204
	ds_write2_b32 v199, v8, v24 offset0:64 offset1:96
	ds_write2_b32 v199, v9, v25 offset0:196 offset1:228
	ds_write2_b32 v193, v10, v26 offset0:72 offset1:104
	ds_write2_b32 v193, v11, v27 offset0:204 offset1:236
	ds_write2_b32 v194, v12, v28 offset0:96 offset1:128
	ds_write2_b32 v195, v13, v29 offset0:100 offset1:132
	ds_write2_b32 v196, v14, v30 offset0:104 offset1:136
	ds_write2_b32 v197, v15, v31 offset0:108 offset1:140
	ds_write2_b32 v198, v32, v48 offset0:128 offset1:160
	ds_write2_b32 v190, v33, v49 offset0:4 offset1:36
	ds_write2_b32 v190, v34, v50 offset0:136 offset1:168
	ds_write2_b32 v191, v35, v51 offset0:12 offset1:44
	ds_write2_b32 v192, v36, v52 offset0:160 offset1:192
	ds_write2_b32 v186, v37, v53 offset0:36 offset1:68
	ds_write2_b32 v186, v38, v54 offset0:168 offset1:200
	ds_write2_b32 v187, v39, v55 offset0:44 offset1:76
	ds_write2_b32 v189, v40, v56 offset0:192 offset1:224
	ds_write2_b32 v179, v41, v57 offset0:68 offset1:100
	ds_write2_b32 v179, v42, v58 offset0:200 offset1:232
	ds_write2_b32 v181, v43, v59 offset0:76 offset1:108
	ds_write2_b32 v182, v44, v60 offset0:96 offset1:128
	ds_write2_b32 v183, v45, v61 offset0:100 offset1:132
	ds_write2_b32 v184, v46, v62 offset0:104 offset1:136
	ds_write2_b32 v185, v47, v63 offset0:108 offset1:140
	ds_write2_b32 v178, v64, v80 offset1:32
	ds_write2_b32 v178, v65, v81 offset0:132 offset1:164
	ds_write2_b32 v177, v66, v82 offset0:8 offset1:40
	ds_write2_b32 v177, v67, v83 offset0:140 offset1:172
	ds_write2_b32 v176, v68, v84 offset0:32 offset1:64
	ds_write2_b32 v176, v69, v85 offset0:164 offset1:196
	ds_write2_b32 v175, v70, v86 offset0:40 offset1:72
	ds_write2_b32 v175, v71, v87 offset0:172 offset1:204
	ds_write2_b32 v174, v72, v88 offset0:64 offset1:96
	ds_write2_b32 v174, v73, v89 offset0:196 offset1:228
	ds_write2_b32 v147, v74, v90 offset0:72 offset1:104
	ds_write2_b32 v147, v75, v91 offset0:204 offset1:236
	ds_write2_b32 v169, v76, v92 offset0:96 offset1:128
	ds_write2_b32 v170, v77, v93 offset0:100 offset1:132
	ds_write2_b32 v171, v78, v94 offset0:104 offset1:136
	ds_write2_b32 v172, v79, v95 offset0:108 offset1:140
	ds_write2_b32 v136, v96, v112 offset0:128 offset1:160
	v_add_u32_e32 v136, 0xc800, v153
	ds_write2_b32 v136, v97, v113 offset0:4 offset1:36
	ds_write2_b32 v136, v98, v114 offset0:136 offset1:168
	v_add_u32_e32 v136, 0xcc00, v153
	ds_write2_b32 v136, v99, v115 offset0:12 offset1:44
	v_add_u32_e32 v136, 0xd400, v153
	ds_write2_b32 v136, v100, v116 offset0:160 offset1:192
	v_add_u32_e32 v136, 0xd800, v153
	ds_write2_b32 v136, v101, v117 offset0:36 offset1:68
	ds_write2_b32 v136, v102, v118 offset0:168 offset1:200
	v_add_u32_e32 v136, 0xdc00, v153
	ds_write2_b32 v136, v103, v119 offset0:44 offset1:76
	v_add_u32_e32 v136, 0xe400, v153
	ds_write2_b32 v136, v104, v120 offset0:192 offset1:224
	v_add_u32_e32 v136, 0xe800, v153
	ds_write2_b32 v136, v105, v121 offset0:68 offset1:100
	ds_write2_b32 v136, v106, v122 offset0:200 offset1:232
	v_add_u32_e32 v136, 0xec00, v153
	ds_write2_b32 v136, v107, v123 offset0:76 offset1:108
	v_add_u32_e32 v136, 0xf600, v153
	ds_write2_b32 v136, v108, v124 offset0:96 offset1:128
	v_add_u32_e32 v136, 0xf800, v153
	ds_write2_b32 v136, v109, v125 offset0:100 offset1:132
	v_add_u32_e32 v136, 0xfa00, v153
	ds_write2_b32 v136, v110, v126 offset0:104 offset1:136
	v_add_u32_e32 v136, 0xfc00, v153
	ds_write2_b32 v136, v111, v127 offset0:108 offset1:140

.LBB0_1322:
	v_cmp_lt_i32_e32 vcc, 14, v4
	s_and_saveexec_b64 s[2:3], vcc
	s_cbranch_execz .LBB0_1376
	s_waitcnt vmcnt(0)
	s_waitcnt lgkmcnt(0)
	v_mov_b32_e32 v254, 0x12000
	v_mov_b32_e32 v252, s97
	v_mov_b32_e32 v253, s96
	ds_write_b64 v254, v[252:253]
	s_waitcnt lgkmcnt(0)
	s_barrier
	s_mov_b64 s[4:5], exec
	v_readlane_b32 s6, v255, 5
	v_readlane_b32 s7, v255, 6
	s_and_b64 s[6:7], s[4:5], s[6:7]
	s_mov_b64 exec, s[6:7]
	s_cbranch_execz .LBB0_1375
	s_add_i32 s50, 0, 0x12000
	s_mov_b64 s[6:7], src_shared_base
	s_cmp_lg_u32 s50, -1
	s_cselect_b32 s6, s50, 0
	s_cselect_b32 s8, s7, 0
	s_add_i32 s51, 0, 0x12004
	s_cmp_lg_u32 s51, -1
	v_mov_b32_e32 v0, s6
	v_mov_b32_e32 v1, s8
	s_cselect_b32 s6, s51, 0
	s_cselect_b32 s7, s7, 0
	s_waitcnt vmcnt(0) expcnt(0) lgkmcnt(0)
	flat_load_dword v2, v[0:1] sc0 sc1
	s_waitcnt vmcnt(0)
	v_mov_b32_e32 v0, s6
	v_mov_b32_e32 v1, s7
	flat_load_dword v0, v[0:1] sc0 sc1
	s_waitcnt vmcnt(0) lgkmcnt(0)
	v_cmp_eq_u32_e32 vcc, 0, v2
	s_and_saveexec_b64 s[6:7], vcc
	s_cbranch_execz .LBB0_1339
	s_add_u32 s8, s94, 0x1d11e200
	s_addc_u32 s9, s95, 0
	s_add_u32 s10, s94, 0x1d11e400
	s_addc_u32 s11, s95, 0
	s_add_u32 s12, s94, 0x1d11e500
	s_addc_u32 s13, s95, 0
	s_add_u32 s14, s94, 0x1d11e600
	s_addc_u32 s15, s95, 0
	s_add_u32 s16, s94, 0x1d11e700
	s_addc_u32 s17, s95, 0
	s_add_u32 s18, s94, 0x1d11e800
	s_addc_u32 s19, s95, 0
	s_add_u32 s20, s94, 0x1d11e900
	s_addc_u32 s21, s95, 0
	s_add_u32 s22, s94, 0x1d11ea00
	s_addc_u32 s23, s95, 0
	s_add_u32 s24, s94, 0x1d11eb00
	s_addc_u32 s25, s95, 0
	s_add_u32 s26, s94, 0x1d11ec00
	s_addc_u32 s27, s95, 0
	s_add_u32 s28, s94, 0x1d11ed00
	s_addc_u32 s29, s95, 0
	s_add_u32 s30, s94, 0x1d11ee00
	s_addc_u32 s31, s95, 0
	s_add_u32 s34, s94, 0x1d11ef00
	s_addc_u32 s35, s95, 0
	s_add_u32 s36, s94, 0x1d11f000
	s_addc_u32 s37, s95, 0
	s_add_u32 s38, s94, 0x1d11f100
	s_addc_u32 s39, s95, 0
	s_add_u32 s40, s94, 0x1d11f200
	s_addc_u32 s41, s95, 0
	s_add_u32 s42, s94, 0x1d11f300
	s_addc_u32 s43, s95, 0
	s_mov_b32 s52, 1
	v_mov_b32_e32 v16, 0
	s_branch .LBB0_1327

.LBB0_1666:
	s_or_b64 exec, exec, s[26:27]
	v_readlane_b32 s0, v255, 4
	s_cmp_lt_i32 s0, 17
	s_cselect_b64 s[0:1], -1, 0
	v_cmp_lt_i32_e32 vcc, 16, v4
	s_and_b64 s[2:3], s[0:1], vcc
	s_and_saveexec_b64 s[0:1], s[2:3]
	s_cbranch_execz .LBB0_1732
	v_mov_b32_e32 v254, 0x12000
	ds_read_b64 v[252:253], v254
	s_waitcnt lgkmcnt(0)
	v_readfirstlane_b32 s97, v252
	v_readfirstlane_b32 s96, v253
	v_readlane_b32 s2, v255, 0
	s_cmpk_gt_u32 s2, 0x7ff
	v_readlane_b32 s3, v255, 1
	s_cbranch_scc1 .LBB0_1677
	v_lshrrev_b32_e32 v2, 4, v180
	v_xor_b32_e32 v2, v2, v180
	v_lshlrev_b32_e32 v2, 3, v2
	v_and_b32_e32 v147, 24, v2
	v_lshlrev_b32_e32 v2, 4, v180
	s_add_u32 s2, s94, 0x1cfde000
	v_lshrrev_b32_e32 v0, 5, v180
	v_and_b32_e32 v2, 0x3c00, v2
	v_bfe_u32 v3, v180, 2, 2
	s_addc_u32 s3, s95, 0
	v_add_u32_e32 v148, 0, v2
	v_bfe_u32 v2, v180, 5, 1
	v_bitop3_b32 v0, v0, v3, 1 bitop3:0x6c
	s_add_u32 s4, s94, 0x16ede000
	v_lshlrev_b32_e32 v149, 4, v0
	v_bitop3_b32 v0, v2, v3, 2 bitop3:0x36
	s_addc_u32 s5, s95, 0
	v_and_b32_e32 v1, 31, v180
	v_lshlrev_b32_e32 v150, 4, v0
	v_lshlrev_b32_e32 v0, 6, v180
	v_and_b32_e32 v3, 64, v180
	v_lshrrev_b32_e32 v146, 2, v180
	s_add_u32 s16, s94, 0xcede000
	v_readlane_b32 s6, v255, 0
	v_and_b32_e32 v151, 0xe7c0, v0
	v_and_b32_e32 v152, 0x17c0, v0
	v_lshrrev_b32_e32 v0, 3, v180
	v_lshlrev_b32_e32 v3, 2, v3
	v_lshlrev_b32_e32 v1, 2, v1
	s_addc_u32 s17, s95, 0
	v_readlane_b32 s7, v255, 1
	s_lshr_b32 s19, s6, 3
	s_bfe_u32 s20, s6, 0x20001
	s_lshl_b32 s6, s6, 3
	v_add3_u32 v3, 0, v3, v1
	s_movk_i32 s8, 0x80
	s_movk_i32 s9, 0x840
	v_and_b32_e32 v1, 0x380, v180
	v_or_b32_e32 v0, 0x7b, v0
	v_lshlrev_b32_e32 v128, 11, v146
	v_mov_b32_e32 v129, 0
	s_and_b32 s21, s6, 8
	v_cmp_gt_u32_e64 s[6:7], s8, v180
	v_mad_u32_u24 v153, v2, s9, v3
	v_cmp_eq_u32_e64 s[8:9], s8, v1
	v_mul_u32_u24_e32 v2, 0x210, v0
	v_lshl_add_u64 v[0:1], s[94:95], 0, v[128:129]
	v_lshlrev_b32_e32 v128, 1, v147
	v_lshl_add_u64 v[0:1], v[0:1], 0, v[128:129]
	s_waitcnt lgkmcnt(0)
	s_mov_b64 s[12:13], 0xca0000
	v_lshl_add_u64 v[130:131], v[0:1], 0, s[12:13]
	s_mov_b64 s[12:13], 0x4ca0000
	s_lshr_b32 s18, s33, 3
	s_mov_b32 s11, 0
	s_movk_i32 s22, 0x210
	v_lshl_add_u64 v[132:133], v[0:1], 0, s[12:13]
	v_add_u32_e32 v154, 0x1000, v148
	v_add_u32_e32 v155, 0x2000, v148
	v_add_u32_e32 v156, 0x3000, v148
	v_add_u32_e32 v157, 0x4000, v148
	v_add_u32_e32 v158, 0x5000, v148
	v_add_u32_e32 v159, 0x6000, v148
	v_add_u32_e32 v160, 0x7000, v148
	v_add_u32_e32 v161, 0x8000, v148
	v_add_u32_e32 v162, 0x9000, v148
	v_add_u32_e32 v163, 0xa000, v148
	v_add_u32_e32 v164, 0xb000, v148
	s_mov_b64 s[12:13], 0x80
	s_mov_b32 s23, 0x20000
	v_add_u32_e32 v165, v3, v2
	s_mov_b32 s24, 0x40000
	s_mov_b32 s25, 0x60000
	s_branch .LBB0_1670

.LBB0_1670:
	s_lshr_b32 s10, s19, 4
	s_and_b32 s10, s10, 12
	s_bfe_u32 s15, s19, 0x20001
	s_or_b32 s10, s10, s20
	s_lshl_b32 s14, s15, 4
	s_and_b32 s26, s19, 1
	s_or_b32 s27, s14, s10
	s_lshl_b32 s14, s27, 9
	s_lshl_b32 s28, s26, 8
	s_or_b32 s14, s14, s28
	v_or_b32_e32 v0, s14, v146
	v_lshlrev_b32_e32 v0, 2, v0
	global_load_dword v2, v0, s[2:3]
	global_load_dword v4, v0, s[2:3] offset:256
	global_load_dword v10, v0, s[2:3] offset:512
	global_load_dword v11, v0, s[2:3] offset:768
	s_lshl_b32 s15, s15, 22
	s_bfe_u32 s28, s19, 0x30003
	v_readfirstlane_b32 s29, v148
	v_readfirstlane_b32 s30, v154
	s_or_b32 s28, s28, s21
	s_mov_b32 m0, s29
	v_readfirstlane_b32 s31, v155
	s_lshl_b32 s43, s28, 17
	s_lshl_b32 s10, s10, 21
	s_waitcnt vmcnt(0)
	s_barrier
	v_readfirstlane_b32 s34, v156
	s_or_b32 s10, s10, s43
	v_readfirstlane_b32 s35, v157
	s_bitset1_b32 s10, 25
	v_readfirstlane_b32 s36, v158
	v_lshl_add_u64 v[134:135], v[130:131], 0, s[10:11]
	v_mov_b32_e32 v1, v129
	v_readfirstlane_b32 s37, v159
	v_lshl_add_u64 v[136:137], v[132:133], 0, s[10:11]
	v_mov_b32_e32 v3, v129
	v_readfirstlane_b32 s38, v160
	v_mov_b32_e32 v5, v129
	v_readfirstlane_b32 s39, v161
	v_readfirstlane_b32 s40, v162
	v_readfirstlane_b32 s41, v163
	v_readfirstlane_b32 s42, v164
	v_lshl_add_u64 v[6:7], v[134:135], 0, 64
	v_lshl_add_u64 v[8:9], v[136:137], 0, 64
	s_mov_b32 s14, s11
	s_mov_b32 s29, s11
	v_mov_b32_e32 v16, 0
	v_mov_b32_e32 v17, v129
	v_mov_b32_e32 v18, v129
	v_mov_b32_e32 v19, v129
	v_mov_b32_e32 v20, v129
	v_mov_b32_e32 v21, v129
	v_mov_b32_e32 v22, v129
	v_mov_b32_e32 v23, v129
	v_mov_b32_e32 v24, v129
	v_mov_b32_e32 v25, v129
	v_mov_b32_e32 v26, v129
	v_mov_b32_e32 v27, v129
	v_mov_b32_e32 v28, v129
	v_mov_b32_e32 v29, v129
	v_mov_b32_e32 v30, v129
	v_mov_b32_e32 v31, v129
	v_mov_b32_e32 v32, 0
	v_mov_b32_e32 v33, v129
	v_mov_b32_e32 v34, v129
	v_mov_b32_e32 v35, v129
	v_mov_b32_e32 v36, v129
	v_mov_b32_e32 v37, v129
	v_mov_b32_e32 v38, v129
	v_mov_b32_e32 v39, v129
	v_mov_b32_e32 v40, v129
	v_mov_b32_e32 v41, v129
	v_mov_b32_e32 v42, v129
	v_mov_b32_e32 v43, v129
	v_mov_b32_e32 v44, v129
	v_mov_b32_e32 v45, v129
	v_mov_b32_e32 v46, v129
	v_mov_b32_e32 v47, v129
	v_mov_b32_e32 v48, 0
	v_mov_b32_e32 v49, v129
	v_mov_b32_e32 v50, v129
	v_mov_b32_e32 v51, v129
	v_mov_b32_e32 v52, v129
	v_mov_b32_e32 v53, v129
	v_mov_b32_e32 v54, v129
	v_mov_b32_e32 v55, v129
	v_mov_b32_e32 v56, v129
	v_mov_b32_e32 v57, v129
	v_mov_b32_e32 v58, v129
	s_waitcnt vmcnt(3)
	v_lshl_add_u32 v0, v2, 10, s15
	s_waitcnt vmcnt(2)
	v_lshl_add_u32 v2, v4, 10, s15
	v_or_b32_e32 v0, v0, v147
	s_waitcnt vmcnt(1)
	v_lshl_add_u32 v4, v10, 10, s15
	v_or_b32_e32 v2, v2, v147
	v_lshlrev_b32_e32 v128, 1, v0
	s_waitcnt vmcnt(0)
	v_lshl_add_u32 v10, v11, 10, s15
	v_or_b32_e32 v4, v4, v147
	v_lshlrev_b32_e32 v0, 1, v2
	s_nop 0
	s_mov_b32 m0, s30
	v_or_b32_e32 v10, v10, v147
	v_lshlrev_b32_e32 v2, 1, v4
	s_nop 0
	s_mov_b32 m0, s31
	v_lshlrev_b32_e32 v4, 1, v10
	s_nop 0
	s_mov_b32 m0, s34
	v_lshl_add_u64 v[138:139], s[4:5], 0, v[128:129]
	s_nop 0
	s_mov_b32 m0, s35
	v_lshl_add_u64 v[140:141], s[4:5], 0, v[0:1]
	s_nop 0
	s_mov_b32 m0, s36
	v_lshl_add_u64 v[0:1], v[138:139], 0, 64
	s_nop 0
	s_mov_b32 m0, s37
	v_lshl_add_u64 v[142:143], s[4:5], 0, v[2:3]
	v_lshl_add_u64 v[10:11], v[140:141], 0, 64
	s_nop 0
	s_mov_b32 m0, s38
	v_lshl_add_u64 v[144:145], s[4:5], 0, v[4:5]
	v_lshl_add_u64 v[12:13], v[142:143], 0, 64
	s_nop 0
	s_mov_b32 m0, s39
	v_lshl_add_u64 v[14:15], v[144:145], 0, 64
	s_nop 0
	s_mov_b32 m0, s40
	s_mov_b32 s15, 2
	s_nop 0
	s_mov_b32 m0, s41
	v_mov_b32_e32 v0, 0
	s_nop 0
	s_mov_b32 m0, s42
	v_mov_b32_e32 v1, v129
	s_nop 0
	v_mov_b32_e32 v2, v129
	v_mov_b32_e32 v4, v129
	v_mov_b32_e32 v6, v129
	v_mov_b32_e32 v7, v129
	v_mov_b32_e32 v8, v129
	v_mov_b32_e32 v9, v129
	v_mov_b32_e32 v10, v129
	v_mov_b32_e32 v11, v129
	v_mov_b32_e32 v12, v129
	v_mov_b32_e32 v13, v129
	v_mov_b32_e32 v14, v129
	v_mov_b32_e32 v15, v129
	v_mov_b32_e32 v59, v129
	v_mov_b32_e32 v60, v129
	v_mov_b32_e32 v61, v129
	v_mov_b32_e32 v62, v129
	v_mov_b32_e32 v63, v129
	v_mov_b32_e32 v64, 0
	v_mov_b32_e32 v65, v129
	v_mov_b32_e32 v66, v129
	v_mov_b32_e32 v67, v129
	v_mov_b32_e32 v68, v129
	v_mov_b32_e32 v69, v129
	v_mov_b32_e32 v70, v129
	v_mov_b32_e32 v71, v129
	v_mov_b32_e32 v72, v129
	v_mov_b32_e32 v73, v129
	v_mov_b32_e32 v74, v129
	v_mov_b32_e32 v75, v129
	v_mov_b32_e32 v76, v129
	v_mov_b32_e32 v77, v129
	v_mov_b32_e32 v78, v129
	v_mov_b32_e32 v79, v129
	v_mov_b32_e32 v80, 0
	v_mov_b32_e32 v81, v129
	v_mov_b32_e32 v82, v129
	v_mov_b32_e32 v83, v129
	v_mov_b32_e32 v84, v129
	v_mov_b32_e32 v85, v129
	v_mov_b32_e32 v86, v129
	v_mov_b32_e32 v87, v129
	v_mov_b32_e32 v88, v129
	v_mov_b32_e32 v89, v129
	v_mov_b32_e32 v90, v129
	v_mov_b32_e32 v91, v129
	v_mov_b32_e32 v92, v129
	v_mov_b32_e32 v93, v129
	v_mov_b32_e32 v94, v129
	v_mov_b32_e32 v95, v129
	v_mov_b32_e32 v96, 0
	v_mov_b32_e32 v97, v129
	v_mov_b32_e32 v98, v129
	v_mov_b32_e32 v99, v129
	v_mov_b32_e32 v100, v129
	v_mov_b32_e32 v101, v129
	v_mov_b32_e32 v102, v129
	v_mov_b32_e32 v103, v129
	v_mov_b32_e32 v104, v129
	v_mov_b32_e32 v105, v129
	v_mov_b32_e32 v106, v129
	v_mov_b32_e32 v107, v129
	v_mov_b32_e32 v108, v129
	v_mov_b32_e32 v109, v129
	v_mov_b32_e32 v110, v129
	v_mov_b32_e32 v111, v129
	v_mov_b32_e32 v112, 0
	v_mov_b32_e32 v113, v129
	v_mov_b32_e32 v114, v129
	v_mov_b32_e32 v115, v129
	v_mov_b32_e32 v116, v129
	v_mov_b32_e32 v117, v129
	v_mov_b32_e32 v118, v129
	v_mov_b32_e32 v119, v129
	v_mov_b32_e32 v120, v129
	v_mov_b32_e32 v121, v129
	v_mov_b32_e32 v122, v129
	v_mov_b32_e32 v123, v129
	v_mov_b32_e32 v124, v129
	v_mov_b32_e32 v125, v129
	v_mov_b32_e32 v126, v129
	v_mov_b32_e32 v127, v129
	s_mov_b64 s[54:55], 0x80
	v_lshrrev_b32_e32 v170, 6, v180
	v_lshlrev_b32_e32 v176, 11, v170
	v_and_b32_e32 v166, 63, v180
	v_readfirstlane_b32 s53, v176
	v_lshrrev_b32_e32 v167, 5, v166
	v_bfe_u32 v168, v166, 1, 3
	v_xor_b32_e32 v168, v167, v168
	v_and_b32_e32 v169, 31, v166
	v_lshlrev_b32_e32 v169, 7, v169
	v_lshrrev_b32_e32 v169, 3, v166
	v_lshlrev_b32_e32 v176, 4, v169
	v_add_u32_e32 v177, 0x80, v176
	v_and_b32_e32 v169, 7, v166
	v_lshrrev_b32_e32 v167, 4, v166
	v_xor_b32_e32 v167, v169, v167
	v_lshrrev_b32_e32 v169, 5, v166
	v_sub_u32_e32 v182, v167, v169
	v_xor_b32_e32 v167, 4, v167
	v_add_u32_e32 v169, 2, v169
	v_sub_u32_e32 v184, v167, v169
	v_lshlrev_b32_e32 v182, 4, v182
	v_ashrrev_i32_e32 v183, 31, v182
	v_lshlrev_b32_e32 v184, 4, v184
	v_ashrrev_i32_e32 v185, 31, v184
	ds_bpermute_b32 v240, v176, v134
	ds_bpermute_b32 v241, v176, v135
	ds_bpermute_b32 v242, v177, v134
	ds_bpermute_b32 v243, v177, v135
	ds_bpermute_b32 v244, v176, v136
	ds_bpermute_b32 v245, v176, v137
	ds_bpermute_b32 v246, v177, v136
	ds_bpermute_b32 v247, v177, v137
	s_waitcnt lgkmcnt(0)
	ds_bpermute_b32 v178, v176, v138
	ds_bpermute_b32 v179, v176, v139
	ds_bpermute_b32 v230, v177, v138
	ds_bpermute_b32 v231, v177, v139
	ds_bpermute_b32 v232, v176, v140
	ds_bpermute_b32 v233, v176, v141
	ds_bpermute_b32 v234, v177, v140
	ds_bpermute_b32 v235, v177, v141
	ds_bpermute_b32 v236, v176, v142
	ds_bpermute_b32 v237, v176, v143
	ds_bpermute_b32 v238, v177, v142
	ds_bpermute_b32 v239, v177, v143
	ds_bpermute_b32 v134, v176, v144
	ds_bpermute_b32 v135, v176, v145
	ds_bpermute_b32 v136, v177, v144
	ds_bpermute_b32 v137, v177, v145
	s_waitcnt lgkmcnt(0)
	v_and_b32_e32 v169, 31, v166
	v_lshlrev_b32_e32 v169, 7, v169
	v_lshrrev_b32_e32 v167, 1, v170
	v_lshl_add_u32 v138, v167, 14, v169
	v_and_b32_e32 v167, 1, v170
	v_lshl_add_u32 v142, v167, 13, v169
	v_add_u32_e32 v142, 0x10000, v142
	v_xor_b32_e32 v169, 6, v168
	v_lshl_add_u32 v141, v169, 4, v138
	v_lshl_add_u32 v145, v169, 4, v142
	v_xor_b32_e32 v169, 4, v168
	v_lshl_add_u32 v140, v169, 4, v138
	v_lshl_add_u32 v144, v169, 4, v142
	v_xor_b32_e32 v169, 2, v168
	v_lshl_add_u32 v139, v169, 4, v138
	v_lshl_add_u32 v143, v169, 4, v142
	v_xor_b32_e32 v169, 0, v168
	v_lshl_add_u32 v138, v169, 4, v138
	v_lshl_add_u32 v142, v169, 4, v142
	v_lshl_add_u64 v[178:179], v[178:179], 0, v[182:183]
	v_lshl_add_u64 v[230:231], v[230:231], 0, v[184:185]
	v_lshl_add_u64 v[232:233], v[232:233], 0, v[182:183]
	v_lshl_add_u64 v[234:235], v[234:235], 0, v[184:185]
	v_lshl_add_u64 v[236:237], v[236:237], 0, v[182:183]
	v_lshl_add_u64 v[238:239], v[238:239], 0, v[184:185]
	v_lshl_add_u64 v[134:135], v[134:135], 0, v[182:183]
	v_lshl_add_u64 v[136:137], v[136:137], 0, v[184:185]
	v_lshl_add_u64 v[240:241], v[240:241], 0, v[182:183]
	v_lshl_add_u64 v[242:243], v[242:243], 0, v[184:185]
	v_lshl_add_u64 v[244:245], v[244:245], 0, v[182:183]
	v_lshl_add_u64 v[246:247], v[246:247], 0, v[184:185]
	s_mov_b32 s58, s53
	s_add_i32 m0, s58, 0x0
	s_nop 0
	global_load_lds_dwordx4 v[178:179], off
	s_add_i32 m0, s58, 0x400
	v_lshl_add_u64 v[178:179], v[178:179], 0, s[54:55]
	global_load_lds_dwordx4 v[230:231], off
	s_add_i32 m0, s58, 0x2000
	v_lshl_add_u64 v[230:231], v[230:231], 0, s[54:55]
	global_load_lds_dwordx4 v[232:233], off
	s_add_i32 m0, s58, 0x2400
	v_lshl_add_u64 v[232:233], v[232:233], 0, s[54:55]
	global_load_lds_dwordx4 v[234:235], off
	s_add_i32 m0, s58, 0x4000
	v_lshl_add_u64 v[234:235], v[234:235], 0, s[54:55]
	global_load_lds_dwordx4 v[236:237], off
	s_add_i32 m0, s58, 0x4400
	v_lshl_add_u64 v[236:237], v[236:237], 0, s[54:55]
	global_load_lds_dwordx4 v[238:239], off
	s_add_i32 m0, s58, 0x6000
	v_lshl_add_u64 v[238:239], v[238:239], 0, s[54:55]
	global_load_lds_dwordx4 v[134:135], off
	s_add_i32 m0, s58, 0x6400
	v_lshl_add_u64 v[134:135], v[134:135], 0, s[54:55]
	global_load_lds_dwordx4 v[136:137], off
	v_lshl_add_u64 v[136:137], v[136:137], 0, s[54:55]
	s_add_i32 s58, s53, 0x10000
	s_add_i32 m0, s58, 0x0
	s_nop 0
	global_load_lds_dwordx4 v[240:241], off
	s_add_i32 m0, s58, 0x400
	v_lshl_add_u64 v[240:241], v[240:241], 0, s[54:55]
	global_load_lds_dwordx4 v[242:243], off
	s_add_i32 m0, s58, 0x2000
	v_lshl_add_u64 v[242:243], v[242:243], 0, s[54:55]
	global_load_lds_dwordx4 v[244:245], off
	s_add_i32 m0, s58, 0x2400
	v_lshl_add_u64 v[244:245], v[244:245], 0, s[54:55]
	global_load_lds_dwordx4 v[246:247], off
	v_lshl_add_u64 v[246:247], v[246:247], 0, s[54:55]
	s_mov_b32 s14, 0
	s_mov_b32 s15, 0

.Lg_ph16_noB:
	s_waitcnt lgkmcnt(3)
	v_mfma_f32_32x32x16_bf16 v[0:15], v[166:169], v[186:189], v[0:15]
	v_mfma_f32_32x32x16_bf16 v[16:31], v[166:169], v[190:193], v[16:31]
	ds_read_b128 v[166:169], v139
	s_waitcnt lgkmcnt(3)
	v_mfma_f32_32x32x16_bf16 v[32:47], v[170:173], v[186:189], v[32:47]
	v_mfma_f32_32x32x16_bf16 v[48:63], v[170:173], v[190:193], v[48:63]
	ds_read_b128 v[170:173], v139 offset:4096
	s_waitcnt lgkmcnt(3)
	v_mfma_f32_32x32x16_bf16 v[64:79], v[174:177], v[186:189], v[64:79]
	v_mfma_f32_32x32x16_bf16 v[80:95], v[174:177], v[190:193], v[80:95]
	ds_read_b128 v[174:177], v139 offset:8192
	s_waitcnt lgkmcnt(3)
	v_mfma_f32_32x32x16_bf16 v[96:111], v[182:185], v[186:189], v[96:111]
	v_mfma_f32_32x32x16_bf16 v[112:127], v[182:185], v[190:193], v[112:127]
	ds_read_b128 v[182:185], v139 offset:12288
	s_waitcnt lgkmcnt(3)
	v_mfma_f32_32x32x16_bf16 v[0:15], v[166:169], v[194:197], v[0:15]
	v_mfma_f32_32x32x16_bf16 v[16:31], v[166:169], v[198:201], v[16:31]
	ds_read_b128 v[166:169], v140
	s_waitcnt lgkmcnt(3)
	v_mfma_f32_32x32x16_bf16 v[32:47], v[170:173], v[194:197], v[32:47]
	v_mfma_f32_32x32x16_bf16 v[48:63], v[170:173], v[198:201], v[48:63]
	ds_read_b128 v[170:173], v140 offset:4096
	s_waitcnt lgkmcnt(3)
	v_mfma_f32_32x32x16_bf16 v[64:79], v[174:177], v[194:197], v[64:79]
	v_mfma_f32_32x32x16_bf16 v[80:95], v[174:177], v[198:201], v[80:95]
	ds_read_b128 v[174:177], v140 offset:8192
	s_waitcnt lgkmcnt(3)
	v_mfma_f32_32x32x16_bf16 v[96:111], v[182:185], v[194:197], v[96:111]
	v_mfma_f32_32x32x16_bf16 v[112:127], v[182:185], v[198:201], v[112:127]
	ds_read_b128 v[182:185], v140 offset:12288
	s_waitcnt lgkmcnt(3)
	v_mfma_f32_32x32x16_bf16 v[0:15], v[166:169], v[202:205], v[0:15]
	v_mfma_f32_32x32x16_bf16 v[16:31], v[166:169], v[218:221], v[16:31]
	ds_read_b128 v[166:169], v141
	s_waitcnt lgkmcnt(3)
	v_mfma_f32_32x32x16_bf16 v[32:47], v[170:173], v[202:205], v[32:47]
	v_mfma_f32_32x32x16_bf16 v[48:63], v[170:173], v[218:221], v[48:63]
	ds_read_b128 v[170:173], v141 offset:4096
	s_waitcnt lgkmcnt(3)
	v_mfma_f32_32x32x16_bf16 v[64:79], v[174:177], v[202:205], v[64:79]
	v_mfma_f32_32x32x16_bf16 v[80:95], v[174:177], v[218:221], v[80:95]
	ds_read_b128 v[174:177], v141 offset:8192
	s_waitcnt lgkmcnt(3)
	v_mfma_f32_32x32x16_bf16 v[96:111], v[182:185], v[202:205], v[96:111]
	v_mfma_f32_32x32x16_bf16 v[112:127], v[182:185], v[218:221], v[112:127]
	ds_read_b128 v[182:185], v141 offset:12288
	s_waitcnt lgkmcnt(3)
	v_mfma_f32_32x32x16_bf16 v[0:15], v[166:169], v[222:225], v[0:15]
	v_mfma_f32_32x32x16_bf16 v[16:31], v[166:169], v[226:229], v[16:31]
	s_waitcnt lgkmcnt(2)
	v_mfma_f32_32x32x16_bf16 v[32:47], v[170:173], v[222:225], v[32:47]
	v_mfma_f32_32x32x16_bf16 v[48:63], v[170:173], v[226:229], v[48:63]
	s_waitcnt lgkmcnt(1)
	v_mfma_f32_32x32x16_bf16 v[64:79], v[174:177], v[222:225], v[64:79]
	v_mfma_f32_32x32x16_bf16 v[80:95], v[174:177], v[226:229], v[80:95]
	s_waitcnt lgkmcnt(0)
	v_mfma_f32_32x32x16_bf16 v[96:111], v[182:185], v[222:225], v[96:111]
	v_mfma_f32_32x32x16_bf16 v[112:127], v[182:185], v[226:229], v[112:127]
	v_xor_b32_e32 v138, 0x8000, v138
	v_xor_b32_e32 v139, 0x8000, v139
	v_xor_b32_e32 v140, 0x8000, v140
	v_xor_b32_e32 v141, 0x8000, v141
	s_xor_b32 s15, s15, 0x8000
	s_add_i32 s14, s14, 1
	s_cmp_eq_u32 s14, 16
	s_cbranch_scc0 .Lg_ph16_top
	s_waitcnt vmcnt(0)
	v_mov_b32_e32 v128, v180
	v_add_u32_e32 v192, 0x400, v153
	v_add_u32_e32 v191, 0x1000, v153
	v_add_u32_e32 v190, 0x1400, v153
	v_add_u32_e32 v189, 0x2000, v153
	v_add_u32_e32 v183, 0x2400, v153
	v_add_u32_e32 v184, 0x3000, v153
	v_add_u32_e32 v185, 0x3200, v153
	v_add_u32_e32 v186, 0x3400, v153
	v_add_u32_e32 v187, 0x3600, v153
	v_add_u32_e32 v188, 0x4000, v153
	v_add_u32_e32 v179, 0x4400, v153
	v_add_u32_e32 v181, 0x4800, v153
	v_add_u32_e32 v182, 0x5000, v153
	v_add_u32_e32 v176, 0x5400, v153
	v_add_u32_e32 v177, 0x5800, v153
	v_add_u32_e32 v178, 0x6000, v153
	v_add_u32_e32 v170, 0x6400, v153
	v_add_u32_e32 v171, 0x6800, v153
	v_add_u32_e32 v172, 0x7200, v153
	v_add_u32_e32 v173, 0x7400, v153
	v_add_u32_e32 v174, 0x7600, v153
	v_add_u32_e32 v175, 0x7800, v153
	v_add_u32_e32 v169, 0x8400, v153
	v_add_u32_e32 v168, 0x8800, v153
	v_add_u32_e32 v167, 0x9400, v153
	v_add_u32_e32 v166, 0x9800, v153
	v_add_u32_e32 v145, 0xa400, v153
	v_add_u32_e32 v140, 0xa800, v153
	v_add_u32_e32 v141, 0xb400, v153
	v_add_u32_e32 v142, 0xb600, v153
	v_add_u32_e32 v143, 0xb800, v153
	v_add_u32_e32 v144, 0xba00, v153
	s_waitcnt vmcnt(0)
	s_barrier
	s_and_saveexec_b64 s[14:15], s[6:7]
	s_cbranch_execz .LBB0_1674
	v_add_u32_e32 v134, 0xc400, v153
	ds_write2_b32 v153, v0, v16 offset1:32
	ds_write2_b32 v153, v1, v17 offset0:132 offset1:164
	ds_write2_b32 v192, v2, v18 offset0:8 offset1:40
	ds_write2_b32 v192, v3, v19 offset0:140 offset1:172
	ds_write2_b32 v191, v4, v20 offset0:32 offset1:64
	ds_write2_b32 v191, v5, v21 offset0:164 offset1:196
	ds_write2_b32 v190, v6, v22 offset0:40 offset1:72
	ds_write2_b32 v190, v7, v23 offset0:172 offset1:204
	ds_write2_b32 v189, v8, v24 offset0:64 offset1:96
	ds_write2_b32 v189, v9, v25 offset0:196 offset1:228
	ds_write2_b32 v183, v10, v26 offset0:72 offset1:104
	ds_write2_b32 v183, v11, v27 offset0:204 offset1:236
	ds_write2_b32 v184, v12, v28 offset0:96 offset1:128
	ds_write2_b32 v185, v13, v29 offset0:100 offset1:132
	ds_write2_b32 v186, v14, v30 offset0:104 offset1:136
	ds_write2_b32 v187, v15, v31 offset0:108 offset1:140
	ds_write2_b32 v188, v32, v48 offset0:128 offset1:160
	ds_write2_b32 v179, v33, v49 offset0:4 offset1:36
	ds_write2_b32 v179, v34, v50 offset0:136 offset1:168
	ds_write2_b32 v181, v35, v51 offset0:12 offset1:44
	ds_write2_b32 v182, v36, v52 offset0:160 offset1:192
	ds_write2_b32 v176, v37, v53 offset0:36 offset1:68
	ds_write2_b32 v176, v38, v54 offset0:168 offset1:200
	ds_write2_b32 v177, v39, v55 offset0:44 offset1:76
	ds_write2_b32 v178, v40, v56 offset0:192 offset1:224
	ds_write2_b32 v170, v41, v57 offset0:68 offset1:100
	ds_write2_b32 v170, v42, v58 offset0:200 offset1:232
	ds_write2_b32 v171, v43, v59 offset0:76 offset1:108
	ds_write2_b32 v172, v44, v60 offset0:96 offset1:128
	ds_write2_b32 v173, v45, v61 offset0:100 offset1:132
	ds_write2_b32 v174, v46, v62 offset0:104 offset1:136
	ds_write2_b32 v175, v47, v63 offset0:108 offset1:140
	ds_write2_b32 v169, v64, v80 offset1:32
	ds_write2_b32 v169, v65, v81 offset0:132 offset1:164
	ds_write2_b32 v168, v66, v82 offset0:8 offset1:40
	ds_write2_b32 v168, v67, v83 offset0:140 offset1:172
	ds_write2_b32 v167, v68, v84 offset0:32 offset1:64
	ds_write2_b32 v167, v69, v85 offset0:164 offset1:196
	ds_write2_b32 v166, v70, v86 offset0:40 offset1:72
	ds_write2_b32 v166, v71, v87 offset0:172 offset1:204
	ds_write2_b32 v145, v72, v88 offset0:64 offset1:96
	ds_write2_b32 v145, v73, v89 offset0:196 offset1:228
	ds_write2_b32 v140, v74, v90 offset0:72 offset1:104
	ds_write2_b32 v140, v75, v91 offset0:204 offset1:236
	ds_write2_b32 v141, v76, v92 offset0:96 offset1:128
	ds_write2_b32 v142, v77, v93 offset0:100 offset1:132
	ds_write2_b32 v143, v78, v94 offset0:104 offset1:136
	ds_write2_b32 v144, v79, v95 offset0:108 offset1:140
	ds_write2_b32 v134, v96, v112 offset0:128 offset1:160
	v_add_u32_e32 v134, 0xc800, v153
	ds_write2_b32 v134, v97, v113 offset0:4 offset1:36
	ds_write2_b32 v134, v98, v114 offset0:136 offset1:168
	v_add_u32_e32 v134, 0xcc00, v153
	ds_write2_b32 v134, v99, v115 offset0:12 offset1:44
	v_add_u32_e32 v134, 0xd400, v153
	ds_write2_b32 v134, v100, v116 offset0:160 offset1:192
	v_add_u32_e32 v134, 0xd800, v153
	ds_write2_b32 v134, v101, v117 offset0:36 offset1:68
	ds_write2_b32 v134, v102, v118 offset0:168 offset1:200
	v_add_u32_e32 v134, 0xdc00, v153
	ds_write2_b32 v134, v103, v119 offset0:44 offset1:76
	v_add_u32_e32 v134, 0xe400, v153
	ds_write2_b32 v134, v104, v120 offset0:192 offset1:224
	v_add_u32_e32 v134, 0xe800, v153
	ds_write2_b32 v134, v105, v121 offset0:68 offset1:100
	ds_write2_b32 v134, v106, v122 offset0:200 offset1:232
	v_add_u32_e32 v134, 0xec00, v153
	ds_write2_b32 v134, v107, v123 offset0:76 offset1:108
	v_add_u32_e32 v134, 0xf600, v153
	ds_write2_b32 v134, v108, v124 offset0:96 offset1:128
	v_add_u32_e32 v134, 0xf800, v153
	ds_write2_b32 v134, v109, v125 offset0:100 offset1:132
	v_add_u32_e32 v134, 0xfa00, v153
	ds_write2_b32 v134, v110, v126 offset0:104 offset1:136
	v_add_u32_e32 v134, 0xfc00, v153
	ds_write2_b32 v134, v111, v127 offset0:108 offset1:140

.LBB0_1677:
	v_cmp_lt_i32_e32 vcc, 17, v4
	s_and_saveexec_b64 s[2:3], vcc
	s_cbranch_execz .LBB0_1731
	s_waitcnt vmcnt(0)
	s_waitcnt lgkmcnt(0)
	v_mov_b32_e32 v254, 0x12000
	v_mov_b32_e32 v252, s97
	v_mov_b32_e32 v253, s96
	ds_write_b64 v254, v[252:253]
	s_waitcnt lgkmcnt(0)
	s_barrier
	s_mov_b64 s[4:5], exec
	v_readlane_b32 s6, v255, 5
	v_readlane_b32 s7, v255, 6
	s_and_b64 s[6:7], s[4:5], s[6:7]
	s_mov_b64 exec, s[6:7]
	s_cbranch_execz .LBB0_1730
	s_add_i32 s50, 0, 0x12000
	s_mov_b64 s[6:7], src_shared_base
	s_cmp_lg_u32 s50, -1
	s_cselect_b32 s6, s50, 0
	s_cselect_b32 s8, s7, 0
	s_add_i32 s51, 0, 0x12004
	s_cmp_lg_u32 s51, -1
	v_mov_b32_e32 v0, s6
	v_mov_b32_e32 v1, s8
	s_cselect_b32 s6, s51, 0
	s_cselect_b32 s7, s7, 0
	s_waitcnt vmcnt(0) expcnt(0) lgkmcnt(0)
	flat_load_dword v2, v[0:1] sc0 sc1
	s_waitcnt vmcnt(0)
	v_mov_b32_e32 v0, s6
	v_mov_b32_e32 v1, s7
	flat_load_dword v0, v[0:1] sc0 sc1
	s_waitcnt vmcnt(0) lgkmcnt(0)
	v_cmp_eq_u32_e32 vcc, 0, v2
	s_and_saveexec_b64 s[6:7], vcc
	s_cbranch_execz .LBB0_1694
	s_add_u32 s8, s94, 0x1d11e200
	s_addc_u32 s9, s95, 0
	s_add_u32 s10, s94, 0x1d11e400
	s_addc_u32 s11, s95, 0
	s_add_u32 s12, s94, 0x1d11e500
	s_addc_u32 s13, s95, 0
	s_add_u32 s14, s94, 0x1d11e600
	s_addc_u32 s15, s95, 0
	s_add_u32 s16, s94, 0x1d11e700
	s_addc_u32 s17, s95, 0
	s_add_u32 s18, s94, 0x1d11e800
	s_addc_u32 s19, s95, 0
	s_add_u32 s20, s94, 0x1d11e900
	s_addc_u32 s21, s95, 0
	s_add_u32 s22, s94, 0x1d11ea00
	s_addc_u32 s23, s95, 0
	s_add_u32 s24, s94, 0x1d11eb00
	s_addc_u32 s25, s95, 0
	s_add_u32 s26, s94, 0x1d11ec00
	s_addc_u32 s27, s95, 0
	s_add_u32 s28, s94, 0x1d11ed00
	s_addc_u32 s29, s95, 0
	s_add_u32 s30, s94, 0x1d11ee00
	s_addc_u32 s31, s95, 0
	s_add_u32 s34, s94, 0x1d11ef00
	s_addc_u32 s35, s95, 0
	s_add_u32 s36, s94, 0x1d11f000
	s_addc_u32 s37, s95, 0
	s_add_u32 s38, s94, 0x1d11f100
	s_addc_u32 s39, s95, 0
	s_add_u32 s40, s94, 0x1d11f200
	s_addc_u32 s41, s95, 0
	s_add_u32 s42, s94, 0x1d11f300
	s_addc_u32 s43, s95, 0
	s_mov_b32 s52, 1
	v_mov_b32_e32 v16, 0
	s_branch .LBB0_1682

.LBB0_1732:
	s_or_b64 exec, exec, s[0:1]
	v_readlane_b32 s0, v255, 4
	s_cmp_lt_i32 s0, 18
	s_cselect_b64 s[0:1], -1, 0
	v_cmp_lt_i32_e32 vcc, 17, v4
	s_and_b64 s[2:3], s[0:1], vcc
	s_and_saveexec_b64 s[0:1], s[2:3]
	s_cbranch_execz .LBB0_1798
	v_mov_b32_e32 v254, 0x12000
	ds_read_b64 v[252:253], v254
	s_waitcnt lgkmcnt(0)
	v_readfirstlane_b32 s97, v252
	v_readfirstlane_b32 s96, v253
	v_readlane_b32 s2, v255, 0
	s_cmpk_gt_u32 s2, 0x3ff
	v_readlane_b32 s3, v255, 1
	s_cbranch_scc1 .LBB0_1743
	v_lshlrev_b32_e32 v3, 4, v180
	v_lshrrev_b32_e32 v1, 5, v180
	v_and_b32_e32 v3, 0x3c00, v3
	v_bfe_u32 v4, v180, 2, 2
	s_add_u32 s2, s94, 0xcede000
	v_add_u32_e32 v152, 0, v3
	v_bfe_u32 v3, v180, 5, 1
	v_bitop3_b32 v1, v1, v4, 1 bitop3:0x6c
	s_addc_u32 s3, s95, 0
	v_lshlrev_b32_e32 v153, 4, v1
	v_bitop3_b32 v1, v3, v4, 2 bitop3:0x36
	s_add_u32 s24, s94, 0x14ede000
	v_and_b32_e32 v2, 31, v180
	v_lshrrev_b32_e32 v0, 4, v180
	v_lshlrev_b32_e32 v154, 4, v1
	v_lshlrev_b32_e32 v1, 6, v180
	v_and_b32_e32 v4, 64, v180
	s_addc_u32 s25, s95, 0
	v_xor_b32_e32 v0, v0, v180
	v_and_b32_e32 v155, 0xe7c0, v1
	v_and_b32_e32 v156, 0x17c0, v1
	v_lshrrev_b32_e32 v1, 3, v180
	v_lshlrev_b32_e32 v4, 2, v4
	v_lshlrev_b32_e32 v2, 2, v2
	v_lshrrev_b32_e32 v129, 2, v180
	s_add_u32 s26, s94, 0x1cffe000
	v_readlane_b32 s4, v255, 0
	v_lshlrev_b32_e32 v0, 3, v0
	v_add3_u32 v2, 0, v4, v2
	s_movk_i32 s8, 0x840
	v_or_b32_e32 v1, 0x7b, v1
	s_addc_u32 s27, s95, 0
	v_readlane_b32 s5, v255, 1
	s_and_b32 s28, s4, 7
	s_lshr_b32 s30, s4, 3
	v_and_b32_e32 v128, 24, v0
	v_lshlrev_b32_e32 v0, 10, v129
	v_mov_b32_e32 v131, 0
	s_movk_i32 s4, 0x80
	v_mad_u32_u24 v157, v3, s8, v2
	v_and_b32_e32 v3, 0x380, v180
	v_mul_u32_u24_e32 v1, 0x210, v1
	s_lshr_b32 s29, s33, 3
	s_mov_b32 s5, 0
	v_cmp_gt_u32_e64 s[6:7], s4, v180
	v_cmp_eq_u32_e64 s[8:9], s4, v3
	s_movk_i32 s31, 0x210
	v_or_b32_e32 v158, 0x10000, v128
	s_mov_b32 s34, 0x20000
	v_or_b32_e32 v159, 0x20000, v128
	v_or_b32_e32 v160, 0x30000, v128
	v_lshlrev_b32_e32 v132, 1, v0
	v_mov_b32_e32 v133, v131
	v_lshlrev_b32_e32 v134, 1, v128
	v_mov_b32_e32 v135, v131
	s_waitcnt lgkmcnt(0)
	s_mov_b64 s[10:11], 0xaca0000
	v_add_u32_e32 v161, 0x1000, v152
	v_add_u32_e32 v162, 0x2000, v152
	v_add_u32_e32 v163, 0x3000, v152
	s_mov_b64 s[12:13], 0xacc0000
	v_add_u32_e32 v164, 0x4000, v152
	v_add_u32_e32 v165, 0x5000, v152
	v_add_u32_e32 v166, 0x6000, v152
	v_add_u32_e32 v167, 0x7000, v152
	v_add_u32_e32 v168, 0x8000, v152
	v_add_u32_e32 v169, 0x9000, v152
	s_mov_b64 s[14:15], 0xaca0040
	v_add_u32_e32 v170, 0xa000, v152
	s_mov_b64 s[16:17], 0xacc0040
	v_add_u32_e32 v171, 0xb000, v152
	s_mov_b64 s[18:19], 0x80
	v_add_u32_e32 v172, v2, v1
	s_mov_b32 s35, 0x40000
	s_mov_b32 s36, 0x60000
	s_branch .LBB0_1736

.LBB0_1736:
	s_lshr_b32 s4, s30, 3
	s_and_b32 s4, s4, 8
	s_lshl_b32 s20, s30, 3
	s_or_b32 s4, s4, s28
	s_and_b32 s37, s30, 1
	s_and_b32 s20, s20, 48
	s_or_b32 s38, s4, s20
	s_lshl_b32 s22, s37, 8
	s_lshl_b32 s20, s30, 4
	s_lshl_b32 s23, s38, 9
	v_or_b32_e32 v0, s22, v129
	s_and_b32 s39, s20, 0x380
	v_or_b32_e32 v0, s23, v0
	s_lshl_b32 s20, s39, 11
	s_lshl_b32 s4, s4, 21
	v_lshlrev_b32_e32 v1, 10, v0
	s_or_b32 s4, s4, s20
	s_add_u32 s20, s94, s4
	v_or_b32_e32 v0, v1, v128
	v_readfirstlane_b32 s4, v152
	v_lshlrev_b32_e32 v130, 1, v0
	s_mov_b32 m0, s4
	v_readfirstlane_b32 s4, v161
	s_addc_u32 s21, s95, 0
	v_add_lshl_u32 v0, v1, v158, 1
	s_waitcnt vmcnt(0)
	s_barrier
	s_nop 0
	s_mov_b32 m0, s4
	v_readfirstlane_b32 s4, v162
	v_add_lshl_u32 v2, v1, v159, 1
	v_lshl_add_u64 v[6:7], s[20:21], 0, v[132:133]
	s_nop 0
	s_mov_b32 m0, s4
	v_readfirstlane_b32 s4, v163
	v_add_lshl_u32 v4, v1, v160, 1
	v_lshl_add_u64 v[6:7], v[6:7], 0, v[134:135]
	s_nop 0
	s_mov_b32 m0, s4
	v_readfirstlane_b32 s4, v164
	v_lshl_add_u64 v[136:137], v[6:7], 0, s[10:11]
	s_nop 0
	s_mov_b32 m0, s4
	v_readfirstlane_b32 s4, v165
	v_lshl_add_u64 v[138:139], s[2:3], 0, v[130:131]
	v_mov_b32_e32 v1, v131
	v_lshl_add_u64 v[146:147], v[6:7], 0, s[12:13]
	s_nop 0
	s_mov_b32 m0, s4
	v_readfirstlane_b32 s4, v166
	v_lshl_add_u64 v[140:141], s[2:3], 0, v[0:1]
	v_mov_b32_e32 v3, v131
	s_nop 0
	v_lshl_add_u64 v[0:1], v[138:139], 0, 64
	s_mov_b32 m0, s4
	v_readfirstlane_b32 s4, v167
	v_lshl_add_u64 v[142:143], s[2:3], 0, v[2:3]
	v_mov_b32_e32 v5, v131
	s_nop 0
	v_lshl_add_u64 v[0:1], v[140:141], 0, 64
	s_mov_b32 m0, s4
	v_readfirstlane_b32 s4, v168
	v_lshl_add_u64 v[144:145], s[2:3], 0, v[4:5]
	s_nop 0
	v_lshl_add_u64 v[0:1], v[142:143], 0, 64
	s_mov_b32 m0, s4
	v_readfirstlane_b32 s4, v169
	s_nop 0
	v_lshl_add_u64 v[0:1], v[144:145], 0, 64
	s_mov_b32 m0, s4
	v_readfirstlane_b32 s4, v170
	s_nop 0
	v_lshl_add_u64 v[0:1], v[6:7], 0, s[14:15]
	s_mov_b32 m0, s4
	v_readfirstlane_b32 s4, v171
	s_nop 0
	v_lshl_add_u64 v[0:1], v[6:7], 0, s[16:17]
	s_mov_b32 m0, s4
	s_mov_b32 s20, s5
	s_nop 0
	s_mov_b32 s21, 2
	s_mov_b32 s40, s5
	v_mov_b32_e32 v0, 0
	v_mov_b32_e32 v1, v131
	v_mov_b32_e32 v2, v131
	v_mov_b32_e32 v4, v131
	v_mov_b32_e32 v6, v131
	v_mov_b32_e32 v7, v131
	v_mov_b32_e32 v8, v131
	v_mov_b32_e32 v9, v131
	v_mov_b32_e32 v10, v131
	v_mov_b32_e32 v11, v131
	v_mov_b32_e32 v12, v131
	v_mov_b32_e32 v13, v131
	v_mov_b32_e32 v14, v131
	v_mov_b32_e32 v15, v131
	v_mov_b32_e32 v16, 0
	v_mov_b32_e32 v17, v131
	v_mov_b32_e32 v18, v131
	v_mov_b32_e32 v19, v131
	v_mov_b32_e32 v20, v131
	v_mov_b32_e32 v21, v131
	v_mov_b32_e32 v22, v131
	v_mov_b32_e32 v23, v131
	v_mov_b32_e32 v24, v131
	v_mov_b32_e32 v25, v131
	v_mov_b32_e32 v26, v131
	v_mov_b32_e32 v27, v131
	v_mov_b32_e32 v28, v131
	v_mov_b32_e32 v29, v131
	v_mov_b32_e32 v30, v131
	v_mov_b32_e32 v31, v131
	v_mov_b32_e32 v32, 0
	v_mov_b32_e32 v33, v131
	v_mov_b32_e32 v34, v131
	v_mov_b32_e32 v35, v131
	v_mov_b32_e32 v36, v131
	v_mov_b32_e32 v37, v131
	v_mov_b32_e32 v38, v131
	v_mov_b32_e32 v39, v131
	v_mov_b32_e32 v40, v131
	v_mov_b32_e32 v41, v131
	v_mov_b32_e32 v42, v131
	v_mov_b32_e32 v43, v131
	v_mov_b32_e32 v44, v131
	v_mov_b32_e32 v45, v131
	v_mov_b32_e32 v46, v131
	v_mov_b32_e32 v47, v131
	v_mov_b32_e32 v48, 0
	v_mov_b32_e32 v49, v131
	v_mov_b32_e32 v50, v131
	v_mov_b32_e32 v51, v131
	v_mov_b32_e32 v52, v131
	v_mov_b32_e32 v53, v131
	v_mov_b32_e32 v54, v131
	v_mov_b32_e32 v55, v131
	v_mov_b32_e32 v56, v131
	v_mov_b32_e32 v57, v131
	v_mov_b32_e32 v58, v131
	v_mov_b32_e32 v59, v131
	v_mov_b32_e32 v60, v131
	v_mov_b32_e32 v61, v131
	v_mov_b32_e32 v62, v131
	v_mov_b32_e32 v63, v131
	v_mov_b32_e32 v64, 0
	v_mov_b32_e32 v65, v131
	v_mov_b32_e32 v66, v131
	v_mov_b32_e32 v67, v131
	v_mov_b32_e32 v68, v131
	v_mov_b32_e32 v69, v131
	v_mov_b32_e32 v70, v131
	v_mov_b32_e32 v71, v131
	v_mov_b32_e32 v72, v131
	v_mov_b32_e32 v73, v131
	v_mov_b32_e32 v74, v131
	v_mov_b32_e32 v75, v131
	v_mov_b32_e32 v76, v131
	v_mov_b32_e32 v77, v131
	v_mov_b32_e32 v78, v131
	v_mov_b32_e32 v79, v131
	v_mov_b32_e32 v80, 0
	v_mov_b32_e32 v81, v131
	v_mov_b32_e32 v82, v131
	v_mov_b32_e32 v83, v131
	v_mov_b32_e32 v84, v131
	v_mov_b32_e32 v85, v131
	v_mov_b32_e32 v86, v131
	v_mov_b32_e32 v87, v131
	v_mov_b32_e32 v88, v131
	v_mov_b32_e32 v89, v131
	v_mov_b32_e32 v90, v131
	v_mov_b32_e32 v91, v131
	v_mov_b32_e32 v92, v131
	v_mov_b32_e32 v93, v131
	v_mov_b32_e32 v94, v131
	v_mov_b32_e32 v95, v131
	v_mov_b32_e32 v96, 0
	v_mov_b32_e32 v97, v131
	v_mov_b32_e32 v98, v131
	v_mov_b32_e32 v99, v131
	v_mov_b32_e32 v100, v131
	v_mov_b32_e32 v101, v131
	v_mov_b32_e32 v102, v131
	v_mov_b32_e32 v103, v131
	v_mov_b32_e32 v104, v131
	v_mov_b32_e32 v105, v131
	v_mov_b32_e32 v106, v131
	v_mov_b32_e32 v107, v131
	v_mov_b32_e32 v108, v131
	v_mov_b32_e32 v109, v131
	v_mov_b32_e32 v110, v131
	v_mov_b32_e32 v111, v131
	v_mov_b32_e32 v112, 0
	v_mov_b32_e32 v113, v131
	v_mov_b32_e32 v114, v131
	v_mov_b32_e32 v115, v131
	v_mov_b32_e32 v116, v131
	v_mov_b32_e32 v117, v131
	v_mov_b32_e32 v118, v131
	v_mov_b32_e32 v119, v131
	v_mov_b32_e32 v120, v131
	v_mov_b32_e32 v121, v131
	v_mov_b32_e32 v122, v131
	v_mov_b32_e32 v123, v131
	v_mov_b32_e32 v124, v131
	v_mov_b32_e32 v125, v131
	v_mov_b32_e32 v126, v131
	v_mov_b32_e32 v127, v131
	s_mov_b64 s[54:55], 0x80
	v_lshrrev_b32_e32 v174, 6, v180
	v_lshlrev_b32_e32 v184, 11, v174
	v_and_b32_e32 v148, 63, v180
	v_readfirstlane_b32 s53, v184
	v_lshrrev_b32_e32 v149, 5, v148
	v_bfe_u32 v150, v148, 1, 3
	v_xor_b32_e32 v150, v149, v150
	v_and_b32_e32 v151, 31, v148
	v_lshlrev_b32_e32 v151, 7, v151
	v_lshrrev_b32_e32 v151, 3, v148
	v_lshlrev_b32_e32 v184, 4, v151
	v_add_u32_e32 v185, 0x80, v184
	v_and_b32_e32 v151, 7, v148
	v_lshrrev_b32_e32 v149, 4, v148
	v_xor_b32_e32 v149, v151, v149
	v_lshrrev_b32_e32 v151, 5, v148
	v_sub_u32_e32 v186, v149, v151
	v_xor_b32_e32 v149, 4, v149
	v_add_u32_e32 v151, 2, v151
	v_sub_u32_e32 v188, v149, v151
	v_lshlrev_b32_e32 v186, 4, v186
	v_ashrrev_i32_e32 v187, 31, v186
	v_lshlrev_b32_e32 v188, 4, v188
	v_ashrrev_i32_e32 v189, 31, v188
	ds_bpermute_b32 v246, v184, v136
	ds_bpermute_b32 v247, v184, v137
	ds_bpermute_b32 v248, v185, v136
	ds_bpermute_b32 v249, v185, v137
	ds_bpermute_b32 v250, v184, v146
	ds_bpermute_b32 v251, v184, v147
	ds_bpermute_b32 v252, v185, v146
	ds_bpermute_b32 v253, v185, v147
	s_waitcnt lgkmcnt(0)
	ds_bpermute_b32 v178, v184, v138
	ds_bpermute_b32 v179, v184, v139
	ds_bpermute_b32 v236, v185, v138
	ds_bpermute_b32 v237, v185, v139
	ds_bpermute_b32 v238, v184, v140
	ds_bpermute_b32 v239, v184, v141
	ds_bpermute_b32 v240, v185, v140
	ds_bpermute_b32 v241, v185, v141
	ds_bpermute_b32 v242, v184, v142
	ds_bpermute_b32 v243, v184, v143
	ds_bpermute_b32 v244, v185, v142
	ds_bpermute_b32 v245, v185, v143
	ds_bpermute_b32 v136, v184, v144
	ds_bpermute_b32 v137, v184, v145
	ds_bpermute_b32 v146, v185, v144
	ds_bpermute_b32 v147, v185, v145
	s_waitcnt lgkmcnt(0)
	v_and_b32_e32 v151, 31, v148
	v_lshlrev_b32_e32 v151, 7, v151
	v_lshrrev_b32_e32 v149, 1, v174
	v_lshl_add_u32 v138, v149, 14, v151
	v_and_b32_e32 v149, 1, v174
	v_lshl_add_u32 v142, v149, 13, v151
	v_add_u32_e32 v142, 0x10000, v142
	v_xor_b32_e32 v151, 6, v150
	v_lshl_add_u32 v141, v151, 4, v138
	v_lshl_add_u32 v145, v151, 4, v142
	v_xor_b32_e32 v151, 4, v150
	v_lshl_add_u32 v140, v151, 4, v138
	v_lshl_add_u32 v144, v151, 4, v142
	v_xor_b32_e32 v151, 2, v150
	v_lshl_add_u32 v139, v151, 4, v138
	v_lshl_add_u32 v143, v151, 4, v142
	v_xor_b32_e32 v151, 0, v150
	v_lshl_add_u32 v138, v151, 4, v138
	v_lshl_add_u32 v142, v151, 4, v142
	v_lshl_add_u64 v[178:179], v[178:179], 0, v[186:187]
	v_lshl_add_u64 v[236:237], v[236:237], 0, v[188:189]
	v_lshl_add_u64 v[238:239], v[238:239], 0, v[186:187]
	v_lshl_add_u64 v[240:241], v[240:241], 0, v[188:189]
	v_lshl_add_u64 v[242:243], v[242:243], 0, v[186:187]
	v_lshl_add_u64 v[244:245], v[244:245], 0, v[188:189]
	v_lshl_add_u64 v[136:137], v[136:137], 0, v[186:187]
	v_lshl_add_u64 v[146:147], v[146:147], 0, v[188:189]
	v_lshl_add_u64 v[246:247], v[246:247], 0, v[186:187]
	v_lshl_add_u64 v[248:249], v[248:249], 0, v[188:189]
	v_lshl_add_u64 v[250:251], v[250:251], 0, v[186:187]
	v_lshl_add_u64 v[252:253], v[252:253], 0, v[188:189]
	s_mov_b32 s58, s53
	s_add_i32 m0, s58, 0x0
	s_nop 0
	global_load_lds_dwordx4 v[178:179], off
	s_add_i32 m0, s58, 0x400
	v_lshl_add_u64 v[178:179], v[178:179], 0, s[54:55]
	global_load_lds_dwordx4 v[236:237], off
	s_add_i32 m0, s58, 0x2000
	v_lshl_add_u64 v[236:237], v[236:237], 0, s[54:55]
	global_load_lds_dwordx4 v[238:239], off
	s_add_i32 m0, s58, 0x2400
	v_lshl_add_u64 v[238:239], v[238:239], 0, s[54:55]
	global_load_lds_dwordx4 v[240:241], off
	s_add_i32 m0, s58, 0x4000
	v_lshl_add_u64 v[240:241], v[240:241], 0, s[54:55]
	global_load_lds_dwordx4 v[242:243], off
	s_add_i32 m0, s58, 0x4400
	v_lshl_add_u64 v[242:243], v[242:243], 0, s[54:55]
	global_load_lds_dwordx4 v[244:245], off
	s_add_i32 m0, s58, 0x6000
	v_lshl_add_u64 v[244:245], v[244:245], 0, s[54:55]
	global_load_lds_dwordx4 v[136:137], off
	s_add_i32 m0, s58, 0x6400
	v_lshl_add_u64 v[136:137], v[136:137], 0, s[54:55]
	global_load_lds_dwordx4 v[146:147], off
	v_lshl_add_u64 v[146:147], v[146:147], 0, s[54:55]
	s_add_i32 s58, s53, 0x10000
	s_add_i32 m0, s58, 0x0
	s_nop 0
	global_load_lds_dwordx4 v[246:247], off
	s_add_i32 m0, s58, 0x400
	v_lshl_add_u64 v[246:247], v[246:247], 0, s[54:55]
	global_load_lds_dwordx4 v[248:249], off
	s_add_i32 m0, s58, 0x2000
	v_lshl_add_u64 v[248:249], v[248:249], 0, s[54:55]
	global_load_lds_dwordx4 v[250:251], off
	s_add_i32 m0, s58, 0x2400
	v_lshl_add_u64 v[250:251], v[250:251], 0, s[54:55]
	global_load_lds_dwordx4 v[252:253], off
	v_lshl_add_u64 v[252:253], v[252:253], 0, s[54:55]
	s_mov_b32 s20, 0
	s_mov_b32 s21, 0

.Lg_ph17_noB:
	s_waitcnt lgkmcnt(3)
	v_mfma_f32_32x32x16_bf16 v[0:15], v[148:151], v[190:193], v[0:15]
	v_mfma_f32_32x32x16_bf16 v[16:31], v[148:151], v[194:197], v[16:31]
	ds_read_b128 v[148:151], v139
	s_waitcnt lgkmcnt(3)
	v_mfma_f32_32x32x16_bf16 v[32:47], v[174:177], v[190:193], v[32:47]
	v_mfma_f32_32x32x16_bf16 v[48:63], v[174:177], v[194:197], v[48:63]
	ds_read_b128 v[174:177], v139 offset:4096
	s_waitcnt lgkmcnt(3)
	v_mfma_f32_32x32x16_bf16 v[64:79], v[182:185], v[190:193], v[64:79]
	v_mfma_f32_32x32x16_bf16 v[80:95], v[182:185], v[194:197], v[80:95]
	ds_read_b128 v[182:185], v139 offset:8192
	s_waitcnt lgkmcnt(3)
	v_mfma_f32_32x32x16_bf16 v[96:111], v[186:189], v[190:193], v[96:111]
	v_mfma_f32_32x32x16_bf16 v[112:127], v[186:189], v[194:197], v[112:127]
	ds_read_b128 v[186:189], v139 offset:12288
	s_waitcnt lgkmcnt(3)
	v_mfma_f32_32x32x16_bf16 v[0:15], v[148:151], v[198:201], v[0:15]
	v_mfma_f32_32x32x16_bf16 v[16:31], v[148:151], v[202:205], v[16:31]
	ds_read_b128 v[148:151], v140
	s_waitcnt lgkmcnt(3)
	v_mfma_f32_32x32x16_bf16 v[32:47], v[174:177], v[198:201], v[32:47]
	v_mfma_f32_32x32x16_bf16 v[48:63], v[174:177], v[202:205], v[48:63]
	ds_read_b128 v[174:177], v140 offset:4096
	s_waitcnt lgkmcnt(3)
	v_mfma_f32_32x32x16_bf16 v[64:79], v[182:185], v[198:201], v[64:79]
	v_mfma_f32_32x32x16_bf16 v[80:95], v[182:185], v[202:205], v[80:95]
	ds_read_b128 v[182:185], v140 offset:8192
	s_waitcnt lgkmcnt(3)
	v_mfma_f32_32x32x16_bf16 v[96:111], v[186:189], v[198:201], v[96:111]
	v_mfma_f32_32x32x16_bf16 v[112:127], v[186:189], v[202:205], v[112:127]
	ds_read_b128 v[186:189], v140 offset:12288
	s_waitcnt lgkmcnt(3)
	v_mfma_f32_32x32x16_bf16 v[0:15], v[148:151], v[206:209], v[0:15]
	v_mfma_f32_32x32x16_bf16 v[16:31], v[148:151], v[224:227], v[16:31]
	ds_read_b128 v[148:151], v141
	s_waitcnt lgkmcnt(3)
	v_mfma_f32_32x32x16_bf16 v[32:47], v[174:177], v[206:209], v[32:47]
	v_mfma_f32_32x32x16_bf16 v[48:63], v[174:177], v[224:227], v[48:63]
	ds_read_b128 v[174:177], v141 offset:4096
	s_waitcnt lgkmcnt(3)
	v_mfma_f32_32x32x16_bf16 v[64:79], v[182:185], v[206:209], v[64:79]
	v_mfma_f32_32x32x16_bf16 v[80:95], v[182:185], v[224:227], v[80:95]
	ds_read_b128 v[182:185], v141 offset:8192
	s_waitcnt lgkmcnt(3)
	v_mfma_f32_32x32x16_bf16 v[96:111], v[186:189], v[206:209], v[96:111]
	v_mfma_f32_32x32x16_bf16 v[112:127], v[186:189], v[224:227], v[112:127]
	ds_read_b128 v[186:189], v141 offset:12288
	s_waitcnt lgkmcnt(3)
	v_mfma_f32_32x32x16_bf16 v[0:15], v[148:151], v[228:231], v[0:15]
	v_mfma_f32_32x32x16_bf16 v[16:31], v[148:151], v[232:235], v[16:31]
	s_waitcnt lgkmcnt(2)
	v_mfma_f32_32x32x16_bf16 v[32:47], v[174:177], v[228:231], v[32:47]
	v_mfma_f32_32x32x16_bf16 v[48:63], v[174:177], v[232:235], v[48:63]
	s_waitcnt lgkmcnt(1)
	v_mfma_f32_32x32x16_bf16 v[64:79], v[182:185], v[228:231], v[64:79]
	v_mfma_f32_32x32x16_bf16 v[80:95], v[182:185], v[232:235], v[80:95]
	s_waitcnt lgkmcnt(0)
	v_mfma_f32_32x32x16_bf16 v[96:111], v[186:189], v[228:231], v[96:111]
	v_mfma_f32_32x32x16_bf16 v[112:127], v[186:189], v[232:235], v[112:127]
	v_xor_b32_e32 v138, 0x8000, v138
	v_xor_b32_e32 v139, 0x8000, v139
	v_xor_b32_e32 v140, 0x8000, v140
	v_xor_b32_e32 v141, 0x8000, v141
	s_xor_b32 s21, s21, 0x8000
	s_add_i32 s20, s20, 1
	s_cmp_eq_u32 s20, 16
	s_cbranch_scc0 .Lg_ph17_top
	s_waitcnt vmcnt(0)
	v_mov_b32_e32 v146, v180
	v_add_u32_e32 v208, 0x400, v157
	v_add_u32_e32 v207, 0x1000, v157
	v_add_u32_e32 v206, 0x1400, v157
	v_add_u32_e32 v205, 0x2000, v157
	v_add_u32_e32 v199, 0x2400, v157
	v_add_u32_e32 v200, 0x3000, v157
	v_add_u32_e32 v201, 0x3200, v157
	v_add_u32_e32 v202, 0x3400, v157
	v_add_u32_e32 v203, 0x3600, v157
	v_add_u32_e32 v204, 0x4000, v157
	v_add_u32_e32 v196, 0x4400, v157
	v_add_u32_e32 v197, 0x4800, v157
	v_add_u32_e32 v198, 0x5000, v157
	v_add_u32_e32 v193, 0x5400, v157
	v_add_u32_e32 v194, 0x5800, v157
	v_add_u32_e32 v195, 0x6000, v157
	v_add_u32_e32 v187, 0x6400, v157
	v_add_u32_e32 v188, 0x6800, v157
	v_add_u32_e32 v189, 0x7200, v157
	v_add_u32_e32 v190, 0x7400, v157
	v_add_u32_e32 v191, 0x7600, v157
	v_add_u32_e32 v192, 0x7800, v157
	v_add_u32_e32 v186, 0x8400, v157
	v_add_u32_e32 v185, 0x8800, v157
	v_add_u32_e32 v184, 0x9400, v157
	v_add_u32_e32 v183, 0x9800, v157
	v_add_u32_e32 v181, 0xa400, v157
	v_add_u32_e32 v174, 0xa800, v157
	v_add_u32_e32 v175, 0xb400, v157
	v_add_u32_e32 v176, 0xb600, v157
	v_add_u32_e32 v177, 0xb800, v157
	v_add_u32_e32 v178, 0xba00, v157
	s_waitcnt vmcnt(0)
	s_barrier
	s_and_saveexec_b64 s[20:21], s[6:7]
	s_cbranch_execz .LBB0_1740
	v_add_u32_e32 v130, 0xc400, v157
	ds_write2_b32 v157, v0, v16 offset1:32
	ds_write2_b32 v157, v1, v17 offset0:132 offset1:164
	ds_write2_b32 v208, v2, v18 offset0:8 offset1:40
	ds_write2_b32 v208, v3, v19 offset0:140 offset1:172
	ds_write2_b32 v207, v4, v20 offset0:32 offset1:64
	ds_write2_b32 v207, v5, v21 offset0:164 offset1:196
	ds_write2_b32 v206, v6, v22 offset0:40 offset1:72
	ds_write2_b32 v206, v7, v23 offset0:172 offset1:204
	ds_write2_b32 v205, v8, v24 offset0:64 offset1:96
	ds_write2_b32 v205, v9, v25 offset0:196 offset1:228
	ds_write2_b32 v199, v10, v26 offset0:72 offset1:104
	ds_write2_b32 v199, v11, v27 offset0:204 offset1:236
	ds_write2_b32 v200, v12, v28 offset0:96 offset1:128
	ds_write2_b32 v201, v13, v29 offset0:100 offset1:132
	ds_write2_b32 v202, v14, v30 offset0:104 offset1:136
	ds_write2_b32 v203, v15, v31 offset0:108 offset1:140
	ds_write2_b32 v204, v32, v48 offset0:128 offset1:160
	ds_write2_b32 v196, v33, v49 offset0:4 offset1:36
	ds_write2_b32 v196, v34, v50 offset0:136 offset1:168
	ds_write2_b32 v197, v35, v51 offset0:12 offset1:44
	ds_write2_b32 v198, v36, v52 offset0:160 offset1:192
	ds_write2_b32 v193, v37, v53 offset0:36 offset1:68
	ds_write2_b32 v193, v38, v54 offset0:168 offset1:200
	ds_write2_b32 v194, v39, v55 offset0:44 offset1:76
	ds_write2_b32 v195, v40, v56 offset0:192 offset1:224
	ds_write2_b32 v187, v41, v57 offset0:68 offset1:100
	ds_write2_b32 v187, v42, v58 offset0:200 offset1:232
	ds_write2_b32 v188, v43, v59 offset0:76 offset1:108
	ds_write2_b32 v189, v44, v60 offset0:96 offset1:128
	ds_write2_b32 v190, v45, v61 offset0:100 offset1:132
	ds_write2_b32 v191, v46, v62 offset0:104 offset1:136
	ds_write2_b32 v192, v47, v63 offset0:108 offset1:140
	ds_write2_b32 v186, v64, v80 offset1:32
	ds_write2_b32 v186, v65, v81 offset0:132 offset1:164
	ds_write2_b32 v185, v66, v82 offset0:8 offset1:40
	ds_write2_b32 v185, v67, v83 offset0:140 offset1:172
	ds_write2_b32 v184, v68, v84 offset0:32 offset1:64
	ds_write2_b32 v184, v69, v85 offset0:164 offset1:196
	ds_write2_b32 v183, v70, v86 offset0:40 offset1:72
	ds_write2_b32 v183, v71, v87 offset0:172 offset1:204
	ds_write2_b32 v181, v72, v88 offset0:64 offset1:96
	ds_write2_b32 v181, v73, v89 offset0:196 offset1:228
	ds_write2_b32 v174, v74, v90 offset0:72 offset1:104
	ds_write2_b32 v174, v75, v91 offset0:204 offset1:236
	ds_write2_b32 v175, v76, v92 offset0:96 offset1:128
	ds_write2_b32 v176, v77, v93 offset0:100 offset1:132
	ds_write2_b32 v177, v78, v94 offset0:104 offset1:136
	ds_write2_b32 v178, v79, v95 offset0:108 offset1:140
	ds_write2_b32 v130, v96, v112 offset0:128 offset1:160
	v_add_u32_e32 v130, 0xc800, v157
	ds_write2_b32 v130, v97, v113 offset0:4 offset1:36
	ds_write2_b32 v130, v98, v114 offset0:136 offset1:168
	v_add_u32_e32 v130, 0xcc00, v157
	ds_write2_b32 v130, v99, v115 offset0:12 offset1:44
	v_add_u32_e32 v130, 0xd400, v157
	ds_write2_b32 v130, v100, v116 offset0:160 offset1:192
	v_add_u32_e32 v130, 0xd800, v157
	ds_write2_b32 v130, v101, v117 offset0:36 offset1:68
	ds_write2_b32 v130, v102, v118 offset0:168 offset1:200
	v_add_u32_e32 v130, 0xdc00, v157
	ds_write2_b32 v130, v103, v119 offset0:44 offset1:76
	v_add_u32_e32 v130, 0xe400, v157
	ds_write2_b32 v130, v104, v120 offset0:192 offset1:224
	v_add_u32_e32 v130, 0xe800, v157
	ds_write2_b32 v130, v105, v121 offset0:68 offset1:100
	ds_write2_b32 v130, v106, v122 offset0:200 offset1:232
	v_add_u32_e32 v130, 0xec00, v157
	ds_write2_b32 v130, v107, v123 offset0:76 offset1:108
	v_add_u32_e32 v130, 0xf600, v157
	ds_write2_b32 v130, v108, v124 offset0:96 offset1:128
	v_add_u32_e32 v130, 0xf800, v157
	ds_write2_b32 v130, v109, v125 offset0:100 offset1:132
	v_add_u32_e32 v130, 0xfa00, v157
	ds_write2_b32 v130, v110, v126 offset0:104 offset1:136
	v_add_u32_e32 v130, 0xfc00, v157
	ds_write2_b32 v130, v111, v127 offset0:108 offset1:140

.LBB0_1743:
	v_cmp_lt_i32_e32 vcc, 18, v4
	s_and_saveexec_b64 s[2:3], vcc
	s_cbranch_execz .LBB0_1797
	s_waitcnt vmcnt(0)
	s_waitcnt lgkmcnt(0)
	v_mov_b32_e32 v254, 0x12000
	v_mov_b32_e32 v252, s97
	v_mov_b32_e32 v253, s96
	ds_write_b64 v254, v[252:253]
	s_waitcnt lgkmcnt(0)
	s_barrier
	s_mov_b64 s[4:5], exec
	v_readlane_b32 s6, v255, 5
	v_readlane_b32 s7, v255, 6
	s_and_b64 s[6:7], s[4:5], s[6:7]
	s_mov_b64 exec, s[6:7]
	s_cbranch_execz .LBB0_1796
	s_add_i32 s50, 0, 0x12000
	s_mov_b64 s[6:7], src_shared_base
	s_cmp_lg_u32 s50, -1
	s_cselect_b32 s6, s50, 0
	s_cselect_b32 s8, s7, 0
	s_add_i32 s51, 0, 0x12004
	s_cmp_lg_u32 s51, -1
	v_mov_b32_e32 v0, s6
	v_mov_b32_e32 v1, s8
	s_cselect_b32 s6, s51, 0
	s_cselect_b32 s7, s7, 0
	s_waitcnt vmcnt(0) expcnt(0) lgkmcnt(0)
	flat_load_dword v2, v[0:1] sc0 sc1
	s_waitcnt vmcnt(0)
	v_mov_b32_e32 v0, s6
	v_mov_b32_e32 v1, s7
	flat_load_dword v0, v[0:1] sc0 sc1
	s_waitcnt vmcnt(0) lgkmcnt(0)
	v_cmp_eq_u32_e32 vcc, 0, v2
	s_and_saveexec_b64 s[6:7], vcc
	s_cbranch_execz .LBB0_1760
	s_add_u32 s8, s94, 0x1d11e200
	s_addc_u32 s9, s95, 0
	s_add_u32 s10, s94, 0x1d11e400
	s_addc_u32 s11, s95, 0
	s_add_u32 s12, s94, 0x1d11e500
	s_addc_u32 s13, s95, 0
	s_add_u32 s14, s94, 0x1d11e600
	s_addc_u32 s15, s95, 0
	s_add_u32 s16, s94, 0x1d11e700
	s_addc_u32 s17, s95, 0
	s_add_u32 s18, s94, 0x1d11e800
	s_addc_u32 s19, s95, 0
	s_add_u32 s20, s94, 0x1d11e900
	s_addc_u32 s21, s95, 0
	s_add_u32 s22, s94, 0x1d11ea00
	s_addc_u32 s23, s95, 0
	s_add_u32 s24, s94, 0x1d11eb00
	s_addc_u32 s25, s95, 0
	s_add_u32 s26, s94, 0x1d11ec00
	s_addc_u32 s27, s95, 0
	s_add_u32 s28, s94, 0x1d11ed00
	s_addc_u32 s29, s95, 0
	s_add_u32 s30, s94, 0x1d11ee00
	s_addc_u32 s31, s95, 0
	s_add_u32 s34, s94, 0x1d11ef00
	s_addc_u32 s35, s95, 0
	s_add_u32 s36, s94, 0x1d11f000
	s_addc_u32 s37, s95, 0
	s_add_u32 s38, s94, 0x1d11f100
	s_addc_u32 s39, s95, 0
	s_add_u32 s40, s94, 0x1d11f200
	s_addc_u32 s41, s95, 0
	s_add_u32 s42, s94, 0x1d11f300
	s_addc_u32 s43, s95, 0
	s_mov_b32 s52, 1
	v_mov_b32_e32 v16, 0
	s_branch .LBB0_1748
